# norm1+norm2 phases rewritten by hand: 16 consecutive rows per wave, modulation vectors kept in registers, x double-buffered 2x4 rows; scan as 4-batch loop
# speedup vs baseline: 1.0068x; 1.0068x over previous
; DI void norm_phase(const Args& A, int wave_s, int l, int which, int rows) {
;     const Ctx C = make_ctx(A, wave_s);
;     const float* gn = (which == 1 ? C.n1g : C.n2g) + l * 1024;
;     const bool from_in = (l == 0 && which == 1);
;     f32x4 g[4];
; #pragma unroll
;     for (int j = 0; j < 4; ++j) g[j] = *(const f32x4*)(gn + 4 * (C.lane + 64 * j));
;     for (int m0 = C.gw * 2; m0 < rows; m0 += C.NGW * 2) {
;         f32x4 xv[2][4];
;         const float* modp[2];
; #pragma unroll
;         for (int rr = 0; rr < 2; ++rr) {
;             const int m = m0 + rr; const float* xr; int v;
;             if (m < NLAT) { xr = (from_in ? C.x : C.out) + (size_t)m * 1024; v = m >> 13; }
;             else { xr = (from_in ? C.ctx : C.XC) + (size_t)(m - NLAT) * 1024; v = 4; }
;             modp[rr] = C.SM + SM_MOD + (l * 5 + v) * 6144 + (which == 1 ? 0 : 3072);
; #pragma unroll
;             for (int j = 0; j < 4; ++j) xv[rr][j] = ((const f32x4*)xr)[C.lane + 64 * j];
.LBB0_55:
	s_lshl_b32 s4, s56, 10
	s_mov_b32 s5, s97
	v_writelane_b32 v255, s4, 32
	s_mul_i32 s45, s56, 5
	v_mbcnt_lo_u32_b32 v48, -1, 0
	v_mbcnt_hi_u32_b32 v48, -1, v48
	s_nop 0
	v_writelane_b32 v255, s5, 33
	v_mbcnt_lo_u32_b32 v0, -1, 0
	v_mbcnt_hi_u32_b32 v0, -1, v0
	v_readlane_b32 s6, v255, 32
	v_lshlrev_b32_e32 v1, 4, v0
	v_lshlrev_b32_e32 v2, 3, v0
	v_xor_b32_e32 v4, 1, v0
	v_xor_b32_e32 v5, 2, v0
	v_xor_b32_e32 v6, 4, v0
	v_xor_b32_e32 v7, 8, v0
	v_xor_b32_e32 v8, 16, v0
	v_xor_b32_e32 v9, 32, v0
	v_lshlrev_b32_e32 v4, 2, v4
	v_lshlrev_b32_e32 v5, 2, v5
	v_lshlrev_b32_e32 v6, 2, v6
	v_lshlrev_b32_e32 v7, 2, v7
	v_lshlrev_b32_e32 v8, 2, v8
	v_lshlrev_b32_e32 v9, 2, v9
	v_mov_b32_e32 v60, 0x358637bd
	s_lshr_b32 s6, s6, 10
	s_lshr_b32 s4, s94, 6
	s_lshl_b32 s5, s65, 3
	s_add_u32 s4, s4, s5
	s_lshr_b32 s5, s4, 9
	s_mul_i32 s7, s6, 5
	s_add_u32 s5, s7, s5
	s_mul_i32 s5, s5, 0x6000
	s_add_u32 s24, s88, 0x100000
	s_addc_u32 s25, s89, 0
	s_add_u32 s24, s24, s5
	s_addc_u32 s25, s25, 0
	s_add_u32 s26, s24, 0x1000
	s_addc_u32 s27, s25, 0
	v_readlane_b32 s28, v252, 46
	v_readlane_b32 s29, v252, 47
	s_lshl_b32 s7, s6, 12
	s_nop 1
	s_add_u32 s28, s28, s7
	s_addc_u32 s29, s29, 0
	v_readlane_b32 s8, v252, 31
	v_readlane_b32 s9, v252, 32
	s_add_u32 s30, s88, 0x3400000
	s_addc_u32 s31, s89, 0
	v_readlane_b32 s10, v252, 34
	v_readlane_b32 s11, v252, 35
	v_readlane_b32 s2, v252, 38
	v_readlane_b32 s32, v252, 39
	s_nop 1
	s_cmp_eq_u32 s6, 0
	s_cselect_b32 s8, s10, s8
	s_cselect_b32 s9, s11, s9
	s_cselect_b32 s30, s2, s30
	s_cselect_b32 s31, s32, s31
	s_mov_b32 s2, 1
	s_cmp_lt_u32 s4, 0x400
	s_cselect_b32 s2, s2, 0
	s_and_b32 s7, s4, 0x3ff
	s_lshl_b32 s5, s7, 12
	s_add_u32 s30, s30, s5
	s_addc_u32 s31, s31, 0
	s_lshl_b32 s5, s4, 16
	s_add_u32 s8, s8, s5
	s_addc_u32 s9, s9, 0
	s_add_u32 s10, s88, 0x3800000
	s_addc_u32 s11, s89, 0
	s_lshl_b32 s5, s4, 15
	s_add_u32 s10, s10, s5
	s_addc_u32 s11, s11, 0
	s_mov_b32 s32, 0x3a800000
	global_load_dwordx4 v[24:27], v1, s[28:29]
	global_load_dwordx4 v[28:31], v1, s[28:29] offset:1024
	global_load_dwordx4 v[32:35], v1, s[28:29] offset:2048
	global_load_dwordx4 v[36:39], v1, s[28:29] offset:3072
	global_load_dwordx4 v[40:43], v1, s[26:27]
	global_load_dwordx4 v[64:67], v1, s[26:27] offset:1024
	global_load_dwordx4 v[68:71], v1, s[26:27] offset:2048
	global_load_dwordx4 v[72:75], v1, s[26:27] offset:3072
	global_load_dwordx4 v[80:83], v1, s[24:25]
	global_load_dwordx4 v[84:87], v1, s[24:25] offset:1024
	global_load_dwordx4 v[88:91], v1, s[24:25] offset:2048
	global_load_dwordx4 v[92:95], v1, s[24:25] offset:3072
	global_load_dwordx4 v[96:99], v1, s[8:9]
	global_load_dwordx4 v[100:103], v1, s[8:9] offset:1024
	global_load_dwordx4 v[104:107], v1, s[8:9] offset:2048
	global_load_dwordx4 v[108:111], v1, s[8:9] offset:3072
	s_add_u32 s8, s8, 0x1000
	s_addc_u32 s9, s9, 0
	global_load_dwordx4 v[112:115], v1, s[8:9]
	global_load_dwordx4 v[116:119], v1, s[8:9] offset:1024
	global_load_dwordx4 v[120:123], v1, s[8:9] offset:2048
	global_load_dwordx4 v[124:127], v1, s[8:9] offset:3072
	s_add_u32 s8, s8, 0x1000
	s_addc_u32 s9, s9, 0
	global_load_dwordx4 v[128:131], v1, s[8:9]
	global_load_dwordx4 v[132:135], v1, s[8:9] offset:1024
	global_load_dwordx4 v[136:139], v1, s[8:9] offset:2048
	global_load_dwordx4 v[140:143], v1, s[8:9] offset:3072
	s_add_u32 s8, s8, 0x1000
	s_addc_u32 s9, s9, 0
	global_load_dwordx4 v[144:147], v1, s[8:9]
	global_load_dwordx4 v[148:151], v1, s[8:9] offset:1024
	global_load_dwordx4 v[152:155], v1, s[8:9] offset:2048
	global_load_dwordx4 v[156:159], v1, s[8:9] offset:3072
	s_add_u32 s8, s8, 0x1000
	s_addc_u32 s9, s9, 0
	global_load_dwordx4 v[164:167], v1, s[8:9]
	global_load_dwordx4 v[168:171], v1, s[8:9] offset:1024
	global_load_dwordx4 v[172:175], v1, s[8:9] offset:2048
	global_load_dwordx4 v[176:179], v1, s[8:9] offset:3072
	s_add_u32 s8, s8, 0x1000
	s_addc_u32 s9, s9, 0
	global_load_dwordx4 v[180:183], v1, s[8:9]
	global_load_dwordx4 v[184:187], v1, s[8:9] offset:1024
	global_load_dwordx4 v[188:191], v1, s[8:9] offset:2048
	global_load_dwordx4 v[192:195], v1, s[8:9] offset:3072
	s_add_u32 s8, s8, 0x1000
	s_addc_u32 s9, s9, 0
	global_load_dwordx4 v[196:199], v1, s[8:9]
	global_load_dwordx4 v[200:203], v1, s[8:9] offset:1024
	global_load_dwordx4 v[204:207], v1, s[8:9] offset:2048
	global_load_dwordx4 v[208:211], v1, s[8:9] offset:3072
	s_add_u32 s8, s8, 0x1000
	s_addc_u32 s9, s9, 0
	global_load_dwordx4 v[212:215], v1, s[8:9]
	global_load_dwordx4 v[216:219], v1, s[8:9] offset:1024
	global_load_dwordx4 v[220:223], v1, s[8:9] offset:2048
	global_load_dwordx4 v[224:227], v1, s[8:9] offset:3072
	s_add_u32 s8, s8, 0x1000
	s_addc_u32 s9, s9, 0
	s_waitcnt vmcnt(32)
	v_pk_add_f32 v[40:41], v[40:41], 1.0 op_sel_hi:[1,0]
	v_pk_add_f32 v[42:43], v[42:43], 1.0 op_sel_hi:[1,0]
	v_pk_add_f32 v[64:65], v[64:65], 1.0 op_sel_hi:[1,0]
	v_pk_add_f32 v[66:67], v[66:67], 1.0 op_sel_hi:[1,0]
	v_pk_add_f32 v[68:69], v[68:69], 1.0 op_sel_hi:[1,0]
	v_pk_add_f32 v[70:71], v[70:71], 1.0 op_sel_hi:[1,0]
	v_pk_add_f32 v[72:73], v[72:73], 1.0 op_sel_hi:[1,0]
	v_pk_add_f32 v[74:75], v[74:75], 1.0 op_sel_hi:[1,0]
	s_waitcnt vmcnt(16)
; DI unsigned pk2(float lo, float hi) { return f2bf(lo) | (f2bf(hi) << 16); }
; DI void norm_phase(const Args& A, int wave_s, int l, int which, int rows) {
;     ...
;             float ss = 0.f;
; #pragma unroll
;             for (int j = 0; j < 4; ++j) ss += (xv[rr][j].x * xv[rr][j].x + xv[rr][j].y * xv[rr][j].y) + (xv[rr][j].z * xv[rr][j].z + xv[rr][j].w * xv[rr][j].w);
;             ss = wave_sum(C.lane, ss);
;             const float rs = rsqrtf(ss * (1.f / 1024.f) + EPS);
; #pragma unroll
;             for (int j = 0; j < 4; ++j) { const int col = 4 * (C.lane + 64 * j);
;                 const f32x4 y = xv[rr][j] * rs * g[j] * (sc[j] + 1.f) + sh[j];
;                 v2u o; o.x = pk2(y.x, y.y); o.y = pk2(y.z, y.w);
;                 *(v2u*)(C.H + (size_t)m * 1024 + col) = o; }
	v_mul_f32_e32 v10, v96, v96
	v_fmac_f32_e32 v10, v97, v97
	v_fmac_f32_e32 v10, v98, v98
	v_fmac_f32_e32 v10, v99, v99
	v_fmac_f32_e32 v10, v100, v100
	v_fmac_f32_e32 v10, v101, v101
	v_fmac_f32_e32 v10, v102, v102
	v_fmac_f32_e32 v10, v103, v103
	v_fmac_f32_e32 v10, v104, v104
	v_fmac_f32_e32 v10, v105, v105
	v_fmac_f32_e32 v10, v106, v106
	v_fmac_f32_e32 v10, v107, v107
	v_fmac_f32_e32 v10, v108, v108
	v_fmac_f32_e32 v10, v109, v109
	v_fmac_f32_e32 v10, v110, v110
	v_fmac_f32_e32 v10, v111, v111
	v_mul_f32_e32 v11, v112, v112
	v_fmac_f32_e32 v11, v113, v113
	v_fmac_f32_e32 v11, v114, v114
	v_fmac_f32_e32 v11, v115, v115
	v_fmac_f32_e32 v11, v116, v116
	v_fmac_f32_e32 v11, v117, v117
	v_fmac_f32_e32 v11, v118, v118
	v_fmac_f32_e32 v11, v119, v119
	v_fmac_f32_e32 v11, v120, v120
	v_fmac_f32_e32 v11, v121, v121
	v_fmac_f32_e32 v11, v122, v122
	v_fmac_f32_e32 v11, v123, v123
	v_fmac_f32_e32 v11, v124, v124
	v_fmac_f32_e32 v11, v125, v125
	v_fmac_f32_e32 v11, v126, v126
	v_fmac_f32_e32 v11, v127, v127
	v_mul_f32_e32 v12, v128, v128
	v_fmac_f32_e32 v12, v129, v129
	v_fmac_f32_e32 v12, v130, v130
	v_fmac_f32_e32 v12, v131, v131
	v_fmac_f32_e32 v12, v132, v132
	v_fmac_f32_e32 v12, v133, v133
	v_fmac_f32_e32 v12, v134, v134
	v_fmac_f32_e32 v12, v135, v135
	v_fmac_f32_e32 v12, v136, v136
	v_fmac_f32_e32 v12, v137, v137
	v_fmac_f32_e32 v12, v138, v138
	v_fmac_f32_e32 v12, v139, v139
	v_fmac_f32_e32 v12, v140, v140
	v_fmac_f32_e32 v12, v141, v141
	v_fmac_f32_e32 v12, v142, v142
	v_fmac_f32_e32 v12, v143, v143
	v_mul_f32_e32 v13, v144, v144
	v_fmac_f32_e32 v13, v145, v145
	v_fmac_f32_e32 v13, v146, v146
	v_fmac_f32_e32 v13, v147, v147
	v_fmac_f32_e32 v13, v148, v148
	v_fmac_f32_e32 v13, v149, v149
	v_fmac_f32_e32 v13, v150, v150
	v_fmac_f32_e32 v13, v151, v151
	v_fmac_f32_e32 v13, v152, v152
	v_fmac_f32_e32 v13, v153, v153
	v_fmac_f32_e32 v13, v154, v154
	v_fmac_f32_e32 v13, v155, v155
	v_fmac_f32_e32 v13, v156, v156
	v_fmac_f32_e32 v13, v157, v157
	v_fmac_f32_e32 v13, v158, v158
	v_fmac_f32_e32 v13, v159, v159
	ds_bpermute_b32 v14, v4, v10
	ds_bpermute_b32 v15, v4, v11
	ds_bpermute_b32 v16, v4, v12
	ds_bpermute_b32 v17, v4, v13
	s_waitcnt lgkmcnt(0)
	v_add_f32_e32 v10, v10, v14
	v_add_f32_e32 v11, v11, v15
	v_add_f32_e32 v12, v12, v16
	v_add_f32_e32 v13, v13, v17
	ds_bpermute_b32 v14, v5, v10
	ds_bpermute_b32 v15, v5, v11
	ds_bpermute_b32 v16, v5, v12
	ds_bpermute_b32 v17, v5, v13
	s_waitcnt lgkmcnt(0)
	v_add_f32_e32 v10, v10, v14
	v_add_f32_e32 v11, v11, v15
	v_add_f32_e32 v12, v12, v16
	v_add_f32_e32 v13, v13, v17
	ds_bpermute_b32 v14, v6, v10
	ds_bpermute_b32 v15, v6, v11
	ds_bpermute_b32 v16, v6, v12
	ds_bpermute_b32 v17, v6, v13
	s_waitcnt lgkmcnt(0)
	v_add_f32_e32 v10, v10, v14
	v_add_f32_e32 v11, v11, v15
	v_add_f32_e32 v12, v12, v16
	v_add_f32_e32 v13, v13, v17
	ds_bpermute_b32 v14, v7, v10
	ds_bpermute_b32 v15, v7, v11
	ds_bpermute_b32 v16, v7, v12
	ds_bpermute_b32 v17, v7, v13
	s_waitcnt lgkmcnt(0)
	v_add_f32_e32 v10, v10, v14
	v_add_f32_e32 v11, v11, v15
	v_add_f32_e32 v12, v12, v16
	v_add_f32_e32 v13, v13, v17
	ds_bpermute_b32 v14, v8, v10
	ds_bpermute_b32 v15, v8, v11
	ds_bpermute_b32 v16, v8, v12
	ds_bpermute_b32 v17, v8, v13
	s_waitcnt lgkmcnt(0)
	v_add_f32_e32 v10, v10, v14
	v_add_f32_e32 v11, v11, v15
	v_add_f32_e32 v12, v12, v16
	v_add_f32_e32 v13, v13, v17
	ds_bpermute_b32 v14, v9, v10
	ds_bpermute_b32 v15, v9, v11
	ds_bpermute_b32 v16, v9, v12
	ds_bpermute_b32 v17, v9, v13
	s_waitcnt lgkmcnt(0)
	v_add_f32_e32 v10, v10, v14
	v_add_f32_e32 v11, v11, v15
	v_add_f32_e32 v12, v12, v16
	v_add_f32_e32 v13, v13, v17
	v_fma_f32 v10, v10, s32, v60
	v_fma_f32 v11, v11, s32, v60
	v_fma_f32 v12, v12, s32, v60
	v_fma_f32 v13, v13, s32, v60
	v_rsq_f32_e32 v18, v10
	v_rsq_f32_e32 v20, v11
	v_rsq_f32_e32 v22, v12
	v_rsq_f32_e32 v62, v13
	s_nop 0
	v_pk_mul_f32 v[96:97], v[96:97], v[18:19] op_sel_hi:[1,0]
	v_pk_mul_f32 v[98:99], v[98:99], v[18:19] op_sel_hi:[1,0]
	v_pk_mul_f32 v[100:101], v[100:101], v[18:19] op_sel_hi:[1,0]
	v_pk_mul_f32 v[102:103], v[102:103], v[18:19] op_sel_hi:[1,0]
	v_pk_mul_f32 v[104:105], v[104:105], v[18:19] op_sel_hi:[1,0]
	v_pk_mul_f32 v[106:107], v[106:107], v[18:19] op_sel_hi:[1,0]
	v_pk_mul_f32 v[108:109], v[108:109], v[18:19] op_sel_hi:[1,0]
	v_pk_mul_f32 v[110:111], v[110:111], v[18:19] op_sel_hi:[1,0]
	v_pk_mul_f32 v[96:97], v[24:25], v[96:97]
	v_pk_mul_f32 v[98:99], v[26:27], v[98:99]
	v_pk_mul_f32 v[100:101], v[28:29], v[100:101]
	v_pk_mul_f32 v[102:103], v[30:31], v[102:103]
	v_pk_mul_f32 v[104:105], v[32:33], v[104:105]
	v_pk_mul_f32 v[106:107], v[34:35], v[106:107]
	v_pk_mul_f32 v[108:109], v[36:37], v[108:109]
	v_pk_mul_f32 v[110:111], v[38:39], v[110:111]
	v_pk_fma_f32 v[96:97], v[40:41], v[96:97], v[80:81]
	v_pk_fma_f32 v[98:99], v[42:43], v[98:99], v[82:83]
	v_pk_fma_f32 v[100:101], v[64:65], v[100:101], v[84:85]
	v_pk_fma_f32 v[102:103], v[66:67], v[102:103], v[86:87]
	v_pk_fma_f32 v[104:105], v[68:69], v[104:105], v[88:89]
	v_pk_fma_f32 v[106:107], v[70:71], v[106:107], v[90:91]
	v_pk_fma_f32 v[108:109], v[72:73], v[108:109], v[92:93]
	v_pk_fma_f32 v[110:111], v[74:75], v[110:111], v[94:95]
	v_cvt_pk_bf16_f32 v96, v96, v97
	v_cvt_pk_bf16_f32 v97, v98, v99
	v_cvt_pk_bf16_f32 v100, v100, v101
	v_cvt_pk_bf16_f32 v101, v102, v103
	v_cvt_pk_bf16_f32 v104, v104, v105
	v_cvt_pk_bf16_f32 v105, v106, v107
	v_cvt_pk_bf16_f32 v108, v108, v109
	v_cvt_pk_bf16_f32 v109, v110, v111
	global_store_dwordx2 v2, v[96:97], s[10:11]
	global_store_dwordx2 v2, v[100:101], s[10:11] offset:512
	global_store_dwordx2 v2, v[104:105], s[10:11] offset:1024
	global_store_dwordx2 v2, v[108:109], s[10:11] offset:1536
	s_add_u32 s10, s10, 0x800
; DI unsigned pk2(float lo, float hi) { return f2bf(lo) | (f2bf(hi) << 16); }
; DI void norm_phase(const Args& A, int wave_s, int l, int which, int rows) {
;     ...
;             for (int j = 0; j < 4; ++j) xv[rr][j] = ((const f32x4*)xr)[C.lane + 64 * j];
;     ...
;             for (int j = 0; j < 4; ++j) { const int col = 4 * (C.lane + 64 * j);
;                 const f32x4 y = xv[rr][j] * rs * g[j] * (sc[j] + 1.f) + sh[j];
;                 v2u o; o.x = pk2(y.x, y.y); o.y = pk2(y.z, y.w);
;                 *(v2u*)(C.H + (size_t)m * 1024 + col) = o; }
	s_addc_u32 s11, s11, 0
	v_pk_mul_f32 v[112:113], v[112:113], v[20:21] op_sel_hi:[1,0]
	v_pk_mul_f32 v[114:115], v[114:115], v[20:21] op_sel_hi:[1,0]
	v_pk_mul_f32 v[116:117], v[116:117], v[20:21] op_sel_hi:[1,0]
	v_pk_mul_f32 v[118:119], v[118:119], v[20:21] op_sel_hi:[1,0]
	v_pk_mul_f32 v[120:121], v[120:121], v[20:21] op_sel_hi:[1,0]
	v_pk_mul_f32 v[122:123], v[122:123], v[20:21] op_sel_hi:[1,0]
	v_pk_mul_f32 v[124:125], v[124:125], v[20:21] op_sel_hi:[1,0]
	v_pk_mul_f32 v[126:127], v[126:127], v[20:21] op_sel_hi:[1,0]
	v_pk_mul_f32 v[112:113], v[24:25], v[112:113]
	v_pk_mul_f32 v[114:115], v[26:27], v[114:115]
	v_pk_mul_f32 v[116:117], v[28:29], v[116:117]
	v_pk_mul_f32 v[118:119], v[30:31], v[118:119]
	v_pk_mul_f32 v[120:121], v[32:33], v[120:121]
	v_pk_mul_f32 v[122:123], v[34:35], v[122:123]
	v_pk_mul_f32 v[124:125], v[36:37], v[124:125]
	v_pk_mul_f32 v[126:127], v[38:39], v[126:127]
	v_pk_fma_f32 v[112:113], v[40:41], v[112:113], v[80:81]
	v_pk_fma_f32 v[114:115], v[42:43], v[114:115], v[82:83]
	v_pk_fma_f32 v[116:117], v[64:65], v[116:117], v[84:85]
	v_pk_fma_f32 v[118:119], v[66:67], v[118:119], v[86:87]
	v_pk_fma_f32 v[120:121], v[68:69], v[120:121], v[88:89]
	v_pk_fma_f32 v[122:123], v[70:71], v[122:123], v[90:91]
	v_pk_fma_f32 v[124:125], v[72:73], v[124:125], v[92:93]
	v_pk_fma_f32 v[126:127], v[74:75], v[126:127], v[94:95]
	v_cvt_pk_bf16_f32 v112, v112, v113
	v_cvt_pk_bf16_f32 v113, v114, v115
	v_cvt_pk_bf16_f32 v116, v116, v117
	v_cvt_pk_bf16_f32 v117, v118, v119
	v_cvt_pk_bf16_f32 v120, v120, v121
	v_cvt_pk_bf16_f32 v121, v122, v123
	v_cvt_pk_bf16_f32 v124, v124, v125
	v_cvt_pk_bf16_f32 v125, v126, v127
	global_store_dwordx2 v2, v[112:113], s[10:11]
	global_store_dwordx2 v2, v[116:117], s[10:11] offset:512
	global_store_dwordx2 v2, v[120:121], s[10:11] offset:1024
	global_store_dwordx2 v2, v[124:125], s[10:11] offset:1536
	s_add_u32 s10, s10, 0x800
	s_addc_u32 s11, s11, 0
	v_pk_mul_f32 v[128:129], v[128:129], v[22:23] op_sel_hi:[1,0]
	v_pk_mul_f32 v[130:131], v[130:131], v[22:23] op_sel_hi:[1,0]
	v_pk_mul_f32 v[132:133], v[132:133], v[22:23] op_sel_hi:[1,0]
	v_pk_mul_f32 v[134:135], v[134:135], v[22:23] op_sel_hi:[1,0]
	v_pk_mul_f32 v[136:137], v[136:137], v[22:23] op_sel_hi:[1,0]
	v_pk_mul_f32 v[138:139], v[138:139], v[22:23] op_sel_hi:[1,0]
	v_pk_mul_f32 v[140:141], v[140:141], v[22:23] op_sel_hi:[1,0]
	v_pk_mul_f32 v[142:143], v[142:143], v[22:23] op_sel_hi:[1,0]
	v_pk_mul_f32 v[128:129], v[24:25], v[128:129]
	v_pk_mul_f32 v[130:131], v[26:27], v[130:131]
	v_pk_mul_f32 v[132:133], v[28:29], v[132:133]
	v_pk_mul_f32 v[134:135], v[30:31], v[134:135]
	v_pk_mul_f32 v[136:137], v[32:33], v[136:137]
	v_pk_mul_f32 v[138:139], v[34:35], v[138:139]
	v_pk_mul_f32 v[140:141], v[36:37], v[140:141]
	v_pk_mul_f32 v[142:143], v[38:39], v[142:143]
	v_pk_fma_f32 v[128:129], v[40:41], v[128:129], v[80:81]
	v_pk_fma_f32 v[130:131], v[42:43], v[130:131], v[82:83]
	v_pk_fma_f32 v[132:133], v[64:65], v[132:133], v[84:85]
	v_pk_fma_f32 v[134:135], v[66:67], v[134:135], v[86:87]
	v_pk_fma_f32 v[136:137], v[68:69], v[136:137], v[88:89]
	v_pk_fma_f32 v[138:139], v[70:71], v[138:139], v[90:91]
	v_pk_fma_f32 v[140:141], v[72:73], v[140:141], v[92:93]
	v_pk_fma_f32 v[142:143], v[74:75], v[142:143], v[94:95]
	v_cvt_pk_bf16_f32 v128, v128, v129
	v_cvt_pk_bf16_f32 v129, v130, v131
	v_cvt_pk_bf16_f32 v132, v132, v133
	v_cvt_pk_bf16_f32 v133, v134, v135
	v_cvt_pk_bf16_f32 v136, v136, v137
	v_cvt_pk_bf16_f32 v137, v138, v139
	v_cvt_pk_bf16_f32 v140, v140, v141
	v_cvt_pk_bf16_f32 v141, v142, v143
	global_store_dwordx2 v2, v[128:129], s[10:11]
	global_store_dwordx2 v2, v[132:133], s[10:11] offset:512
	global_store_dwordx2 v2, v[136:137], s[10:11] offset:1024
	global_store_dwordx2 v2, v[140:141], s[10:11] offset:1536
	s_add_u32 s10, s10, 0x800
	s_addc_u32 s11, s11, 0
	v_pk_mul_f32 v[144:145], v[144:145], v[62:63] op_sel_hi:[1,0]
	v_pk_mul_f32 v[146:147], v[146:147], v[62:63] op_sel_hi:[1,0]
	v_pk_mul_f32 v[148:149], v[148:149], v[62:63] op_sel_hi:[1,0]
	v_pk_mul_f32 v[150:151], v[150:151], v[62:63] op_sel_hi:[1,0]
	v_pk_mul_f32 v[152:153], v[152:153], v[62:63] op_sel_hi:[1,0]
	v_pk_mul_f32 v[154:155], v[154:155], v[62:63] op_sel_hi:[1,0]
	v_pk_mul_f32 v[156:157], v[156:157], v[62:63] op_sel_hi:[1,0]
	v_pk_mul_f32 v[158:159], v[158:159], v[62:63] op_sel_hi:[1,0]
	v_pk_mul_f32 v[144:145], v[24:25], v[144:145]
	v_pk_mul_f32 v[146:147], v[26:27], v[146:147]
	v_pk_mul_f32 v[148:149], v[28:29], v[148:149]
	v_pk_mul_f32 v[150:151], v[30:31], v[150:151]
	v_pk_mul_f32 v[152:153], v[32:33], v[152:153]
	v_pk_mul_f32 v[154:155], v[34:35], v[154:155]
	v_pk_mul_f32 v[156:157], v[36:37], v[156:157]
	v_pk_mul_f32 v[158:159], v[38:39], v[158:159]
	v_pk_fma_f32 v[144:145], v[40:41], v[144:145], v[80:81]
	v_pk_fma_f32 v[146:147], v[42:43], v[146:147], v[82:83]
	v_pk_fma_f32 v[148:149], v[64:65], v[148:149], v[84:85]
	v_pk_fma_f32 v[150:151], v[66:67], v[150:151], v[86:87]
	v_pk_fma_f32 v[152:153], v[68:69], v[152:153], v[88:89]
	v_pk_fma_f32 v[154:155], v[70:71], v[154:155], v[90:91]
	v_pk_fma_f32 v[156:157], v[72:73], v[156:157], v[92:93]
	v_pk_fma_f32 v[158:159], v[74:75], v[158:159], v[94:95]
	v_cvt_pk_bf16_f32 v144, v144, v145
	v_cvt_pk_bf16_f32 v145, v146, v147
	v_cvt_pk_bf16_f32 v148, v148, v149
	v_cvt_pk_bf16_f32 v149, v150, v151
	v_cvt_pk_bf16_f32 v152, v152, v153
	v_cvt_pk_bf16_f32 v153, v154, v155
	v_cvt_pk_bf16_f32 v156, v156, v157
	v_cvt_pk_bf16_f32 v157, v158, v159
	global_store_dwordx2 v2, v[144:145], s[10:11]
	global_store_dwordx2 v2, v[148:149], s[10:11] offset:512
	global_store_dwordx2 v2, v[152:153], s[10:11] offset:1024
	global_store_dwordx2 v2, v[156:157], s[10:11] offset:1536
	s_add_u32 s10, s10, 0x800
	s_addc_u32 s11, s11, 0
	global_load_dwordx4 v[96:99], v1, s[8:9]
	global_load_dwordx4 v[100:103], v1, s[8:9] offset:1024
	global_load_dwordx4 v[104:107], v1, s[8:9] offset:2048
	global_load_dwordx4 v[108:111], v1, s[8:9] offset:3072
	s_add_u32 s8, s8, 0x1000
	s_addc_u32 s9, s9, 0
	global_load_dwordx4 v[112:115], v1, s[8:9]
	global_load_dwordx4 v[116:119], v1, s[8:9] offset:1024
	global_load_dwordx4 v[120:123], v1, s[8:9] offset:2048
	global_load_dwordx4 v[124:127], v1, s[8:9] offset:3072
	s_add_u32 s8, s8, 0x1000
	s_addc_u32 s9, s9, 0
	global_load_dwordx4 v[128:131], v1, s[8:9]
	global_load_dwordx4 v[132:135], v1, s[8:9] offset:1024
	global_load_dwordx4 v[136:139], v1, s[8:9] offset:2048
	global_load_dwordx4 v[140:143], v1, s[8:9] offset:3072
	s_add_u32 s8, s8, 0x1000
	s_addc_u32 s9, s9, 0
	global_load_dwordx4 v[144:147], v1, s[8:9]
	global_load_dwordx4 v[148:151], v1, s[8:9] offset:1024
	global_load_dwordx4 v[152:155], v1, s[8:9] offset:2048
	global_load_dwordx4 v[156:159], v1, s[8:9] offset:3072
	s_add_u32 s8, s8, 0x1000
	s_addc_u32 s9, s9, 0
	s_waitcnt vmcnt(32)
; DI unsigned pk2(float lo, float hi) { return f2bf(lo) | (f2bf(hi) << 16); }
; DI void norm_phase(const Args& A, int wave_s, int l, int which, int rows) {
;     ...
;             float ss = 0.f;
; #pragma unroll
;             for (int j = 0; j < 4; ++j) ss += (xv[rr][j].x * xv[rr][j].x + xv[rr][j].y * xv[rr][j].y) + (xv[rr][j].z * xv[rr][j].z + xv[rr][j].w * xv[rr][j].w);
;             ss = wave_sum(C.lane, ss);
;             const float rs = rsqrtf(ss * (1.f / 1024.f) + EPS);
; #pragma unroll
;             for (int j = 0; j < 4; ++j) { const int col = 4 * (C.lane + 64 * j);
;                 const f32x4 y = xv[rr][j] * rs * g[j] * (sc[j] + 1.f) + sh[j];
;                 v2u o; o.x = pk2(y.x, y.y); o.y = pk2(y.z, y.w);
;                 *(v2u*)(C.H + (size_t)m * 1024 + col) = o; }
	v_mul_f32_e32 v10, v164, v164
	v_fmac_f32_e32 v10, v165, v165
	v_fmac_f32_e32 v10, v166, v166
	v_fmac_f32_e32 v10, v167, v167
	v_fmac_f32_e32 v10, v168, v168
	v_fmac_f32_e32 v10, v169, v169
	v_fmac_f32_e32 v10, v170, v170
	v_fmac_f32_e32 v10, v171, v171
	v_fmac_f32_e32 v10, v172, v172
	v_fmac_f32_e32 v10, v173, v173
	v_fmac_f32_e32 v10, v174, v174
	v_fmac_f32_e32 v10, v175, v175
	v_fmac_f32_e32 v10, v176, v176
	v_fmac_f32_e32 v10, v177, v177
	v_fmac_f32_e32 v10, v178, v178
	v_fmac_f32_e32 v10, v179, v179
	v_mul_f32_e32 v11, v180, v180
	v_fmac_f32_e32 v11, v181, v181
	v_fmac_f32_e32 v11, v182, v182
	v_fmac_f32_e32 v11, v183, v183
	v_fmac_f32_e32 v11, v184, v184
	v_fmac_f32_e32 v11, v185, v185
	v_fmac_f32_e32 v11, v186, v186
	v_fmac_f32_e32 v11, v187, v187
	v_fmac_f32_e32 v11, v188, v188
	v_fmac_f32_e32 v11, v189, v189
	v_fmac_f32_e32 v11, v190, v190
	v_fmac_f32_e32 v11, v191, v191
	v_fmac_f32_e32 v11, v192, v192
	v_fmac_f32_e32 v11, v193, v193
	v_fmac_f32_e32 v11, v194, v194
	v_fmac_f32_e32 v11, v195, v195
	v_mul_f32_e32 v12, v196, v196
	v_fmac_f32_e32 v12, v197, v197
	v_fmac_f32_e32 v12, v198, v198
	v_fmac_f32_e32 v12, v199, v199
	v_fmac_f32_e32 v12, v200, v200
	v_fmac_f32_e32 v12, v201, v201
	v_fmac_f32_e32 v12, v202, v202
	v_fmac_f32_e32 v12, v203, v203
	v_fmac_f32_e32 v12, v204, v204
	v_fmac_f32_e32 v12, v205, v205
	v_fmac_f32_e32 v12, v206, v206
	v_fmac_f32_e32 v12, v207, v207
	v_fmac_f32_e32 v12, v208, v208
	v_fmac_f32_e32 v12, v209, v209
	v_fmac_f32_e32 v12, v210, v210
	v_fmac_f32_e32 v12, v211, v211
	v_mul_f32_e32 v13, v212, v212
	v_fmac_f32_e32 v13, v213, v213
	v_fmac_f32_e32 v13, v214, v214
	v_fmac_f32_e32 v13, v215, v215
	v_fmac_f32_e32 v13, v216, v216
	v_fmac_f32_e32 v13, v217, v217
	v_fmac_f32_e32 v13, v218, v218
	v_fmac_f32_e32 v13, v219, v219
	v_fmac_f32_e32 v13, v220, v220
	v_fmac_f32_e32 v13, v221, v221
	v_fmac_f32_e32 v13, v222, v222
	v_fmac_f32_e32 v13, v223, v223
	v_fmac_f32_e32 v13, v224, v224
	v_fmac_f32_e32 v13, v225, v225
	v_fmac_f32_e32 v13, v226, v226
	v_fmac_f32_e32 v13, v227, v227
	ds_bpermute_b32 v14, v4, v10
	ds_bpermute_b32 v15, v4, v11
	ds_bpermute_b32 v16, v4, v12
	ds_bpermute_b32 v17, v4, v13
	s_waitcnt lgkmcnt(0)
	v_add_f32_e32 v10, v10, v14
	v_add_f32_e32 v11, v11, v15
	v_add_f32_e32 v12, v12, v16
	v_add_f32_e32 v13, v13, v17
	ds_bpermute_b32 v14, v5, v10
	ds_bpermute_b32 v15, v5, v11
	ds_bpermute_b32 v16, v5, v12
	ds_bpermute_b32 v17, v5, v13
	s_waitcnt lgkmcnt(0)
	v_add_f32_e32 v10, v10, v14
	v_add_f32_e32 v11, v11, v15
	v_add_f32_e32 v12, v12, v16
	v_add_f32_e32 v13, v13, v17
	ds_bpermute_b32 v14, v6, v10
	ds_bpermute_b32 v15, v6, v11
	ds_bpermute_b32 v16, v6, v12
	ds_bpermute_b32 v17, v6, v13
	s_waitcnt lgkmcnt(0)
	v_add_f32_e32 v10, v10, v14
	v_add_f32_e32 v11, v11, v15
	v_add_f32_e32 v12, v12, v16
	v_add_f32_e32 v13, v13, v17
	ds_bpermute_b32 v14, v7, v10
	ds_bpermute_b32 v15, v7, v11
	ds_bpermute_b32 v16, v7, v12
	ds_bpermute_b32 v17, v7, v13
	s_waitcnt lgkmcnt(0)
	v_add_f32_e32 v10, v10, v14
	v_add_f32_e32 v11, v11, v15
	v_add_f32_e32 v12, v12, v16
	v_add_f32_e32 v13, v13, v17
	ds_bpermute_b32 v14, v8, v10
	ds_bpermute_b32 v15, v8, v11
	ds_bpermute_b32 v16, v8, v12
	ds_bpermute_b32 v17, v8, v13
	s_waitcnt lgkmcnt(0)
	v_add_f32_e32 v10, v10, v14
	v_add_f32_e32 v11, v11, v15
	v_add_f32_e32 v12, v12, v16
	v_add_f32_e32 v13, v13, v17
	ds_bpermute_b32 v14, v9, v10
	ds_bpermute_b32 v15, v9, v11
	ds_bpermute_b32 v16, v9, v12
	ds_bpermute_b32 v17, v9, v13
	s_waitcnt lgkmcnt(0)
	v_add_f32_e32 v10, v10, v14
	v_add_f32_e32 v11, v11, v15
	v_add_f32_e32 v12, v12, v16
	v_add_f32_e32 v13, v13, v17
	v_fma_f32 v10, v10, s32, v60
	v_fma_f32 v11, v11, s32, v60
	v_fma_f32 v12, v12, s32, v60
	v_fma_f32 v13, v13, s32, v60
	v_rsq_f32_e32 v18, v10
	v_rsq_f32_e32 v20, v11
	v_rsq_f32_e32 v22, v12
	v_rsq_f32_e32 v62, v13
	s_nop 0
	v_pk_mul_f32 v[164:165], v[164:165], v[18:19] op_sel_hi:[1,0]
	v_pk_mul_f32 v[166:167], v[166:167], v[18:19] op_sel_hi:[1,0]
	v_pk_mul_f32 v[168:169], v[168:169], v[18:19] op_sel_hi:[1,0]
	v_pk_mul_f32 v[170:171], v[170:171], v[18:19] op_sel_hi:[1,0]
	v_pk_mul_f32 v[172:173], v[172:173], v[18:19] op_sel_hi:[1,0]
	v_pk_mul_f32 v[174:175], v[174:175], v[18:19] op_sel_hi:[1,0]
	v_pk_mul_f32 v[176:177], v[176:177], v[18:19] op_sel_hi:[1,0]
	v_pk_mul_f32 v[178:179], v[178:179], v[18:19] op_sel_hi:[1,0]
	v_pk_mul_f32 v[164:165], v[24:25], v[164:165]
	v_pk_mul_f32 v[166:167], v[26:27], v[166:167]
	v_pk_mul_f32 v[168:169], v[28:29], v[168:169]
	v_pk_mul_f32 v[170:171], v[30:31], v[170:171]
	v_pk_mul_f32 v[172:173], v[32:33], v[172:173]
	v_pk_mul_f32 v[174:175], v[34:35], v[174:175]
	v_pk_mul_f32 v[176:177], v[36:37], v[176:177]
	v_pk_mul_f32 v[178:179], v[38:39], v[178:179]
	v_pk_fma_f32 v[164:165], v[40:41], v[164:165], v[80:81]
	v_pk_fma_f32 v[166:167], v[42:43], v[166:167], v[82:83]
	v_pk_fma_f32 v[168:169], v[64:65], v[168:169], v[84:85]
	v_pk_fma_f32 v[170:171], v[66:67], v[170:171], v[86:87]
	v_pk_fma_f32 v[172:173], v[68:69], v[172:173], v[88:89]
	v_pk_fma_f32 v[174:175], v[70:71], v[174:175], v[90:91]
	v_pk_fma_f32 v[176:177], v[72:73], v[176:177], v[92:93]
	v_pk_fma_f32 v[178:179], v[74:75], v[178:179], v[94:95]
	v_cvt_pk_bf16_f32 v164, v164, v165
	v_cvt_pk_bf16_f32 v165, v166, v167
	v_cvt_pk_bf16_f32 v168, v168, v169
	v_cvt_pk_bf16_f32 v169, v170, v171
	v_cvt_pk_bf16_f32 v172, v172, v173
	v_cvt_pk_bf16_f32 v173, v174, v175
	v_cvt_pk_bf16_f32 v176, v176, v177
	v_cvt_pk_bf16_f32 v177, v178, v179
	global_store_dwordx2 v2, v[164:165], s[10:11]
	global_store_dwordx2 v2, v[168:169], s[10:11] offset:512
	global_store_dwordx2 v2, v[172:173], s[10:11] offset:1024
	global_store_dwordx2 v2, v[176:177], s[10:11] offset:1536
; DI unsigned pk2(float lo, float hi) { return f2bf(lo) | (f2bf(hi) << 16); }
; DI void norm_phase(const Args& A, int wave_s, int l, int which, int rows) {
;     ...
;             for (int j = 0; j < 4; ++j) xv[rr][j] = ((const f32x4*)xr)[C.lane + 64 * j];
;     ...
;             for (int j = 0; j < 4; ++j) { const int col = 4 * (C.lane + 64 * j);
;                 const f32x4 y = xv[rr][j] * rs * g[j] * (sc[j] + 1.f) + sh[j];
;                 v2u o; o.x = pk2(y.x, y.y); o.y = pk2(y.z, y.w);
;                 *(v2u*)(C.H + (size_t)m * 1024 + col) = o; }
	s_add_u32 s10, s10, 0x800
	s_addc_u32 s11, s11, 0
	v_pk_mul_f32 v[180:181], v[180:181], v[20:21] op_sel_hi:[1,0]
	v_pk_mul_f32 v[182:183], v[182:183], v[20:21] op_sel_hi:[1,0]
	v_pk_mul_f32 v[184:185], v[184:185], v[20:21] op_sel_hi:[1,0]
	v_pk_mul_f32 v[186:187], v[186:187], v[20:21] op_sel_hi:[1,0]
	v_pk_mul_f32 v[188:189], v[188:189], v[20:21] op_sel_hi:[1,0]
	v_pk_mul_f32 v[190:191], v[190:191], v[20:21] op_sel_hi:[1,0]
	v_pk_mul_f32 v[192:193], v[192:193], v[20:21] op_sel_hi:[1,0]
	v_pk_mul_f32 v[194:195], v[194:195], v[20:21] op_sel_hi:[1,0]
	v_pk_mul_f32 v[180:181], v[24:25], v[180:181]
	v_pk_mul_f32 v[182:183], v[26:27], v[182:183]
	v_pk_mul_f32 v[184:185], v[28:29], v[184:185]
	v_pk_mul_f32 v[186:187], v[30:31], v[186:187]
	v_pk_mul_f32 v[188:189], v[32:33], v[188:189]
	v_pk_mul_f32 v[190:191], v[34:35], v[190:191]
	v_pk_mul_f32 v[192:193], v[36:37], v[192:193]
	v_pk_mul_f32 v[194:195], v[38:39], v[194:195]
	v_pk_fma_f32 v[180:181], v[40:41], v[180:181], v[80:81]
	v_pk_fma_f32 v[182:183], v[42:43], v[182:183], v[82:83]
	v_pk_fma_f32 v[184:185], v[64:65], v[184:185], v[84:85]
	v_pk_fma_f32 v[186:187], v[66:67], v[186:187], v[86:87]
	v_pk_fma_f32 v[188:189], v[68:69], v[188:189], v[88:89]
	v_pk_fma_f32 v[190:191], v[70:71], v[190:191], v[90:91]
	v_pk_fma_f32 v[192:193], v[72:73], v[192:193], v[92:93]
	v_pk_fma_f32 v[194:195], v[74:75], v[194:195], v[94:95]
	v_cvt_pk_bf16_f32 v180, v180, v181
	v_cvt_pk_bf16_f32 v181, v182, v183
	v_cvt_pk_bf16_f32 v184, v184, v185
	v_cvt_pk_bf16_f32 v185, v186, v187
	v_cvt_pk_bf16_f32 v188, v188, v189
	v_cvt_pk_bf16_f32 v189, v190, v191
	v_cvt_pk_bf16_f32 v192, v192, v193
	v_cvt_pk_bf16_f32 v193, v194, v195
	global_store_dwordx2 v2, v[180:181], s[10:11]
	global_store_dwordx2 v2, v[184:185], s[10:11] offset:512
	global_store_dwordx2 v2, v[188:189], s[10:11] offset:1024
	global_store_dwordx2 v2, v[192:193], s[10:11] offset:1536
	s_add_u32 s10, s10, 0x800
	s_addc_u32 s11, s11, 0
	v_pk_mul_f32 v[196:197], v[196:197], v[22:23] op_sel_hi:[1,0]
	v_pk_mul_f32 v[198:199], v[198:199], v[22:23] op_sel_hi:[1,0]
	v_pk_mul_f32 v[200:201], v[200:201], v[22:23] op_sel_hi:[1,0]
	v_pk_mul_f32 v[202:203], v[202:203], v[22:23] op_sel_hi:[1,0]
	v_pk_mul_f32 v[204:205], v[204:205], v[22:23] op_sel_hi:[1,0]
	v_pk_mul_f32 v[206:207], v[206:207], v[22:23] op_sel_hi:[1,0]
	v_pk_mul_f32 v[208:209], v[208:209], v[22:23] op_sel_hi:[1,0]
	v_pk_mul_f32 v[210:211], v[210:211], v[22:23] op_sel_hi:[1,0]
	v_pk_mul_f32 v[196:197], v[24:25], v[196:197]
	v_pk_mul_f32 v[198:199], v[26:27], v[198:199]
	v_pk_mul_f32 v[200:201], v[28:29], v[200:201]
	v_pk_mul_f32 v[202:203], v[30:31], v[202:203]
	v_pk_mul_f32 v[204:205], v[32:33], v[204:205]
	v_pk_mul_f32 v[206:207], v[34:35], v[206:207]
	v_pk_mul_f32 v[208:209], v[36:37], v[208:209]
	v_pk_mul_f32 v[210:211], v[38:39], v[210:211]
	v_pk_fma_f32 v[196:197], v[40:41], v[196:197], v[80:81]
	v_pk_fma_f32 v[198:199], v[42:43], v[198:199], v[82:83]
	v_pk_fma_f32 v[200:201], v[64:65], v[200:201], v[84:85]
	v_pk_fma_f32 v[202:203], v[66:67], v[202:203], v[86:87]
	v_pk_fma_f32 v[204:205], v[68:69], v[204:205], v[88:89]
	v_pk_fma_f32 v[206:207], v[70:71], v[206:207], v[90:91]
	v_pk_fma_f32 v[208:209], v[72:73], v[208:209], v[92:93]
	v_pk_fma_f32 v[210:211], v[74:75], v[210:211], v[94:95]
	v_cvt_pk_bf16_f32 v196, v196, v197
	v_cvt_pk_bf16_f32 v197, v198, v199
	v_cvt_pk_bf16_f32 v200, v200, v201
	v_cvt_pk_bf16_f32 v201, v202, v203
	v_cvt_pk_bf16_f32 v204, v204, v205
	v_cvt_pk_bf16_f32 v205, v206, v207
	v_cvt_pk_bf16_f32 v208, v208, v209
	v_cvt_pk_bf16_f32 v209, v210, v211
	global_store_dwordx2 v2, v[196:197], s[10:11]
	global_store_dwordx2 v2, v[200:201], s[10:11] offset:512
	global_store_dwordx2 v2, v[204:205], s[10:11] offset:1024
	global_store_dwordx2 v2, v[208:209], s[10:11] offset:1536
	s_add_u32 s10, s10, 0x800
	s_addc_u32 s11, s11, 0
	v_pk_mul_f32 v[212:213], v[212:213], v[62:63] op_sel_hi:[1,0]
	v_pk_mul_f32 v[214:215], v[214:215], v[62:63] op_sel_hi:[1,0]
	v_pk_mul_f32 v[216:217], v[216:217], v[62:63] op_sel_hi:[1,0]
	v_pk_mul_f32 v[218:219], v[218:219], v[62:63] op_sel_hi:[1,0]
	v_pk_mul_f32 v[220:221], v[220:221], v[62:63] op_sel_hi:[1,0]
	v_pk_mul_f32 v[222:223], v[222:223], v[62:63] op_sel_hi:[1,0]
	v_pk_mul_f32 v[224:225], v[224:225], v[62:63] op_sel_hi:[1,0]
	v_pk_mul_f32 v[226:227], v[226:227], v[62:63] op_sel_hi:[1,0]
	v_pk_mul_f32 v[212:213], v[24:25], v[212:213]
	v_pk_mul_f32 v[214:215], v[26:27], v[214:215]
	v_pk_mul_f32 v[216:217], v[28:29], v[216:217]
	v_pk_mul_f32 v[218:219], v[30:31], v[218:219]
	v_pk_mul_f32 v[220:221], v[32:33], v[220:221]
	v_pk_mul_f32 v[222:223], v[34:35], v[222:223]
	v_pk_mul_f32 v[224:225], v[36:37], v[224:225]
	v_pk_mul_f32 v[226:227], v[38:39], v[226:227]
	v_pk_fma_f32 v[212:213], v[40:41], v[212:213], v[80:81]
	v_pk_fma_f32 v[214:215], v[42:43], v[214:215], v[82:83]
	v_pk_fma_f32 v[216:217], v[64:65], v[216:217], v[84:85]
	v_pk_fma_f32 v[218:219], v[66:67], v[218:219], v[86:87]
	v_pk_fma_f32 v[220:221], v[68:69], v[220:221], v[88:89]
	v_pk_fma_f32 v[222:223], v[70:71], v[222:223], v[90:91]
	v_pk_fma_f32 v[224:225], v[72:73], v[224:225], v[92:93]
	v_pk_fma_f32 v[226:227], v[74:75], v[226:227], v[94:95]
	v_cvt_pk_bf16_f32 v212, v212, v213
	v_cvt_pk_bf16_f32 v213, v214, v215
	v_cvt_pk_bf16_f32 v216, v216, v217
	v_cvt_pk_bf16_f32 v217, v218, v219
	v_cvt_pk_bf16_f32 v220, v220, v221
	v_cvt_pk_bf16_f32 v221, v222, v223
	v_cvt_pk_bf16_f32 v224, v224, v225
	v_cvt_pk_bf16_f32 v225, v226, v227
	global_store_dwordx2 v2, v[212:213], s[10:11]
	global_store_dwordx2 v2, v[216:217], s[10:11] offset:512
	global_store_dwordx2 v2, v[220:221], s[10:11] offset:1024
	global_store_dwordx2 v2, v[224:225], s[10:11] offset:1536
	s_add_u32 s10, s10, 0x800
	s_addc_u32 s11, s11, 0
	global_load_dwordx4 v[164:167], v1, s[8:9]
	global_load_dwordx4 v[168:171], v1, s[8:9] offset:1024
	global_load_dwordx4 v[172:175], v1, s[8:9] offset:2048
	global_load_dwordx4 v[176:179], v1, s[8:9] offset:3072
	s_add_u32 s8, s8, 0x1000
	s_addc_u32 s9, s9, 0
	global_load_dwordx4 v[180:183], v1, s[8:9]
	global_load_dwordx4 v[184:187], v1, s[8:9] offset:1024
	global_load_dwordx4 v[188:191], v1, s[8:9] offset:2048
	global_load_dwordx4 v[192:195], v1, s[8:9] offset:3072
	s_add_u32 s8, s8, 0x1000
	s_addc_u32 s9, s9, 0
	global_load_dwordx4 v[196:199], v1, s[8:9]
	global_load_dwordx4 v[200:203], v1, s[8:9] offset:1024
	global_load_dwordx4 v[204:207], v1, s[8:9] offset:2048
	global_load_dwordx4 v[208:211], v1, s[8:9] offset:3072
	s_add_u32 s8, s8, 0x1000
	s_addc_u32 s9, s9, 0
	global_load_dwordx4 v[212:215], v1, s[8:9]
	global_load_dwordx4 v[216:219], v1, s[8:9] offset:1024
	global_load_dwordx4 v[220:223], v1, s[8:9] offset:2048
	global_load_dwordx4 v[224:227], v1, s[8:9] offset:3072
	s_add_u32 s8, s8, 0x1000
	s_addc_u32 s9, s9, 0
	s_waitcnt vmcnt(32)
; DI unsigned pk2(float lo, float hi) { return f2bf(lo) | (f2bf(hi) << 16); }
; DI void norm_phase(const Args& A, int wave_s, int l, int which, int rows) {
;     ...
;             float ss = 0.f;
; #pragma unroll
;             for (int j = 0; j < 4; ++j) ss += (xv[rr][j].x * xv[rr][j].x + xv[rr][j].y * xv[rr][j].y) + (xv[rr][j].z * xv[rr][j].z + xv[rr][j].w * xv[rr][j].w);
;             ss = wave_sum(C.lane, ss);
;             const float rs = rsqrtf(ss * (1.f / 1024.f) + EPS);
; #pragma unroll
;             for (int j = 0; j < 4; ++j) { const int col = 4 * (C.lane + 64 * j);
;                 const f32x4 y = xv[rr][j] * rs * g[j] * (sc[j] + 1.f) + sh[j];
;                 v2u o; o.x = pk2(y.x, y.y); o.y = pk2(y.z, y.w);
;                 *(v2u*)(C.H + (size_t)m * 1024 + col) = o; }
	v_mul_f32_e32 v10, v96, v96
	v_fmac_f32_e32 v10, v97, v97
	v_fmac_f32_e32 v10, v98, v98
	v_fmac_f32_e32 v10, v99, v99
	v_fmac_f32_e32 v10, v100, v100
	v_fmac_f32_e32 v10, v101, v101
	v_fmac_f32_e32 v10, v102, v102
	v_fmac_f32_e32 v10, v103, v103
	v_fmac_f32_e32 v10, v104, v104
	v_fmac_f32_e32 v10, v105, v105
	v_fmac_f32_e32 v10, v106, v106
	v_fmac_f32_e32 v10, v107, v107
	v_fmac_f32_e32 v10, v108, v108
	v_fmac_f32_e32 v10, v109, v109
	v_fmac_f32_e32 v10, v110, v110
	v_fmac_f32_e32 v10, v111, v111
	v_mul_f32_e32 v11, v112, v112
	v_fmac_f32_e32 v11, v113, v113
	v_fmac_f32_e32 v11, v114, v114
	v_fmac_f32_e32 v11, v115, v115
	v_fmac_f32_e32 v11, v116, v116
	v_fmac_f32_e32 v11, v117, v117
	v_fmac_f32_e32 v11, v118, v118
	v_fmac_f32_e32 v11, v119, v119
	v_fmac_f32_e32 v11, v120, v120
	v_fmac_f32_e32 v11, v121, v121
	v_fmac_f32_e32 v11, v122, v122
	v_fmac_f32_e32 v11, v123, v123
	v_fmac_f32_e32 v11, v124, v124
	v_fmac_f32_e32 v11, v125, v125
	v_fmac_f32_e32 v11, v126, v126
	v_fmac_f32_e32 v11, v127, v127
	v_mul_f32_e32 v12, v128, v128
	v_fmac_f32_e32 v12, v129, v129
	v_fmac_f32_e32 v12, v130, v130
	v_fmac_f32_e32 v12, v131, v131
	v_fmac_f32_e32 v12, v132, v132
	v_fmac_f32_e32 v12, v133, v133
	v_fmac_f32_e32 v12, v134, v134
	v_fmac_f32_e32 v12, v135, v135
	v_fmac_f32_e32 v12, v136, v136
	v_fmac_f32_e32 v12, v137, v137
	v_fmac_f32_e32 v12, v138, v138
	v_fmac_f32_e32 v12, v139, v139
	v_fmac_f32_e32 v12, v140, v140
	v_fmac_f32_e32 v12, v141, v141
	v_fmac_f32_e32 v12, v142, v142
	v_fmac_f32_e32 v12, v143, v143
	v_mul_f32_e32 v13, v144, v144
	v_fmac_f32_e32 v13, v145, v145
	v_fmac_f32_e32 v13, v146, v146
	v_fmac_f32_e32 v13, v147, v147
	v_fmac_f32_e32 v13, v148, v148
	v_fmac_f32_e32 v13, v149, v149
	v_fmac_f32_e32 v13, v150, v150
	v_fmac_f32_e32 v13, v151, v151
	v_fmac_f32_e32 v13, v152, v152
	v_fmac_f32_e32 v13, v153, v153
	v_fmac_f32_e32 v13, v154, v154
	v_fmac_f32_e32 v13, v155, v155
	v_fmac_f32_e32 v13, v156, v156
	v_fmac_f32_e32 v13, v157, v157
	v_fmac_f32_e32 v13, v158, v158
	v_fmac_f32_e32 v13, v159, v159
	ds_bpermute_b32 v14, v4, v10
	ds_bpermute_b32 v15, v4, v11
	ds_bpermute_b32 v16, v4, v12
	ds_bpermute_b32 v17, v4, v13
	s_waitcnt lgkmcnt(0)
	v_add_f32_e32 v10, v10, v14
	v_add_f32_e32 v11, v11, v15
	v_add_f32_e32 v12, v12, v16
	v_add_f32_e32 v13, v13, v17
	ds_bpermute_b32 v14, v5, v10
	ds_bpermute_b32 v15, v5, v11
	ds_bpermute_b32 v16, v5, v12
	ds_bpermute_b32 v17, v5, v13
	s_waitcnt lgkmcnt(0)
	v_add_f32_e32 v10, v10, v14
	v_add_f32_e32 v11, v11, v15
	v_add_f32_e32 v12, v12, v16
	v_add_f32_e32 v13, v13, v17
	ds_bpermute_b32 v14, v6, v10
	ds_bpermute_b32 v15, v6, v11
	ds_bpermute_b32 v16, v6, v12
	ds_bpermute_b32 v17, v6, v13
	s_waitcnt lgkmcnt(0)
	v_add_f32_e32 v10, v10, v14
	v_add_f32_e32 v11, v11, v15
	v_add_f32_e32 v12, v12, v16
	v_add_f32_e32 v13, v13, v17
	ds_bpermute_b32 v14, v7, v10
	ds_bpermute_b32 v15, v7, v11
	ds_bpermute_b32 v16, v7, v12
	ds_bpermute_b32 v17, v7, v13
	s_waitcnt lgkmcnt(0)
	v_add_f32_e32 v10, v10, v14
	v_add_f32_e32 v11, v11, v15
	v_add_f32_e32 v12, v12, v16
	v_add_f32_e32 v13, v13, v17
	ds_bpermute_b32 v14, v8, v10
	ds_bpermute_b32 v15, v8, v11
	ds_bpermute_b32 v16, v8, v12
	ds_bpermute_b32 v17, v8, v13
	s_waitcnt lgkmcnt(0)
	v_add_f32_e32 v10, v10, v14
	v_add_f32_e32 v11, v11, v15
	v_add_f32_e32 v12, v12, v16
	v_add_f32_e32 v13, v13, v17
	ds_bpermute_b32 v14, v9, v10
	ds_bpermute_b32 v15, v9, v11
	ds_bpermute_b32 v16, v9, v12
	ds_bpermute_b32 v17, v9, v13
	s_waitcnt lgkmcnt(0)
	v_add_f32_e32 v10, v10, v14
	v_add_f32_e32 v11, v11, v15
	v_add_f32_e32 v12, v12, v16
	v_add_f32_e32 v13, v13, v17
	v_fma_f32 v10, v10, s32, v60
	v_fma_f32 v11, v11, s32, v60
	v_fma_f32 v12, v12, s32, v60
	v_fma_f32 v13, v13, s32, v60
	v_rsq_f32_e32 v18, v10
	v_rsq_f32_e32 v20, v11
	v_rsq_f32_e32 v22, v12
	v_rsq_f32_e32 v62, v13
	s_nop 0
	v_pk_mul_f32 v[96:97], v[96:97], v[18:19] op_sel_hi:[1,0]
	v_pk_mul_f32 v[98:99], v[98:99], v[18:19] op_sel_hi:[1,0]
	v_pk_mul_f32 v[100:101], v[100:101], v[18:19] op_sel_hi:[1,0]
	v_pk_mul_f32 v[102:103], v[102:103], v[18:19] op_sel_hi:[1,0]
	v_pk_mul_f32 v[104:105], v[104:105], v[18:19] op_sel_hi:[1,0]
	v_pk_mul_f32 v[106:107], v[106:107], v[18:19] op_sel_hi:[1,0]
	v_pk_mul_f32 v[108:109], v[108:109], v[18:19] op_sel_hi:[1,0]
	v_pk_mul_f32 v[110:111], v[110:111], v[18:19] op_sel_hi:[1,0]
	v_pk_mul_f32 v[96:97], v[24:25], v[96:97]
	v_pk_mul_f32 v[98:99], v[26:27], v[98:99]
	v_pk_mul_f32 v[100:101], v[28:29], v[100:101]
	v_pk_mul_f32 v[102:103], v[30:31], v[102:103]
	v_pk_mul_f32 v[104:105], v[32:33], v[104:105]
	v_pk_mul_f32 v[106:107], v[34:35], v[106:107]
	v_pk_mul_f32 v[108:109], v[36:37], v[108:109]
	v_pk_mul_f32 v[110:111], v[38:39], v[110:111]
	v_pk_fma_f32 v[96:97], v[40:41], v[96:97], v[80:81]
	v_pk_fma_f32 v[98:99], v[42:43], v[98:99], v[82:83]
	v_pk_fma_f32 v[100:101], v[64:65], v[100:101], v[84:85]
	v_pk_fma_f32 v[102:103], v[66:67], v[102:103], v[86:87]
	v_pk_fma_f32 v[104:105], v[68:69], v[104:105], v[88:89]
	v_pk_fma_f32 v[106:107], v[70:71], v[106:107], v[90:91]
	v_pk_fma_f32 v[108:109], v[72:73], v[108:109], v[92:93]
	v_pk_fma_f32 v[110:111], v[74:75], v[110:111], v[94:95]
	v_cvt_pk_bf16_f32 v96, v96, v97
	v_cvt_pk_bf16_f32 v97, v98, v99
	v_cvt_pk_bf16_f32 v100, v100, v101
	v_cvt_pk_bf16_f32 v101, v102, v103
	v_cvt_pk_bf16_f32 v104, v104, v105
	v_cvt_pk_bf16_f32 v105, v106, v107
	v_cvt_pk_bf16_f32 v108, v108, v109
	v_cvt_pk_bf16_f32 v109, v110, v111
	global_store_dwordx2 v2, v[96:97], s[10:11]
	global_store_dwordx2 v2, v[100:101], s[10:11] offset:512
	global_store_dwordx2 v2, v[104:105], s[10:11] offset:1024
	global_store_dwordx2 v2, v[108:109], s[10:11] offset:1536
	s_add_u32 s10, s10, 0x800
; DI unsigned pk2(float lo, float hi) { return f2bf(lo) | (f2bf(hi) << 16); }
; DI void norm_phase(const Args& A, int wave_s, int l, int which, int rows) {
;     ...
;             if (m < NLAT) { xr = (from_in ? C.x : C.out) + (size_t)m * 1024; v = m >> 13; }
;             else { xr = (from_in ? C.ctx : C.XC) + (size_t)(m - NLAT) * 1024; v = 4; }
;             modp[rr] = C.SM + SM_MOD + (l * 5 + v) * 6144 + (which == 1 ? 0 : 3072);
; #pragma unroll
;             for (int j = 0; j < 4; ++j) xv[rr][j] = ((const f32x4*)xr)[C.lane + 64 * j];
;     ...
;             for (int j = 0; j < 4; ++j) { const int col = 4 * (C.lane + 64 * j);
;                 const f32x4 y = xv[rr][j] * rs * g[j] * (sc[j] + 1.f) + sh[j];
;                 v2u o; o.x = pk2(y.x, y.y); o.y = pk2(y.z, y.w);
;                 *(v2u*)(C.H + (size_t)m * 1024 + col) = o; }
	s_addc_u32 s11, s11, 0
	v_pk_mul_f32 v[112:113], v[112:113], v[20:21] op_sel_hi:[1,0]
	v_pk_mul_f32 v[114:115], v[114:115], v[20:21] op_sel_hi:[1,0]
	v_pk_mul_f32 v[116:117], v[116:117], v[20:21] op_sel_hi:[1,0]
	v_pk_mul_f32 v[118:119], v[118:119], v[20:21] op_sel_hi:[1,0]
	v_pk_mul_f32 v[120:121], v[120:121], v[20:21] op_sel_hi:[1,0]
	v_pk_mul_f32 v[122:123], v[122:123], v[20:21] op_sel_hi:[1,0]
	v_pk_mul_f32 v[124:125], v[124:125], v[20:21] op_sel_hi:[1,0]
	v_pk_mul_f32 v[126:127], v[126:127], v[20:21] op_sel_hi:[1,0]
	v_pk_mul_f32 v[112:113], v[24:25], v[112:113]
	v_pk_mul_f32 v[114:115], v[26:27], v[114:115]
	v_pk_mul_f32 v[116:117], v[28:29], v[116:117]
	v_pk_mul_f32 v[118:119], v[30:31], v[118:119]
	v_pk_mul_f32 v[120:121], v[32:33], v[120:121]
	v_pk_mul_f32 v[122:123], v[34:35], v[122:123]
	v_pk_mul_f32 v[124:125], v[36:37], v[124:125]
	v_pk_mul_f32 v[126:127], v[38:39], v[126:127]
	v_pk_fma_f32 v[112:113], v[40:41], v[112:113], v[80:81]
	v_pk_fma_f32 v[114:115], v[42:43], v[114:115], v[82:83]
	v_pk_fma_f32 v[116:117], v[64:65], v[116:117], v[84:85]
	v_pk_fma_f32 v[118:119], v[66:67], v[118:119], v[86:87]
	v_pk_fma_f32 v[120:121], v[68:69], v[120:121], v[88:89]
	v_pk_fma_f32 v[122:123], v[70:71], v[122:123], v[90:91]
	v_pk_fma_f32 v[124:125], v[72:73], v[124:125], v[92:93]
	v_pk_fma_f32 v[126:127], v[74:75], v[126:127], v[94:95]
	v_cvt_pk_bf16_f32 v112, v112, v113
	v_cvt_pk_bf16_f32 v113, v114, v115
	v_cvt_pk_bf16_f32 v116, v116, v117
	v_cvt_pk_bf16_f32 v117, v118, v119
	v_cvt_pk_bf16_f32 v120, v120, v121
	v_cvt_pk_bf16_f32 v121, v122, v123
	v_cvt_pk_bf16_f32 v124, v124, v125
	v_cvt_pk_bf16_f32 v125, v126, v127
	global_store_dwordx2 v2, v[112:113], s[10:11]
	global_store_dwordx2 v2, v[116:117], s[10:11] offset:512
	global_store_dwordx2 v2, v[120:121], s[10:11] offset:1024
	global_store_dwordx2 v2, v[124:125], s[10:11] offset:1536
	s_add_u32 s10, s10, 0x800
	s_addc_u32 s11, s11, 0
	v_pk_mul_f32 v[128:129], v[128:129], v[22:23] op_sel_hi:[1,0]
	v_pk_mul_f32 v[130:131], v[130:131], v[22:23] op_sel_hi:[1,0]
	v_pk_mul_f32 v[132:133], v[132:133], v[22:23] op_sel_hi:[1,0]
	v_pk_mul_f32 v[134:135], v[134:135], v[22:23] op_sel_hi:[1,0]
	v_pk_mul_f32 v[136:137], v[136:137], v[22:23] op_sel_hi:[1,0]
	v_pk_mul_f32 v[138:139], v[138:139], v[22:23] op_sel_hi:[1,0]
	v_pk_mul_f32 v[140:141], v[140:141], v[22:23] op_sel_hi:[1,0]
	v_pk_mul_f32 v[142:143], v[142:143], v[22:23] op_sel_hi:[1,0]
	v_pk_mul_f32 v[128:129], v[24:25], v[128:129]
	v_pk_mul_f32 v[130:131], v[26:27], v[130:131]
	v_pk_mul_f32 v[132:133], v[28:29], v[132:133]
	v_pk_mul_f32 v[134:135], v[30:31], v[134:135]
	v_pk_mul_f32 v[136:137], v[32:33], v[136:137]
	v_pk_mul_f32 v[138:139], v[34:35], v[138:139]
	v_pk_mul_f32 v[140:141], v[36:37], v[140:141]
	v_pk_mul_f32 v[142:143], v[38:39], v[142:143]
	v_pk_fma_f32 v[128:129], v[40:41], v[128:129], v[80:81]
	v_pk_fma_f32 v[130:131], v[42:43], v[130:131], v[82:83]
	v_pk_fma_f32 v[132:133], v[64:65], v[132:133], v[84:85]
	v_pk_fma_f32 v[134:135], v[66:67], v[134:135], v[86:87]
	v_pk_fma_f32 v[136:137], v[68:69], v[136:137], v[88:89]
	v_pk_fma_f32 v[138:139], v[70:71], v[138:139], v[90:91]
	v_pk_fma_f32 v[140:141], v[72:73], v[140:141], v[92:93]
	v_pk_fma_f32 v[142:143], v[74:75], v[142:143], v[94:95]
	v_cvt_pk_bf16_f32 v128, v128, v129
	v_cvt_pk_bf16_f32 v129, v130, v131
	v_cvt_pk_bf16_f32 v132, v132, v133
	v_cvt_pk_bf16_f32 v133, v134, v135
	v_cvt_pk_bf16_f32 v136, v136, v137
	v_cvt_pk_bf16_f32 v137, v138, v139
	v_cvt_pk_bf16_f32 v140, v140, v141
	v_cvt_pk_bf16_f32 v141, v142, v143
	global_store_dwordx2 v2, v[128:129], s[10:11]
	global_store_dwordx2 v2, v[132:133], s[10:11] offset:512
	global_store_dwordx2 v2, v[136:137], s[10:11] offset:1024
	global_store_dwordx2 v2, v[140:141], s[10:11] offset:1536
	s_add_u32 s10, s10, 0x800
	s_addc_u32 s11, s11, 0
	v_pk_mul_f32 v[144:145], v[144:145], v[62:63] op_sel_hi:[1,0]
	v_pk_mul_f32 v[146:147], v[146:147], v[62:63] op_sel_hi:[1,0]
	v_pk_mul_f32 v[148:149], v[148:149], v[62:63] op_sel_hi:[1,0]
	v_pk_mul_f32 v[150:151], v[150:151], v[62:63] op_sel_hi:[1,0]
	v_pk_mul_f32 v[152:153], v[152:153], v[62:63] op_sel_hi:[1,0]
	v_pk_mul_f32 v[154:155], v[154:155], v[62:63] op_sel_hi:[1,0]
	v_pk_mul_f32 v[156:157], v[156:157], v[62:63] op_sel_hi:[1,0]
	v_pk_mul_f32 v[158:159], v[158:159], v[62:63] op_sel_hi:[1,0]
	v_pk_mul_f32 v[144:145], v[24:25], v[144:145]
	v_pk_mul_f32 v[146:147], v[26:27], v[146:147]
	v_pk_mul_f32 v[148:149], v[28:29], v[148:149]
	v_pk_mul_f32 v[150:151], v[30:31], v[150:151]
	v_pk_mul_f32 v[152:153], v[32:33], v[152:153]
	v_pk_mul_f32 v[154:155], v[34:35], v[154:155]
	v_pk_mul_f32 v[156:157], v[36:37], v[156:157]
	v_pk_mul_f32 v[158:159], v[38:39], v[158:159]
	v_pk_fma_f32 v[144:145], v[40:41], v[144:145], v[80:81]
	v_pk_fma_f32 v[146:147], v[42:43], v[146:147], v[82:83]
	v_pk_fma_f32 v[148:149], v[64:65], v[148:149], v[84:85]
	v_pk_fma_f32 v[150:151], v[66:67], v[150:151], v[86:87]
	v_pk_fma_f32 v[152:153], v[68:69], v[152:153], v[88:89]
	v_pk_fma_f32 v[154:155], v[70:71], v[154:155], v[90:91]
	v_pk_fma_f32 v[156:157], v[72:73], v[156:157], v[92:93]
	v_pk_fma_f32 v[158:159], v[74:75], v[158:159], v[94:95]
	v_cvt_pk_bf16_f32 v144, v144, v145
	v_cvt_pk_bf16_f32 v145, v146, v147
	v_cvt_pk_bf16_f32 v148, v148, v149
	v_cvt_pk_bf16_f32 v149, v150, v151
	v_cvt_pk_bf16_f32 v152, v152, v153
	v_cvt_pk_bf16_f32 v153, v154, v155
	v_cvt_pk_bf16_f32 v156, v156, v157
	v_cvt_pk_bf16_f32 v157, v158, v159
	global_store_dwordx2 v2, v[144:145], s[10:11]
	global_store_dwordx2 v2, v[148:149], s[10:11] offset:512
	global_store_dwordx2 v2, v[152:153], s[10:11] offset:1024
	global_store_dwordx2 v2, v[156:157], s[10:11] offset:1536
	s_add_u32 s10, s10, 0x800
	s_addc_u32 s11, s11, 0
	s_mul_i32 s5, s6, 5
	s_add_u32 s5, s5, 4
	s_mul_i32 s5, s5, 0x6000
	s_add_u32 s24, s88, 0x100000
	s_addc_u32 s25, s89, 0
	s_add_u32 s24, s24, s5
	s_addc_u32 s25, s25, 0
	s_add_u32 s26, s24, 0x1000
	s_addc_u32 s27, s25, 0
	global_load_dwordx4 v[96:99], v1, s[30:31]
	global_load_dwordx4 v[100:103], v1, s[30:31] offset:1024
	global_load_dwordx4 v[104:107], v1, s[30:31] offset:2048
	global_load_dwordx4 v[108:111], v1, s[30:31] offset:3072
	global_load_dwordx4 v[112:115], v1, s[26:27]
	global_load_dwordx4 v[116:119], v1, s[26:27] offset:1024
	global_load_dwordx4 v[120:123], v1, s[26:27] offset:2048
	global_load_dwordx4 v[124:127], v1, s[26:27] offset:3072
	global_load_dwordx4 v[128:131], v1, s[24:25]
	global_load_dwordx4 v[132:135], v1, s[24:25] offset:1024
	global_load_dwordx4 v[136:139], v1, s[24:25] offset:2048
	global_load_dwordx4 v[140:143], v1, s[24:25] offset:3072
	s_waitcnt vmcnt(28)
; DI unsigned pk2(float lo, float hi) { return f2bf(lo) | (f2bf(hi) << 16); }
; DI void norm_phase(const Args& A, int wave_s, int l, int which, int rows) {
;     ...
;             float ss = 0.f;
; #pragma unroll
;             for (int j = 0; j < 4; ++j) ss += (xv[rr][j].x * xv[rr][j].x + xv[rr][j].y * xv[rr][j].y) + (xv[rr][j].z * xv[rr][j].z + xv[rr][j].w * xv[rr][j].w);
;             ss = wave_sum(C.lane, ss);
;             const float rs = rsqrtf(ss * (1.f / 1024.f) + EPS);
; #pragma unroll
;             for (int j = 0; j < 4; ++j) { const int col = 4 * (C.lane + 64 * j);
;                 const f32x4 y = xv[rr][j] * rs * g[j] * (sc[j] + 1.f) + sh[j];
;                 v2u o; o.x = pk2(y.x, y.y); o.y = pk2(y.z, y.w);
;                 *(v2u*)(C.H + (size_t)m * 1024 + col) = o; }
	v_mul_f32_e32 v10, v164, v164
	v_fmac_f32_e32 v10, v165, v165
	v_fmac_f32_e32 v10, v166, v166
	v_fmac_f32_e32 v10, v167, v167
	v_fmac_f32_e32 v10, v168, v168
	v_fmac_f32_e32 v10, v169, v169
	v_fmac_f32_e32 v10, v170, v170
	v_fmac_f32_e32 v10, v171, v171
	v_fmac_f32_e32 v10, v172, v172
	v_fmac_f32_e32 v10, v173, v173
	v_fmac_f32_e32 v10, v174, v174
	v_fmac_f32_e32 v10, v175, v175
	v_fmac_f32_e32 v10, v176, v176
	v_fmac_f32_e32 v10, v177, v177
	v_fmac_f32_e32 v10, v178, v178
	v_fmac_f32_e32 v10, v179, v179
	v_mul_f32_e32 v11, v180, v180
	v_fmac_f32_e32 v11, v181, v181
	v_fmac_f32_e32 v11, v182, v182
	v_fmac_f32_e32 v11, v183, v183
	v_fmac_f32_e32 v11, v184, v184
	v_fmac_f32_e32 v11, v185, v185
	v_fmac_f32_e32 v11, v186, v186
	v_fmac_f32_e32 v11, v187, v187
	v_fmac_f32_e32 v11, v188, v188
	v_fmac_f32_e32 v11, v189, v189
	v_fmac_f32_e32 v11, v190, v190
	v_fmac_f32_e32 v11, v191, v191
	v_fmac_f32_e32 v11, v192, v192
	v_fmac_f32_e32 v11, v193, v193
	v_fmac_f32_e32 v11, v194, v194
	v_fmac_f32_e32 v11, v195, v195
	v_mul_f32_e32 v12, v196, v196
	v_fmac_f32_e32 v12, v197, v197
	v_fmac_f32_e32 v12, v198, v198
	v_fmac_f32_e32 v12, v199, v199
	v_fmac_f32_e32 v12, v200, v200
	v_fmac_f32_e32 v12, v201, v201
	v_fmac_f32_e32 v12, v202, v202
	v_fmac_f32_e32 v12, v203, v203
	v_fmac_f32_e32 v12, v204, v204
	v_fmac_f32_e32 v12, v205, v205
	v_fmac_f32_e32 v12, v206, v206
	v_fmac_f32_e32 v12, v207, v207
	v_fmac_f32_e32 v12, v208, v208
	v_fmac_f32_e32 v12, v209, v209
	v_fmac_f32_e32 v12, v210, v210
	v_fmac_f32_e32 v12, v211, v211
	v_mul_f32_e32 v13, v212, v212
	v_fmac_f32_e32 v13, v213, v213
	v_fmac_f32_e32 v13, v214, v214
	v_fmac_f32_e32 v13, v215, v215
	v_fmac_f32_e32 v13, v216, v216
	v_fmac_f32_e32 v13, v217, v217
	v_fmac_f32_e32 v13, v218, v218
	v_fmac_f32_e32 v13, v219, v219
	v_fmac_f32_e32 v13, v220, v220
	v_fmac_f32_e32 v13, v221, v221
	v_fmac_f32_e32 v13, v222, v222
	v_fmac_f32_e32 v13, v223, v223
	v_fmac_f32_e32 v13, v224, v224
	v_fmac_f32_e32 v13, v225, v225
	v_fmac_f32_e32 v13, v226, v226
	v_fmac_f32_e32 v13, v227, v227
	ds_bpermute_b32 v14, v4, v10
	ds_bpermute_b32 v15, v4, v11
	ds_bpermute_b32 v16, v4, v12
	ds_bpermute_b32 v17, v4, v13
	s_waitcnt lgkmcnt(0)
	v_add_f32_e32 v10, v10, v14
	v_add_f32_e32 v11, v11, v15
	v_add_f32_e32 v12, v12, v16
	v_add_f32_e32 v13, v13, v17
	ds_bpermute_b32 v14, v5, v10
	ds_bpermute_b32 v15, v5, v11
	ds_bpermute_b32 v16, v5, v12
	ds_bpermute_b32 v17, v5, v13
	s_waitcnt lgkmcnt(0)
	v_add_f32_e32 v10, v10, v14
	v_add_f32_e32 v11, v11, v15
	v_add_f32_e32 v12, v12, v16
	v_add_f32_e32 v13, v13, v17
	ds_bpermute_b32 v14, v6, v10
	ds_bpermute_b32 v15, v6, v11
	ds_bpermute_b32 v16, v6, v12
	ds_bpermute_b32 v17, v6, v13
	s_waitcnt lgkmcnt(0)
	v_add_f32_e32 v10, v10, v14
	v_add_f32_e32 v11, v11, v15
	v_add_f32_e32 v12, v12, v16
	v_add_f32_e32 v13, v13, v17
	ds_bpermute_b32 v14, v7, v10
	ds_bpermute_b32 v15, v7, v11
	ds_bpermute_b32 v16, v7, v12
	ds_bpermute_b32 v17, v7, v13
	s_waitcnt lgkmcnt(0)
	v_add_f32_e32 v10, v10, v14
	v_add_f32_e32 v11, v11, v15
	v_add_f32_e32 v12, v12, v16
	v_add_f32_e32 v13, v13, v17
	ds_bpermute_b32 v14, v8, v10
	ds_bpermute_b32 v15, v8, v11
	ds_bpermute_b32 v16, v8, v12
	ds_bpermute_b32 v17, v8, v13
	s_waitcnt lgkmcnt(0)
	v_add_f32_e32 v10, v10, v14
	v_add_f32_e32 v11, v11, v15
	v_add_f32_e32 v12, v12, v16
	v_add_f32_e32 v13, v13, v17
	ds_bpermute_b32 v14, v9, v10
	ds_bpermute_b32 v15, v9, v11
	ds_bpermute_b32 v16, v9, v12
	ds_bpermute_b32 v17, v9, v13
	s_waitcnt lgkmcnt(0)
	v_add_f32_e32 v10, v10, v14
	v_add_f32_e32 v11, v11, v15
	v_add_f32_e32 v12, v12, v16
	v_add_f32_e32 v13, v13, v17
	v_fma_f32 v10, v10, s32, v60
	v_fma_f32 v11, v11, s32, v60
	v_fma_f32 v12, v12, s32, v60
	v_fma_f32 v13, v13, s32, v60
	v_rsq_f32_e32 v18, v10
	v_rsq_f32_e32 v20, v11
	v_rsq_f32_e32 v22, v12
	v_rsq_f32_e32 v62, v13
	s_nop 0
	v_pk_mul_f32 v[164:165], v[164:165], v[18:19] op_sel_hi:[1,0]
	v_pk_mul_f32 v[166:167], v[166:167], v[18:19] op_sel_hi:[1,0]
	v_pk_mul_f32 v[168:169], v[168:169], v[18:19] op_sel_hi:[1,0]
	v_pk_mul_f32 v[170:171], v[170:171], v[18:19] op_sel_hi:[1,0]
	v_pk_mul_f32 v[172:173], v[172:173], v[18:19] op_sel_hi:[1,0]
	v_pk_mul_f32 v[174:175], v[174:175], v[18:19] op_sel_hi:[1,0]
	v_pk_mul_f32 v[176:177], v[176:177], v[18:19] op_sel_hi:[1,0]
	v_pk_mul_f32 v[178:179], v[178:179], v[18:19] op_sel_hi:[1,0]
	v_pk_mul_f32 v[164:165], v[24:25], v[164:165]
	v_pk_mul_f32 v[166:167], v[26:27], v[166:167]
	v_pk_mul_f32 v[168:169], v[28:29], v[168:169]
	v_pk_mul_f32 v[170:171], v[30:31], v[170:171]
	v_pk_mul_f32 v[172:173], v[32:33], v[172:173]
	v_pk_mul_f32 v[174:175], v[34:35], v[174:175]
	v_pk_mul_f32 v[176:177], v[36:37], v[176:177]
	v_pk_mul_f32 v[178:179], v[38:39], v[178:179]
	v_pk_fma_f32 v[164:165], v[40:41], v[164:165], v[80:81]
	v_pk_fma_f32 v[166:167], v[42:43], v[166:167], v[82:83]
	v_pk_fma_f32 v[168:169], v[64:65], v[168:169], v[84:85]
	v_pk_fma_f32 v[170:171], v[66:67], v[170:171], v[86:87]
	v_pk_fma_f32 v[172:173], v[68:69], v[172:173], v[88:89]
	v_pk_fma_f32 v[174:175], v[70:71], v[174:175], v[90:91]
	v_pk_fma_f32 v[176:177], v[72:73], v[176:177], v[92:93]
	v_pk_fma_f32 v[178:179], v[74:75], v[178:179], v[94:95]
	v_cvt_pk_bf16_f32 v164, v164, v165
	v_cvt_pk_bf16_f32 v165, v166, v167
	v_cvt_pk_bf16_f32 v168, v168, v169
	v_cvt_pk_bf16_f32 v169, v170, v171
	v_cvt_pk_bf16_f32 v172, v172, v173
	v_cvt_pk_bf16_f32 v173, v174, v175
	v_cvt_pk_bf16_f32 v176, v176, v177
	v_cvt_pk_bf16_f32 v177, v178, v179
	global_store_dwordx2 v2, v[164:165], s[10:11]
	global_store_dwordx2 v2, v[168:169], s[10:11] offset:512
	global_store_dwordx2 v2, v[172:173], s[10:11] offset:1024
	global_store_dwordx2 v2, v[176:177], s[10:11] offset:1536
; DI unsigned pk2(float lo, float hi) { return f2bf(lo) | (f2bf(hi) << 16); }
; DI void norm_phase(const Args& A, int wave_s, int l, int which, int rows) {
;     ...
;             else { xr = (from_in ? C.ctx : C.XC) + (size_t)(m - NLAT) * 1024; v = 4; }
;             modp[rr] = C.SM + SM_MOD + (l * 5 + v) * 6144 + (which == 1 ? 0 : 3072);
;     ...
;             for (int j = 0; j < 4; ++j) { const int col = 4 * (C.lane + 64 * j);
;                 const f32x4 y = xv[rr][j] * rs * g[j] * (sc[j] + 1.f) + sh[j];
;                 v2u o; o.x = pk2(y.x, y.y); o.y = pk2(y.z, y.w);
;                 *(v2u*)(C.H + (size_t)m * 1024 + col) = o; }
	s_add_u32 s10, s10, 0x800
	s_addc_u32 s11, s11, 0
	v_pk_mul_f32 v[180:181], v[180:181], v[20:21] op_sel_hi:[1,0]
	v_pk_mul_f32 v[182:183], v[182:183], v[20:21] op_sel_hi:[1,0]
	v_pk_mul_f32 v[184:185], v[184:185], v[20:21] op_sel_hi:[1,0]
	v_pk_mul_f32 v[186:187], v[186:187], v[20:21] op_sel_hi:[1,0]
	v_pk_mul_f32 v[188:189], v[188:189], v[20:21] op_sel_hi:[1,0]
	v_pk_mul_f32 v[190:191], v[190:191], v[20:21] op_sel_hi:[1,0]
	v_pk_mul_f32 v[192:193], v[192:193], v[20:21] op_sel_hi:[1,0]
	v_pk_mul_f32 v[194:195], v[194:195], v[20:21] op_sel_hi:[1,0]
	v_pk_mul_f32 v[180:181], v[24:25], v[180:181]
	v_pk_mul_f32 v[182:183], v[26:27], v[182:183]
	v_pk_mul_f32 v[184:185], v[28:29], v[184:185]
	v_pk_mul_f32 v[186:187], v[30:31], v[186:187]
	v_pk_mul_f32 v[188:189], v[32:33], v[188:189]
	v_pk_mul_f32 v[190:191], v[34:35], v[190:191]
	v_pk_mul_f32 v[192:193], v[36:37], v[192:193]
	v_pk_mul_f32 v[194:195], v[38:39], v[194:195]
	v_pk_fma_f32 v[180:181], v[40:41], v[180:181], v[80:81]
	v_pk_fma_f32 v[182:183], v[42:43], v[182:183], v[82:83]
	v_pk_fma_f32 v[184:185], v[64:65], v[184:185], v[84:85]
	v_pk_fma_f32 v[186:187], v[66:67], v[186:187], v[86:87]
	v_pk_fma_f32 v[188:189], v[68:69], v[188:189], v[88:89]
	v_pk_fma_f32 v[190:191], v[70:71], v[190:191], v[90:91]
	v_pk_fma_f32 v[192:193], v[72:73], v[192:193], v[92:93]
	v_pk_fma_f32 v[194:195], v[74:75], v[194:195], v[94:95]
	v_cvt_pk_bf16_f32 v180, v180, v181
	v_cvt_pk_bf16_f32 v181, v182, v183
	v_cvt_pk_bf16_f32 v184, v184, v185
	v_cvt_pk_bf16_f32 v185, v186, v187
	v_cvt_pk_bf16_f32 v188, v188, v189
	v_cvt_pk_bf16_f32 v189, v190, v191
	v_cvt_pk_bf16_f32 v192, v192, v193
	v_cvt_pk_bf16_f32 v193, v194, v195
	global_store_dwordx2 v2, v[180:181], s[10:11]
	global_store_dwordx2 v2, v[184:185], s[10:11] offset:512
	global_store_dwordx2 v2, v[188:189], s[10:11] offset:1024
	global_store_dwordx2 v2, v[192:193], s[10:11] offset:1536
	s_add_u32 s10, s10, 0x800
	s_addc_u32 s11, s11, 0
	v_pk_mul_f32 v[196:197], v[196:197], v[22:23] op_sel_hi:[1,0]
	v_pk_mul_f32 v[198:199], v[198:199], v[22:23] op_sel_hi:[1,0]
	v_pk_mul_f32 v[200:201], v[200:201], v[22:23] op_sel_hi:[1,0]
	v_pk_mul_f32 v[202:203], v[202:203], v[22:23] op_sel_hi:[1,0]
	v_pk_mul_f32 v[204:205], v[204:205], v[22:23] op_sel_hi:[1,0]
	v_pk_mul_f32 v[206:207], v[206:207], v[22:23] op_sel_hi:[1,0]
	v_pk_mul_f32 v[208:209], v[208:209], v[22:23] op_sel_hi:[1,0]
	v_pk_mul_f32 v[210:211], v[210:211], v[22:23] op_sel_hi:[1,0]
	v_pk_mul_f32 v[196:197], v[24:25], v[196:197]
	v_pk_mul_f32 v[198:199], v[26:27], v[198:199]
	v_pk_mul_f32 v[200:201], v[28:29], v[200:201]
	v_pk_mul_f32 v[202:203], v[30:31], v[202:203]
	v_pk_mul_f32 v[204:205], v[32:33], v[204:205]
	v_pk_mul_f32 v[206:207], v[34:35], v[206:207]
	v_pk_mul_f32 v[208:209], v[36:37], v[208:209]
	v_pk_mul_f32 v[210:211], v[38:39], v[210:211]
	v_pk_fma_f32 v[196:197], v[40:41], v[196:197], v[80:81]
	v_pk_fma_f32 v[198:199], v[42:43], v[198:199], v[82:83]
	v_pk_fma_f32 v[200:201], v[64:65], v[200:201], v[84:85]
	v_pk_fma_f32 v[202:203], v[66:67], v[202:203], v[86:87]
	v_pk_fma_f32 v[204:205], v[68:69], v[204:205], v[88:89]
	v_pk_fma_f32 v[206:207], v[70:71], v[206:207], v[90:91]
	v_pk_fma_f32 v[208:209], v[72:73], v[208:209], v[92:93]
	v_pk_fma_f32 v[210:211], v[74:75], v[210:211], v[94:95]
	v_cvt_pk_bf16_f32 v196, v196, v197
	v_cvt_pk_bf16_f32 v197, v198, v199
	v_cvt_pk_bf16_f32 v200, v200, v201
	v_cvt_pk_bf16_f32 v201, v202, v203
	v_cvt_pk_bf16_f32 v204, v204, v205
	v_cvt_pk_bf16_f32 v205, v206, v207
	v_cvt_pk_bf16_f32 v208, v208, v209
	v_cvt_pk_bf16_f32 v209, v210, v211
	global_store_dwordx2 v2, v[196:197], s[10:11]
	global_store_dwordx2 v2, v[200:201], s[10:11] offset:512
	global_store_dwordx2 v2, v[204:205], s[10:11] offset:1024
	global_store_dwordx2 v2, v[208:209], s[10:11] offset:1536
	s_add_u32 s10, s10, 0x800
	s_addc_u32 s11, s11, 0
	v_pk_mul_f32 v[212:213], v[212:213], v[62:63] op_sel_hi:[1,0]
	v_pk_mul_f32 v[214:215], v[214:215], v[62:63] op_sel_hi:[1,0]
	v_pk_mul_f32 v[216:217], v[216:217], v[62:63] op_sel_hi:[1,0]
	v_pk_mul_f32 v[218:219], v[218:219], v[62:63] op_sel_hi:[1,0]
	v_pk_mul_f32 v[220:221], v[220:221], v[62:63] op_sel_hi:[1,0]
	v_pk_mul_f32 v[222:223], v[222:223], v[62:63] op_sel_hi:[1,0]
	v_pk_mul_f32 v[224:225], v[224:225], v[62:63] op_sel_hi:[1,0]
	v_pk_mul_f32 v[226:227], v[226:227], v[62:63] op_sel_hi:[1,0]
	v_pk_mul_f32 v[212:213], v[24:25], v[212:213]
	v_pk_mul_f32 v[214:215], v[26:27], v[214:215]
	v_pk_mul_f32 v[216:217], v[28:29], v[216:217]
	v_pk_mul_f32 v[218:219], v[30:31], v[218:219]
	v_pk_mul_f32 v[220:221], v[32:33], v[220:221]
	v_pk_mul_f32 v[222:223], v[34:35], v[222:223]
	v_pk_mul_f32 v[224:225], v[36:37], v[224:225]
	v_pk_mul_f32 v[226:227], v[38:39], v[226:227]
	v_pk_fma_f32 v[212:213], v[40:41], v[212:213], v[80:81]
	v_pk_fma_f32 v[214:215], v[42:43], v[214:215], v[82:83]
	v_pk_fma_f32 v[216:217], v[64:65], v[216:217], v[84:85]
	v_pk_fma_f32 v[218:219], v[66:67], v[218:219], v[86:87]
	v_pk_fma_f32 v[220:221], v[68:69], v[220:221], v[88:89]
	v_pk_fma_f32 v[222:223], v[70:71], v[222:223], v[90:91]
	v_pk_fma_f32 v[224:225], v[72:73], v[224:225], v[92:93]
	v_pk_fma_f32 v[226:227], v[74:75], v[226:227], v[94:95]
	v_cvt_pk_bf16_f32 v212, v212, v213
	v_cvt_pk_bf16_f32 v213, v214, v215
	v_cvt_pk_bf16_f32 v216, v216, v217
	v_cvt_pk_bf16_f32 v217, v218, v219
	v_cvt_pk_bf16_f32 v220, v220, v221
	v_cvt_pk_bf16_f32 v221, v222, v223
	v_cvt_pk_bf16_f32 v224, v224, v225
	v_cvt_pk_bf16_f32 v225, v226, v227
	global_store_dwordx2 v2, v[212:213], s[10:11]
	global_store_dwordx2 v2, v[216:217], s[10:11] offset:512
	global_store_dwordx2 v2, v[220:221], s[10:11] offset:1024
	global_store_dwordx2 v2, v[224:225], s[10:11] offset:1536
	s_add_u32 s10, s10, 0x800
	s_addc_u32 s11, s11, 0
	s_add_u32 s10, s88, 0x3800000
	s_addc_u32 s11, s89, 0
	s_add_u32 s10, s10, 0x4000000
	s_addc_u32 s11, s11, 0
	s_lshl_b32 s5, s7, 11
	s_add_u32 s10, s10, s5
	s_addc_u32 s11, s11, 0
	s_waitcnt vmcnt(16)
	v_pk_add_f32 v[112:113], v[112:113], 1.0 op_sel_hi:[1,0]
	v_pk_add_f32 v[114:115], v[114:115], 1.0 op_sel_hi:[1,0]
	v_pk_add_f32 v[116:117], v[116:117], 1.0 op_sel_hi:[1,0]
	v_pk_add_f32 v[118:119], v[118:119], 1.0 op_sel_hi:[1,0]
	v_pk_add_f32 v[120:121], v[120:121], 1.0 op_sel_hi:[1,0]
	v_pk_add_f32 v[122:123], v[122:123], 1.0 op_sel_hi:[1,0]
	v_pk_add_f32 v[124:125], v[124:125], 1.0 op_sel_hi:[1,0]
	v_pk_add_f32 v[126:127], v[126:127], 1.0 op_sel_hi:[1,0]
	s_cmp_eq_u32 s2, 0
	s_cbranch_scc1 .Lnorm_n1_done
; DI unsigned pk2(float lo, float hi) { return f2bf(lo) | (f2bf(hi) << 16); }
; DI void norm_phase(const Args& A, int wave_s, int l, int which, int rows) {
;     ...
;             float ss = 0.f;
; #pragma unroll
;             for (int j = 0; j < 4; ++j) ss += (xv[rr][j].x * xv[rr][j].x + xv[rr][j].y * xv[rr][j].y) + (xv[rr][j].z * xv[rr][j].z + xv[rr][j].w * xv[rr][j].w);
;             ss = wave_sum(C.lane, ss);
;             const float rs = rsqrtf(ss * (1.f / 1024.f) + EPS);
; #pragma unroll
;             for (int j = 0; j < 4; ++j) { const int col = 4 * (C.lane + 64 * j);
;                 const f32x4 y = xv[rr][j] * rs * g[j] * (sc[j] + 1.f) + sh[j];
;                 v2u o; o.x = pk2(y.x, y.y); o.y = pk2(y.z, y.w);
;                 *(v2u*)(C.H + (size_t)m * 1024 + col) = o; }
	v_mul_f32_e32 v10, v96, v96
	v_fmac_f32_e32 v10, v97, v97
	v_fmac_f32_e32 v10, v98, v98
	v_fmac_f32_e32 v10, v99, v99
	v_fmac_f32_e32 v10, v100, v100
	v_fmac_f32_e32 v10, v101, v101
	v_fmac_f32_e32 v10, v102, v102
	v_fmac_f32_e32 v10, v103, v103
	v_fmac_f32_e32 v10, v104, v104
	v_fmac_f32_e32 v10, v105, v105
	v_fmac_f32_e32 v10, v106, v106
	v_fmac_f32_e32 v10, v107, v107
	v_fmac_f32_e32 v10, v108, v108
	v_fmac_f32_e32 v10, v109, v109
	v_fmac_f32_e32 v10, v110, v110
	v_fmac_f32_e32 v10, v111, v111
	ds_bpermute_b32 v14, v4, v10
	s_waitcnt lgkmcnt(0)
	v_add_f32_e32 v10, v10, v14
	ds_bpermute_b32 v14, v5, v10
	s_waitcnt lgkmcnt(0)
	v_add_f32_e32 v10, v10, v14
	ds_bpermute_b32 v14, v6, v10
	s_waitcnt lgkmcnt(0)
	v_add_f32_e32 v10, v10, v14
	ds_bpermute_b32 v14, v7, v10
	s_waitcnt lgkmcnt(0)
	v_add_f32_e32 v10, v10, v14
	ds_bpermute_b32 v14, v8, v10
	s_waitcnt lgkmcnt(0)
	v_add_f32_e32 v10, v10, v14
	ds_bpermute_b32 v14, v9, v10
	s_waitcnt lgkmcnt(0)
	v_add_f32_e32 v10, v10, v14
	v_fma_f32 v10, v10, s32, v60
	v_rsq_f32_e32 v18, v10
	s_nop 0
	v_pk_mul_f32 v[96:97], v[96:97], v[18:19] op_sel_hi:[1,0]
	v_pk_mul_f32 v[98:99], v[98:99], v[18:19] op_sel_hi:[1,0]
	v_pk_mul_f32 v[100:101], v[100:101], v[18:19] op_sel_hi:[1,0]
	v_pk_mul_f32 v[102:103], v[102:103], v[18:19] op_sel_hi:[1,0]
	v_pk_mul_f32 v[104:105], v[104:105], v[18:19] op_sel_hi:[1,0]
	v_pk_mul_f32 v[106:107], v[106:107], v[18:19] op_sel_hi:[1,0]
	v_pk_mul_f32 v[108:109], v[108:109], v[18:19] op_sel_hi:[1,0]
	v_pk_mul_f32 v[110:111], v[110:111], v[18:19] op_sel_hi:[1,0]
	v_pk_mul_f32 v[96:97], v[24:25], v[96:97]
	v_pk_mul_f32 v[98:99], v[26:27], v[98:99]
	v_pk_mul_f32 v[100:101], v[28:29], v[100:101]
	v_pk_mul_f32 v[102:103], v[30:31], v[102:103]
	v_pk_mul_f32 v[104:105], v[32:33], v[104:105]
	v_pk_mul_f32 v[106:107], v[34:35], v[106:107]
	v_pk_mul_f32 v[108:109], v[36:37], v[108:109]
	v_pk_mul_f32 v[110:111], v[38:39], v[110:111]
	v_pk_fma_f32 v[96:97], v[112:113], v[96:97], v[128:129]
	v_pk_fma_f32 v[98:99], v[114:115], v[98:99], v[130:131]
	v_pk_fma_f32 v[100:101], v[116:117], v[100:101], v[132:133]
	v_pk_fma_f32 v[102:103], v[118:119], v[102:103], v[134:135]
	v_pk_fma_f32 v[104:105], v[120:121], v[104:105], v[136:137]
	v_pk_fma_f32 v[106:107], v[122:123], v[106:107], v[138:139]
	v_pk_fma_f32 v[108:109], v[124:125], v[108:109], v[140:141]
	v_pk_fma_f32 v[110:111], v[126:127], v[110:111], v[142:143]
	v_cvt_pk_bf16_f32 v96, v96, v97
	v_cvt_pk_bf16_f32 v97, v98, v99
	v_cvt_pk_bf16_f32 v100, v100, v101
	v_cvt_pk_bf16_f32 v101, v102, v103
	v_cvt_pk_bf16_f32 v104, v104, v105
	v_cvt_pk_bf16_f32 v105, v106, v107
	v_cvt_pk_bf16_f32 v108, v108, v109
	v_cvt_pk_bf16_f32 v109, v110, v111
	global_store_dwordx2 v2, v[96:97], s[10:11]
	global_store_dwordx2 v2, v[100:101], s[10:11] offset:512
	global_store_dwordx2 v2, v[104:105], s[10:11] offset:1024
	global_store_dwordx2 v2, v[108:109], s[10:11] offset:1536
.Lnorm_n1_done:
.LBB0_61:
	v_mbcnt_lo_u32_b32 v0, -1, 0
	v_mbcnt_hi_u32_b32 v0, -1, v0
	s_waitcnt vmcnt(0)
	s_nop 0
	v_sub_u32_e32 v0, 0, v0
	v_cmp_eq_u32_e32 vcc, s94, v0
	s_barrier
	s_and_saveexec_b64 s[4:5], vcc
	s_cbranch_execz .LBB0_113
	v_readlane_b32 s6, v254, 62
	s_mov_b32 s2, s64
	s_waitcnt vmcnt(0) expcnt(0) lgkmcnt(0)
	v_mov_b32_e32 v0, s6
	ds_read_b32 v2, v0
	v_readlane_b32 s6, v254, 63
	s_waitcnt lgkmcnt(0)
	v_cmp_ne_u32_e32 vcc, 0, v2
	v_mov_b32_e32 v0, s6
	ds_read_b32 v0, v0
	s_cbranch_vccnz .LBB0_77
	s_mov_b32 s12, 1
	s_branch .LBB0_65

; DI void hgrn_scan_phase(const Args& A, int wave_s) {
;     ...
;     for (int gid = blockIdx.x * 512 + C.tid; gid < 32 * 2048; gid += gridDim.x * 512) {
;         const int seq = gid >> 11, e = gid & 2047, k = e >> 5;
;         unsigned* SL = (unsigned*)C.ST + (size_t)seq * 132 * 2048 + e; const float* D = DEC + seq * 132 * 64 + k;
;         float s0 = 0.f, s1 = 0.f;
;         for (int n = 0; n < 132; n += 12) {
;             unsigned sl[12]; float d[12];
; #pragma unroll
;             for (int j = 0; j < 12; ++j) { sl[j] = SL[(size_t)(n + j) * 2048]; d[j] = D[(n + j) * 64]; }
.LBB0_301:
	v_lshrrev_b32_e32 v0, 11, v10
	v_and_b32_e32 v1, 0x7ff, v10
	v_mov_b32_e32 v4, 0x108000
	v_mul_u32_u24_e32 v2, v0, v4
	v_lshl_add_u32 v2, v1, 2, v2
	v_lshrrev_b32_e32 v1, 5, v1
	v_mov_b32_e32 v4, 0x8400
	v_mul_u32_u24_e32 v3, v0, v4
	v_lshl_add_u32 v3, v1, 2, v3
	s_add_u32 s12, s88, 0x18200000
	s_addc_u32 s13, s89, 0
	s_add_u32 s14, s88, 0x1c400000
	s_addc_u32 s15, s89, 0
	v_mov_b32_e32 v6, 0
	v_mov_b32_e32 v7, 0
	s_mov_b32 s16, 4
.Lscan_batch:
	global_load_dword v78, v2, s[12:13]
	s_add_u32 s12, s12, 0x2000
	s_addc_u32 s13, s13, 0
	global_load_dword v12, v3, s[14:15]
	s_add_u32 s14, s14, 0x100
	s_addc_u32 s15, s15, 0
	global_load_dword v79, v2, s[12:13]
	s_add_u32 s12, s12, 0x2000
	s_addc_u32 s13, s13, 0
	global_load_dword v13, v3, s[14:15]
	s_add_u32 s14, s14, 0x100
	s_addc_u32 s15, s15, 0
	global_load_dword v80, v2, s[12:13]
	s_add_u32 s12, s12, 0x2000
	s_addc_u32 s13, s13, 0
	global_load_dword v14, v3, s[14:15]
	s_add_u32 s14, s14, 0x100
	s_addc_u32 s15, s15, 0
	global_load_dword v81, v2, s[12:13]
	s_add_u32 s12, s12, 0x2000
	s_addc_u32 s13, s13, 0
	global_load_dword v15, v3, s[14:15]
	s_add_u32 s14, s14, 0x100
	s_addc_u32 s15, s15, 0
	global_load_dword v82, v2, s[12:13]
	s_add_u32 s12, s12, 0x2000
	s_addc_u32 s13, s13, 0
	global_load_dword v16, v3, s[14:15]
	s_add_u32 s14, s14, 0x100
	s_addc_u32 s15, s15, 0
	global_load_dword v83, v2, s[12:13]
	s_add_u32 s12, s12, 0x2000
	s_addc_u32 s13, s13, 0
	global_load_dword v17, v3, s[14:15]
	s_add_u32 s14, s14, 0x100
	s_addc_u32 s15, s15, 0
	global_load_dword v84, v2, s[12:13]
	s_add_u32 s12, s12, 0x2000
	s_addc_u32 s13, s13, 0
	global_load_dword v18, v3, s[14:15]
	s_add_u32 s14, s14, 0x100
	s_addc_u32 s15, s15, 0
	global_load_dword v85, v2, s[12:13]
	s_add_u32 s12, s12, 0x2000
	s_addc_u32 s13, s13, 0
	global_load_dword v19, v3, s[14:15]
	s_add_u32 s14, s14, 0x100
	s_addc_u32 s15, s15, 0
	global_load_dword v86, v2, s[12:13]
	s_add_u32 s12, s12, 0x2000
	s_addc_u32 s13, s13, 0
	global_load_dword v20, v3, s[14:15]
	s_add_u32 s14, s14, 0x100
	s_addc_u32 s15, s15, 0
	global_load_dword v87, v2, s[12:13]
	s_add_u32 s12, s12, 0x2000
	s_addc_u32 s13, s13, 0
	global_load_dword v21, v3, s[14:15]
	s_add_u32 s14, s14, 0x100
	s_addc_u32 s15, s15, 0
	global_load_dword v88, v2, s[12:13]
	s_add_u32 s12, s12, 0x2000
	s_addc_u32 s13, s13, 0
	global_load_dword v22, v3, s[14:15]
	s_add_u32 s14, s14, 0x100
	s_addc_u32 s15, s15, 0
	global_load_dword v89, v2, s[12:13]
	s_add_u32 s12, s12, 0x2000
	s_addc_u32 s13, s13, 0
	global_load_dword v23, v3, s[14:15]
	s_add_u32 s14, s14, 0x100
	s_addc_u32 s15, s15, 0
	global_load_dword v90, v2, s[12:13]
	s_add_u32 s12, s12, 0x2000
	s_addc_u32 s13, s13, 0
	global_load_dword v24, v3, s[14:15]
	s_add_u32 s14, s14, 0x100
	s_addc_u32 s15, s15, 0
	global_load_dword v91, v2, s[12:13]
	s_add_u32 s12, s12, 0x2000
	s_addc_u32 s13, s13, 0
	global_load_dword v25, v3, s[14:15]
	s_add_u32 s14, s14, 0x100
	s_addc_u32 s15, s15, 0
	global_load_dword v92, v2, s[12:13]
	s_add_u32 s12, s12, 0x2000
	s_addc_u32 s13, s13, 0
	global_load_dword v26, v3, s[14:15]
	s_add_u32 s14, s14, 0x100
	s_addc_u32 s15, s15, 0
	global_load_dword v93, v2, s[12:13]
	s_add_u32 s12, s12, 0x2000
	s_addc_u32 s13, s13, 0
	global_load_dword v27, v3, s[14:15]
	s_add_u32 s14, s14, 0x100
	s_addc_u32 s15, s15, 0
	global_load_dword v94, v2, s[12:13]
	s_add_u32 s12, s12, 0x2000
	s_addc_u32 s13, s13, 0
	global_load_dword v28, v3, s[14:15]
	s_add_u32 s14, s14, 0x100
	s_addc_u32 s15, s15, 0
	global_load_dword v95, v2, s[12:13]
	s_add_u32 s12, s12, 0x2000
	s_addc_u32 s13, s13, 0
	global_load_dword v29, v3, s[14:15]
	s_add_u32 s14, s14, 0x100
	s_addc_u32 s15, s15, 0
	global_load_dword v96, v2, s[12:13]
	s_add_u32 s12, s12, 0x2000
	s_addc_u32 s13, s13, 0
	global_load_dword v30, v3, s[14:15]
	s_add_u32 s14, s14, 0x100
	s_addc_u32 s15, s15, 0
	global_load_dword v97, v2, s[12:13]
	s_add_u32 s12, s12, 0x2000
	s_addc_u32 s13, s13, 0
	global_load_dword v31, v3, s[14:15]
	s_add_u32 s14, s14, 0x100
	s_addc_u32 s15, s15, 0
	global_load_dword v98, v2, s[12:13]
	s_add_u32 s12, s12, 0x2000
	s_addc_u32 s13, s13, 0
	global_load_dword v32, v3, s[14:15]
	s_add_u32 s14, s14, 0x100
	s_addc_u32 s15, s15, 0
	global_load_dword v99, v2, s[12:13]
	s_add_u32 s12, s12, 0x2000
	s_addc_u32 s13, s13, 0
	global_load_dword v33, v3, s[14:15]
	s_add_u32 s14, s14, 0x100
	s_addc_u32 s15, s15, 0
	global_load_dword v100, v2, s[12:13]
	s_add_u32 s12, s12, 0x2000
	s_addc_u32 s13, s13, 0
	global_load_dword v34, v3, s[14:15]
	s_add_u32 s14, s14, 0x100
	s_addc_u32 s15, s15, 0
	global_load_dword v101, v2, s[12:13]
	s_add_u32 s12, s12, 0x2000
	s_addc_u32 s13, s13, 0
	global_load_dword v35, v3, s[14:15]
	s_add_u32 s14, s14, 0x100
	s_addc_u32 s15, s15, 0
	global_load_dword v102, v2, s[12:13]
	s_add_u32 s12, s12, 0x2000
	s_addc_u32 s13, s13, 0
	global_load_dword v36, v3, s[14:15]
	s_add_u32 s14, s14, 0x100
	s_addc_u32 s15, s15, 0
	global_load_dword v103, v2, s[12:13]
	s_add_u32 s12, s12, 0x2000
	s_addc_u32 s13, s13, 0
	global_load_dword v37, v3, s[14:15]
	s_add_u32 s14, s14, 0x100
	s_addc_u32 s15, s15, 0
	global_load_dword v104, v2, s[12:13]
	s_add_u32 s12, s12, 0x2000
	s_addc_u32 s13, s13, 0
	global_load_dword v38, v3, s[14:15]
	s_add_u32 s14, s14, 0x100
	s_addc_u32 s15, s15, 0
	global_load_dword v105, v2, s[12:13]
	s_add_u32 s12, s12, 0x2000
	s_addc_u32 s13, s13, 0
	global_load_dword v39, v3, s[14:15]
	s_add_u32 s14, s14, 0x100
	s_addc_u32 s15, s15, 0
	global_load_dword v106, v2, s[12:13]
	s_add_u32 s12, s12, 0x2000
	s_addc_u32 s13, s13, 0
	global_load_dword v40, v3, s[14:15]
	s_add_u32 s14, s14, 0x100
	s_addc_u32 s15, s15, 0
	global_load_dword v107, v2, s[12:13]
	s_add_u32 s12, s12, 0x2000
	s_addc_u32 s13, s13, 0
	global_load_dword v41, v3, s[14:15]
	s_add_u32 s14, s14, 0x100
	s_addc_u32 s15, s15, 0
	global_load_dword v108, v2, s[12:13]
	s_add_u32 s12, s12, 0x2000
	s_addc_u32 s13, s13, 0
	global_load_dword v42, v3, s[14:15]
	s_add_u32 s14, s14, 0x100
	s_addc_u32 s15, s15, 0
	global_load_dword v109, v2, s[12:13]
	s_add_u32 s12, s12, 0x2000
	s_addc_u32 s13, s13, 0
	global_load_dword v43, v3, s[14:15]
	s_add_u32 s14, s14, 0x100
	s_addc_u32 s15, s15, 0
	global_load_dword v110, v2, s[12:13]
	s_add_u32 s12, s12, 0x2000
	s_addc_u32 s13, s13, 0
	global_load_dword v44, v3, s[14:15]
	s_add_u32 s14, s14, 0x100
	s_addc_u32 s15, s15, 0
	s_sub_u32 s12, s12, 0x42000
	s_subb_u32 s13, s13, 0
	s_waitcnt vmcnt(63)
; DI unsigned pk2(float lo, float hi) { return f2bf(lo) | (f2bf(hi) << 16); }
; DI void hgrn_scan_phase(const Args& A, int wave_s) {
;     ...
;             for (int j = 0; j < 12; ++j) { SL[(size_t)(n + j) * 2048] = pk2(s0, s1);
;                 s0 = d[j] * s0 + __builtin_bit_cast(float, sl[j] << 16); s1 = d[j] * s1 + __builtin_bit_cast(float, sl[j] & 0xffff0000u); }
	v_bfe_u32 v8, v6, 16, 1
	v_bfe_u32 v9, v7, 16, 1
	v_add3_u32 v8, v6, v8, s79
	v_add3_u32 v9, v7, v9, s79
	v_lshrrev_b32_e32 v8, 16, v8
	v_and_or_b32 v8, v9, s82, v8
	global_store_dword v2, v8, s[12:13]
	s_add_u32 s12, s12, 0x2000
	s_addc_u32 s13, s13, 0
	v_lshlrev_b32_e32 v9, 16, v78
	v_and_b32_e32 v5, 0xffff0000, v78
	v_fma_f32 v6, v12, v6, v9
	v_fma_f32 v7, v12, v7, v5
	s_waitcnt vmcnt(63)
	v_bfe_u32 v8, v6, 16, 1
	v_bfe_u32 v9, v7, 16, 1
	v_add3_u32 v8, v6, v8, s79
	v_add3_u32 v9, v7, v9, s79
	v_lshrrev_b32_e32 v8, 16, v8
	v_and_or_b32 v8, v9, s82, v8
	global_store_dword v2, v8, s[12:13]
	s_add_u32 s12, s12, 0x2000
	s_addc_u32 s13, s13, 0
	v_lshlrev_b32_e32 v9, 16, v79
	v_and_b32_e32 v5, 0xffff0000, v79
	v_fma_f32 v6, v13, v6, v9
	v_fma_f32 v7, v13, v7, v5
	s_waitcnt vmcnt(62)
	v_bfe_u32 v8, v6, 16, 1
	v_bfe_u32 v9, v7, 16, 1
	v_add3_u32 v8, v6, v8, s79
	v_add3_u32 v9, v7, v9, s79
	v_lshrrev_b32_e32 v8, 16, v8
	v_and_or_b32 v8, v9, s82, v8
	global_store_dword v2, v8, s[12:13]
	s_add_u32 s12, s12, 0x2000
	s_addc_u32 s13, s13, 0
	v_lshlrev_b32_e32 v9, 16, v80
	v_and_b32_e32 v5, 0xffff0000, v80
	v_fma_f32 v6, v14, v6, v9
	v_fma_f32 v7, v14, v7, v5
	s_waitcnt vmcnt(61)
	v_bfe_u32 v8, v6, 16, 1
	v_bfe_u32 v9, v7, 16, 1
	v_add3_u32 v8, v6, v8, s79
	v_add3_u32 v9, v7, v9, s79
	v_lshrrev_b32_e32 v8, 16, v8
	v_and_or_b32 v8, v9, s82, v8
	global_store_dword v2, v8, s[12:13]
	s_add_u32 s12, s12, 0x2000
	s_addc_u32 s13, s13, 0
	v_lshlrev_b32_e32 v9, 16, v81
	v_and_b32_e32 v5, 0xffff0000, v81
	v_fma_f32 v6, v15, v6, v9
	v_fma_f32 v7, v15, v7, v5
	s_waitcnt vmcnt(60)
	v_bfe_u32 v8, v6, 16, 1
	v_bfe_u32 v9, v7, 16, 1
	v_add3_u32 v8, v6, v8, s79
	v_add3_u32 v9, v7, v9, s79
	v_lshrrev_b32_e32 v8, 16, v8
	v_and_or_b32 v8, v9, s82, v8
	global_store_dword v2, v8, s[12:13]
	s_add_u32 s12, s12, 0x2000
	s_addc_u32 s13, s13, 0
	v_lshlrev_b32_e32 v9, 16, v82
	v_and_b32_e32 v5, 0xffff0000, v82
	v_fma_f32 v6, v16, v6, v9
	v_fma_f32 v7, v16, v7, v5
	s_waitcnt vmcnt(59)
	v_bfe_u32 v8, v6, 16, 1
	v_bfe_u32 v9, v7, 16, 1
	v_add3_u32 v8, v6, v8, s79
	v_add3_u32 v9, v7, v9, s79
	v_lshrrev_b32_e32 v8, 16, v8
	v_and_or_b32 v8, v9, s82, v8
	global_store_dword v2, v8, s[12:13]
	s_add_u32 s12, s12, 0x2000
	s_addc_u32 s13, s13, 0
	v_lshlrev_b32_e32 v9, 16, v83
	v_and_b32_e32 v5, 0xffff0000, v83
	v_fma_f32 v6, v17, v6, v9
	v_fma_f32 v7, v17, v7, v5
	s_waitcnt vmcnt(58)
	v_bfe_u32 v8, v6, 16, 1
	v_bfe_u32 v9, v7, 16, 1
	v_add3_u32 v8, v6, v8, s79
	v_add3_u32 v9, v7, v9, s79
	v_lshrrev_b32_e32 v8, 16, v8
	v_and_or_b32 v8, v9, s82, v8
	global_store_dword v2, v8, s[12:13]
	s_add_u32 s12, s12, 0x2000
	s_addc_u32 s13, s13, 0
	v_lshlrev_b32_e32 v9, 16, v84
	v_and_b32_e32 v5, 0xffff0000, v84
	v_fma_f32 v6, v18, v6, v9
	v_fma_f32 v7, v18, v7, v5
	s_waitcnt vmcnt(57)
	v_bfe_u32 v8, v6, 16, 1
	v_bfe_u32 v9, v7, 16, 1
	v_add3_u32 v8, v6, v8, s79
	v_add3_u32 v9, v7, v9, s79
	v_lshrrev_b32_e32 v8, 16, v8
	v_and_or_b32 v8, v9, s82, v8
	global_store_dword v2, v8, s[12:13]
	s_add_u32 s12, s12, 0x2000
	s_addc_u32 s13, s13, 0
	v_lshlrev_b32_e32 v9, 16, v85
	v_and_b32_e32 v5, 0xffff0000, v85
	v_fma_f32 v6, v19, v6, v9
	v_fma_f32 v7, v19, v7, v5
	s_waitcnt vmcnt(56)
	v_bfe_u32 v8, v6, 16, 1
	v_bfe_u32 v9, v7, 16, 1
	v_add3_u32 v8, v6, v8, s79
	v_add3_u32 v9, v7, v9, s79
	v_lshrrev_b32_e32 v8, 16, v8
	v_and_or_b32 v8, v9, s82, v8
	global_store_dword v2, v8, s[12:13]
	s_add_u32 s12, s12, 0x2000
	s_addc_u32 s13, s13, 0
	v_lshlrev_b32_e32 v9, 16, v86
	v_and_b32_e32 v5, 0xffff0000, v86
	v_fma_f32 v6, v20, v6, v9
	v_fma_f32 v7, v20, v7, v5
	s_waitcnt vmcnt(55)
	v_bfe_u32 v8, v6, 16, 1
	v_bfe_u32 v9, v7, 16, 1
	v_add3_u32 v8, v6, v8, s79
	v_add3_u32 v9, v7, v9, s79
	v_lshrrev_b32_e32 v8, 16, v8
	v_and_or_b32 v8, v9, s82, v8
	global_store_dword v2, v8, s[12:13]
	s_add_u32 s12, s12, 0x2000
	s_addc_u32 s13, s13, 0
	v_lshlrev_b32_e32 v9, 16, v87
	v_and_b32_e32 v5, 0xffff0000, v87
	v_fma_f32 v6, v21, v6, v9
	v_fma_f32 v7, v21, v7, v5
	s_waitcnt vmcnt(54)
	v_bfe_u32 v8, v6, 16, 1
	v_bfe_u32 v9, v7, 16, 1
	v_add3_u32 v8, v6, v8, s79
	v_add3_u32 v9, v7, v9, s79
	v_lshrrev_b32_e32 v8, 16, v8
	v_and_or_b32 v8, v9, s82, v8
	global_store_dword v2, v8, s[12:13]
	s_add_u32 s12, s12, 0x2000
	s_addc_u32 s13, s13, 0
	v_lshlrev_b32_e32 v9, 16, v88
	v_and_b32_e32 v5, 0xffff0000, v88
	v_fma_f32 v6, v22, v6, v9
	v_fma_f32 v7, v22, v7, v5
	s_waitcnt vmcnt(53)
	v_bfe_u32 v8, v6, 16, 1
	v_bfe_u32 v9, v7, 16, 1
	v_add3_u32 v8, v6, v8, s79
	v_add3_u32 v9, v7, v9, s79
	v_lshrrev_b32_e32 v8, 16, v8
	v_and_or_b32 v8, v9, s82, v8
	global_store_dword v2, v8, s[12:13]
	s_add_u32 s12, s12, 0x2000
	s_addc_u32 s13, s13, 0
	v_lshlrev_b32_e32 v9, 16, v89
	v_and_b32_e32 v5, 0xffff0000, v89
	v_fma_f32 v6, v23, v6, v9
	v_fma_f32 v7, v23, v7, v5
	s_waitcnt vmcnt(52)
	v_bfe_u32 v8, v6, 16, 1
	v_bfe_u32 v9, v7, 16, 1
	v_add3_u32 v8, v6, v8, s79
	v_add3_u32 v9, v7, v9, s79
	v_lshrrev_b32_e32 v8, 16, v8
	v_and_or_b32 v8, v9, s82, v8
	global_store_dword v2, v8, s[12:13]
	s_add_u32 s12, s12, 0x2000
	s_addc_u32 s13, s13, 0
	v_lshlrev_b32_e32 v9, 16, v90
	v_and_b32_e32 v5, 0xffff0000, v90
	v_fma_f32 v6, v24, v6, v9
	v_fma_f32 v7, v24, v7, v5
	s_waitcnt vmcnt(51)
	v_bfe_u32 v8, v6, 16, 1
	v_bfe_u32 v9, v7, 16, 1
	v_add3_u32 v8, v6, v8, s79
	v_add3_u32 v9, v7, v9, s79
	v_lshrrev_b32_e32 v8, 16, v8
	v_and_or_b32 v8, v9, s82, v8
	global_store_dword v2, v8, s[12:13]
	s_add_u32 s12, s12, 0x2000
	s_addc_u32 s13, s13, 0
	v_lshlrev_b32_e32 v9, 16, v91
	v_and_b32_e32 v5, 0xffff0000, v91
	v_fma_f32 v6, v25, v6, v9
	v_fma_f32 v7, v25, v7, v5
	s_waitcnt vmcnt(50)
; DI unsigned pk2(float lo, float hi) { return f2bf(lo) | (f2bf(hi) << 16); }
; DI void hgrn_scan_phase(const Args& A, int wave_s) {
;     ...
;             for (int j = 0; j < 12; ++j) { SL[(size_t)(n + j) * 2048] = pk2(s0, s1);
;                 s0 = d[j] * s0 + __builtin_bit_cast(float, sl[j] << 16); s1 = d[j] * s1 + __builtin_bit_cast(float, sl[j] & 0xffff0000u); }
	v_bfe_u32 v8, v6, 16, 1
	v_bfe_u32 v9, v7, 16, 1
	v_add3_u32 v8, v6, v8, s79
	v_add3_u32 v9, v7, v9, s79
	v_lshrrev_b32_e32 v8, 16, v8
	v_and_or_b32 v8, v9, s82, v8
	global_store_dword v2, v8, s[12:13]
	s_add_u32 s12, s12, 0x2000
	s_addc_u32 s13, s13, 0
	v_lshlrev_b32_e32 v9, 16, v92
	v_and_b32_e32 v5, 0xffff0000, v92
	v_fma_f32 v6, v26, v6, v9
	v_fma_f32 v7, v26, v7, v5
	s_waitcnt vmcnt(49)
	v_bfe_u32 v8, v6, 16, 1
	v_bfe_u32 v9, v7, 16, 1
	v_add3_u32 v8, v6, v8, s79
	v_add3_u32 v9, v7, v9, s79
	v_lshrrev_b32_e32 v8, 16, v8
	v_and_or_b32 v8, v9, s82, v8
	global_store_dword v2, v8, s[12:13]
	s_add_u32 s12, s12, 0x2000
	s_addc_u32 s13, s13, 0
	v_lshlrev_b32_e32 v9, 16, v93
	v_and_b32_e32 v5, 0xffff0000, v93
	v_fma_f32 v6, v27, v6, v9
	v_fma_f32 v7, v27, v7, v5
	s_waitcnt vmcnt(48)
	v_bfe_u32 v8, v6, 16, 1
	v_bfe_u32 v9, v7, 16, 1
	v_add3_u32 v8, v6, v8, s79
	v_add3_u32 v9, v7, v9, s79
	v_lshrrev_b32_e32 v8, 16, v8
	v_and_or_b32 v8, v9, s82, v8
	global_store_dword v2, v8, s[12:13]
	s_add_u32 s12, s12, 0x2000
	s_addc_u32 s13, s13, 0
	v_lshlrev_b32_e32 v9, 16, v94
	v_and_b32_e32 v5, 0xffff0000, v94
	v_fma_f32 v6, v28, v6, v9
	v_fma_f32 v7, v28, v7, v5
	s_waitcnt vmcnt(47)
	v_bfe_u32 v8, v6, 16, 1
	v_bfe_u32 v9, v7, 16, 1
	v_add3_u32 v8, v6, v8, s79
	v_add3_u32 v9, v7, v9, s79
	v_lshrrev_b32_e32 v8, 16, v8
	v_and_or_b32 v8, v9, s82, v8
	global_store_dword v2, v8, s[12:13]
	s_add_u32 s12, s12, 0x2000
	s_addc_u32 s13, s13, 0
	v_lshlrev_b32_e32 v9, 16, v95
	v_and_b32_e32 v5, 0xffff0000, v95
	v_fma_f32 v6, v29, v6, v9
	v_fma_f32 v7, v29, v7, v5
	s_waitcnt vmcnt(46)
	v_bfe_u32 v8, v6, 16, 1
	v_bfe_u32 v9, v7, 16, 1
	v_add3_u32 v8, v6, v8, s79
	v_add3_u32 v9, v7, v9, s79
	v_lshrrev_b32_e32 v8, 16, v8
	v_and_or_b32 v8, v9, s82, v8
	global_store_dword v2, v8, s[12:13]
	s_add_u32 s12, s12, 0x2000
	s_addc_u32 s13, s13, 0
	v_lshlrev_b32_e32 v9, 16, v96
	v_and_b32_e32 v5, 0xffff0000, v96
	v_fma_f32 v6, v30, v6, v9
	v_fma_f32 v7, v30, v7, v5
	s_waitcnt vmcnt(45)
	v_bfe_u32 v8, v6, 16, 1
	v_bfe_u32 v9, v7, 16, 1
	v_add3_u32 v8, v6, v8, s79
	v_add3_u32 v9, v7, v9, s79
	v_lshrrev_b32_e32 v8, 16, v8
	v_and_or_b32 v8, v9, s82, v8
	global_store_dword v2, v8, s[12:13]
	s_add_u32 s12, s12, 0x2000
	s_addc_u32 s13, s13, 0
	v_lshlrev_b32_e32 v9, 16, v97
	v_and_b32_e32 v5, 0xffff0000, v97
	v_fma_f32 v6, v31, v6, v9
	v_fma_f32 v7, v31, v7, v5
	s_waitcnt vmcnt(44)
	v_bfe_u32 v8, v6, 16, 1
	v_bfe_u32 v9, v7, 16, 1
	v_add3_u32 v8, v6, v8, s79
	v_add3_u32 v9, v7, v9, s79
	v_lshrrev_b32_e32 v8, 16, v8
	v_and_or_b32 v8, v9, s82, v8
	global_store_dword v2, v8, s[12:13]
	s_add_u32 s12, s12, 0x2000
	s_addc_u32 s13, s13, 0
	v_lshlrev_b32_e32 v9, 16, v98
	v_and_b32_e32 v5, 0xffff0000, v98
	v_fma_f32 v6, v32, v6, v9
	v_fma_f32 v7, v32, v7, v5
	s_waitcnt vmcnt(43)
	v_bfe_u32 v8, v6, 16, 1
	v_bfe_u32 v9, v7, 16, 1
	v_add3_u32 v8, v6, v8, s79
	v_add3_u32 v9, v7, v9, s79
	v_lshrrev_b32_e32 v8, 16, v8
	v_and_or_b32 v8, v9, s82, v8
	global_store_dword v2, v8, s[12:13]
	s_add_u32 s12, s12, 0x2000
	s_addc_u32 s13, s13, 0
	v_lshlrev_b32_e32 v9, 16, v99
	v_and_b32_e32 v5, 0xffff0000, v99
	v_fma_f32 v6, v33, v6, v9
	v_fma_f32 v7, v33, v7, v5
	s_waitcnt vmcnt(42)
	v_bfe_u32 v8, v6, 16, 1
	v_bfe_u32 v9, v7, 16, 1
	v_add3_u32 v8, v6, v8, s79
	v_add3_u32 v9, v7, v9, s79
	v_lshrrev_b32_e32 v8, 16, v8
	v_and_or_b32 v8, v9, s82, v8
	global_store_dword v2, v8, s[12:13]
	s_add_u32 s12, s12, 0x2000
	s_addc_u32 s13, s13, 0
	v_lshlrev_b32_e32 v9, 16, v100
	v_and_b32_e32 v5, 0xffff0000, v100
	v_fma_f32 v6, v34, v6, v9
	v_fma_f32 v7, v34, v7, v5
	s_waitcnt vmcnt(41)
	v_bfe_u32 v8, v6, 16, 1
	v_bfe_u32 v9, v7, 16, 1
	v_add3_u32 v8, v6, v8, s79
	v_add3_u32 v9, v7, v9, s79
	v_lshrrev_b32_e32 v8, 16, v8
	v_and_or_b32 v8, v9, s82, v8
	global_store_dword v2, v8, s[12:13]
	s_add_u32 s12, s12, 0x2000
	s_addc_u32 s13, s13, 0
	v_lshlrev_b32_e32 v9, 16, v101
	v_and_b32_e32 v5, 0xffff0000, v101
	v_fma_f32 v6, v35, v6, v9
	v_fma_f32 v7, v35, v7, v5
	s_waitcnt vmcnt(40)
; DI unsigned pk2(float lo, float hi) { return f2bf(lo) | (f2bf(hi) << 16); }
; DI void hgrn_scan_phase(const Args& A, int wave_s) {
;     ...
;         for (int n = 0; n < 132; n += 12) {
;             unsigned sl[12]; float d[12];
; #pragma unroll
;             for (int j = 0; j < 12; ++j) { sl[j] = SL[(size_t)(n + j) * 2048]; d[j] = D[(n + j) * 64]; }
; #pragma unroll
;             for (int j = 0; j < 12; ++j) { SL[(size_t)(n + j) * 2048] = pk2(s0, s1);
;                 s0 = d[j] * s0 + __builtin_bit_cast(float, sl[j] << 16); s1 = d[j] * s1 + __builtin_bit_cast(float, sl[j] & 0xffff0000u); }
	v_bfe_u32 v8, v6, 16, 1
	v_bfe_u32 v9, v7, 16, 1
	v_add3_u32 v8, v6, v8, s79
	v_add3_u32 v9, v7, v9, s79
	v_lshrrev_b32_e32 v8, 16, v8
	v_and_or_b32 v8, v9, s82, v8
	global_store_dword v2, v8, s[12:13]
	s_add_u32 s12, s12, 0x2000
	s_addc_u32 s13, s13, 0
	v_lshlrev_b32_e32 v9, 16, v102
	v_and_b32_e32 v5, 0xffff0000, v102
	v_fma_f32 v6, v36, v6, v9
	v_fma_f32 v7, v36, v7, v5
	s_waitcnt vmcnt(39)
	v_bfe_u32 v8, v6, 16, 1
	v_bfe_u32 v9, v7, 16, 1
	v_add3_u32 v8, v6, v8, s79
	v_add3_u32 v9, v7, v9, s79
	v_lshrrev_b32_e32 v8, 16, v8
	v_and_or_b32 v8, v9, s82, v8
	global_store_dword v2, v8, s[12:13]
	s_add_u32 s12, s12, 0x2000
	s_addc_u32 s13, s13, 0
	v_lshlrev_b32_e32 v9, 16, v103
	v_and_b32_e32 v5, 0xffff0000, v103
	v_fma_f32 v6, v37, v6, v9
	v_fma_f32 v7, v37, v7, v5
	s_waitcnt vmcnt(38)
	v_bfe_u32 v8, v6, 16, 1
	v_bfe_u32 v9, v7, 16, 1
	v_add3_u32 v8, v6, v8, s79
	v_add3_u32 v9, v7, v9, s79
	v_lshrrev_b32_e32 v8, 16, v8
	v_and_or_b32 v8, v9, s82, v8
	global_store_dword v2, v8, s[12:13]
	s_add_u32 s12, s12, 0x2000
	s_addc_u32 s13, s13, 0
	v_lshlrev_b32_e32 v9, 16, v104
	v_and_b32_e32 v5, 0xffff0000, v104
	v_fma_f32 v6, v38, v6, v9
	v_fma_f32 v7, v38, v7, v5
	s_waitcnt vmcnt(37)
	v_bfe_u32 v8, v6, 16, 1
	v_bfe_u32 v9, v7, 16, 1
	v_add3_u32 v8, v6, v8, s79
	v_add3_u32 v9, v7, v9, s79
	v_lshrrev_b32_e32 v8, 16, v8
	v_and_or_b32 v8, v9, s82, v8
	global_store_dword v2, v8, s[12:13]
	s_add_u32 s12, s12, 0x2000
	s_addc_u32 s13, s13, 0
	v_lshlrev_b32_e32 v9, 16, v105
	v_and_b32_e32 v5, 0xffff0000, v105
	v_fma_f32 v6, v39, v6, v9
	v_fma_f32 v7, v39, v7, v5
	s_waitcnt vmcnt(36)
	v_bfe_u32 v8, v6, 16, 1
	v_bfe_u32 v9, v7, 16, 1
	v_add3_u32 v8, v6, v8, s79
	v_add3_u32 v9, v7, v9, s79
	v_lshrrev_b32_e32 v8, 16, v8
	v_and_or_b32 v8, v9, s82, v8
	global_store_dword v2, v8, s[12:13]
	s_add_u32 s12, s12, 0x2000
	s_addc_u32 s13, s13, 0
	v_lshlrev_b32_e32 v9, 16, v106
	v_and_b32_e32 v5, 0xffff0000, v106
	v_fma_f32 v6, v40, v6, v9
	v_fma_f32 v7, v40, v7, v5
	s_waitcnt vmcnt(35)
	v_bfe_u32 v8, v6, 16, 1
	v_bfe_u32 v9, v7, 16, 1
	v_add3_u32 v8, v6, v8, s79
	v_add3_u32 v9, v7, v9, s79
	v_lshrrev_b32_e32 v8, 16, v8
	v_and_or_b32 v8, v9, s82, v8
	global_store_dword v2, v8, s[12:13]
	s_add_u32 s12, s12, 0x2000
	s_addc_u32 s13, s13, 0
	v_lshlrev_b32_e32 v9, 16, v107
	v_and_b32_e32 v5, 0xffff0000, v107
	v_fma_f32 v6, v41, v6, v9
	v_fma_f32 v7, v41, v7, v5
	s_waitcnt vmcnt(34)
	v_bfe_u32 v8, v6, 16, 1
	v_bfe_u32 v9, v7, 16, 1
	v_add3_u32 v8, v6, v8, s79
	v_add3_u32 v9, v7, v9, s79
	v_lshrrev_b32_e32 v8, 16, v8
	v_and_or_b32 v8, v9, s82, v8
	global_store_dword v2, v8, s[12:13]
	s_add_u32 s12, s12, 0x2000
	s_addc_u32 s13, s13, 0
	v_lshlrev_b32_e32 v9, 16, v108
	v_and_b32_e32 v5, 0xffff0000, v108
	v_fma_f32 v6, v42, v6, v9
	v_fma_f32 v7, v42, v7, v5
	s_waitcnt vmcnt(33)
	v_bfe_u32 v8, v6, 16, 1
	v_bfe_u32 v9, v7, 16, 1
	v_add3_u32 v8, v6, v8, s79
	v_add3_u32 v9, v7, v9, s79
	v_lshrrev_b32_e32 v8, 16, v8
	v_and_or_b32 v8, v9, s82, v8
	global_store_dword v2, v8, s[12:13]
	s_add_u32 s12, s12, 0x2000
	s_addc_u32 s13, s13, 0
	v_lshlrev_b32_e32 v9, 16, v109
	v_and_b32_e32 v5, 0xffff0000, v109
	v_fma_f32 v6, v43, v6, v9
	v_fma_f32 v7, v43, v7, v5
	s_waitcnt vmcnt(32)
	v_bfe_u32 v8, v6, 16, 1
	v_bfe_u32 v9, v7, 16, 1
	v_add3_u32 v8, v6, v8, s79
	v_add3_u32 v9, v7, v9, s79
	v_lshrrev_b32_e32 v8, 16, v8
	v_and_or_b32 v8, v9, s82, v8
	global_store_dword v2, v8, s[12:13]
	s_add_u32 s12, s12, 0x2000
	s_addc_u32 s13, s13, 0
	v_lshlrev_b32_e32 v9, 16, v110
	v_and_b32_e32 v5, 0xffff0000, v110
	v_fma_f32 v6, v44, v6, v9
	v_fma_f32 v7, v44, v7, v5
	s_sub_u32 s16, s16, 1
	s_cmp_lg_u32 s16, 0
	s_cbranch_scc1 .Lscan_batch
	v_readlane_b32 s8, v253, 61
	s_mov_b32 s2, 0xffff
	s_nop 0
	v_add_u32_e32 v10, s8, v10
	v_cmp_lt_i32_e32 vcc, s2, v10
	s_or_b64 s[6:7], vcc, s[6:7]
	v_add_u16_e32 v11, s8, v11
	s_andn2_b64 exec, exec, s[6:7]
	s_cbranch_execnz .LBB0_301

; DI void norm_phase(const Args& A, int wave_s, int l, int which, int rows) {
;     const Ctx C = make_ctx(A, wave_s);
;     const float* gn = (which == 1 ? C.n1g : C.n2g) + l * 1024;
;     const bool from_in = (l == 0 && which == 1);
;     f32x4 g[4];
; #pragma unroll
;     for (int j = 0; j < 4; ++j) g[j] = *(const f32x4*)(gn + 4 * (C.lane + 64 * j));
;     for (int m0 = C.gw * 2; m0 < rows; m0 += C.NGW * 2) {
;         f32x4 xv[2][4];
;         const float* modp[2];
; #pragma unroll
;         for (int rr = 0; rr < 2; ++rr) {
;             const int m = m0 + rr; const float* xr; int v;
;             if (m < NLAT) { xr = (from_in ? C.x : C.out) + (size_t)m * 1024; v = m >> 13; }
;             else { xr = (from_in ? C.ctx : C.XC) + (size_t)(m - NLAT) * 1024; v = 4; }
;             modp[rr] = C.SM + SM_MOD + (l * 5 + v) * 6144 + (which == 1 ? 0 : 3072);
; #pragma unroll
;             for (int j = 0; j < 4; ++j) xv[rr][j] = ((const f32x4*)xr)[C.lane + 64 * j];
.LBB0_528:
	s_or_b64 exec, exec, s[4:5]
	v_readlane_b32 s4, v254, 41
	s_cmp_ge_i32 s4, s42
	s_waitcnt lgkmcnt(0)
	s_barrier
	v_readlane_b32 s5, v254, 42
	v_mbcnt_lo_u32_b32 v48, -1, 0
	v_mbcnt_hi_u32_b32 v48, -1, v48
	v_mbcnt_lo_u32_b32 v0, -1, 0
	v_mbcnt_hi_u32_b32 v0, -1, v0
	v_readlane_b32 s6, v255, 32
	v_lshlrev_b32_e32 v1, 4, v0
	v_lshlrev_b32_e32 v2, 3, v0
	v_xor_b32_e32 v4, 1, v0
	v_xor_b32_e32 v5, 2, v0
	v_xor_b32_e32 v6, 4, v0
	v_xor_b32_e32 v7, 8, v0
	v_xor_b32_e32 v8, 16, v0
	v_xor_b32_e32 v9, 32, v0
	v_lshlrev_b32_e32 v4, 2, v4
	v_lshlrev_b32_e32 v5, 2, v5
	v_lshlrev_b32_e32 v6, 2, v6
	v_lshlrev_b32_e32 v7, 2, v7
	v_lshlrev_b32_e32 v8, 2, v8
	v_lshlrev_b32_e32 v9, 2, v9
	v_mov_b32_e32 v60, 0x358637bd
	s_lshr_b32 s6, s6, 10
	s_lshr_b32 s4, s94, 6
	s_lshl_b32 s5, s65, 3
	s_add_u32 s4, s4, s5
	s_lshr_b32 s5, s4, 9
	s_mul_i32 s7, s6, 5
	s_add_u32 s5, s7, s5
	s_mul_i32 s5, s5, 0x6000
	s_add_u32 s24, s88, 0x103000
	s_addc_u32 s25, s89, 0
	s_add_u32 s24, s24, s5
	s_addc_u32 s25, s25, 0
	s_add_u32 s26, s24, 0x1000
	s_addc_u32 s27, s25, 0
	v_readlane_b32 s28, v252, 48
	v_readlane_b32 s29, v252, 49
	s_lshl_b32 s7, s6, 12
	s_nop 1
	s_add_u32 s28, s28, s7
	s_addc_u32 s29, s29, 0
	v_readlane_b32 s8, v252, 31
	v_readlane_b32 s9, v252, 32
	s_add_u32 s30, s88, 0x3400000
	s_addc_u32 s31, s89, 0
	s_nop 1
	s_cmp_gt_u32 s42, 0x8000
	s_cselect_b32 s2, 1, 0
	s_cmp_lt_u32 s4, 0x400
	s_cselect_b32 s2, s2, 0
	s_and_b32 s7, s4, 0x3ff
	s_lshl_b32 s5, s7, 12
	s_add_u32 s30, s30, s5
	s_addc_u32 s31, s31, 0
	s_lshl_b32 s5, s4, 16
	s_add_u32 s8, s8, s5
	s_addc_u32 s9, s9, 0
	s_add_u32 s10, s88, 0x3800000
	s_addc_u32 s11, s89, 0
	s_lshl_b32 s5, s4, 15
	s_add_u32 s10, s10, s5
	s_addc_u32 s11, s11, 0
	s_mov_b32 s32, 0x3a800000
	global_load_dwordx4 v[24:27], v1, s[28:29]
	global_load_dwordx4 v[28:31], v1, s[28:29] offset:1024
	global_load_dwordx4 v[32:35], v1, s[28:29] offset:2048
	global_load_dwordx4 v[36:39], v1, s[28:29] offset:3072
	global_load_dwordx4 v[40:43], v1, s[26:27]
	global_load_dwordx4 v[64:67], v1, s[26:27] offset:1024
	global_load_dwordx4 v[68:71], v1, s[26:27] offset:2048
	global_load_dwordx4 v[72:75], v1, s[26:27] offset:3072
	global_load_dwordx4 v[80:83], v1, s[24:25]
	global_load_dwordx4 v[84:87], v1, s[24:25] offset:1024
	global_load_dwordx4 v[88:91], v1, s[24:25] offset:2048
	global_load_dwordx4 v[92:95], v1, s[24:25] offset:3072
	global_load_dwordx4 v[96:99], v1, s[8:9]
	global_load_dwordx4 v[100:103], v1, s[8:9] offset:1024
	global_load_dwordx4 v[104:107], v1, s[8:9] offset:2048
	global_load_dwordx4 v[108:111], v1, s[8:9] offset:3072
	s_add_u32 s8, s8, 0x1000
	s_addc_u32 s9, s9, 0
	global_load_dwordx4 v[112:115], v1, s[8:9]
	global_load_dwordx4 v[116:119], v1, s[8:9] offset:1024
	global_load_dwordx4 v[120:123], v1, s[8:9] offset:2048
	global_load_dwordx4 v[124:127], v1, s[8:9] offset:3072
	s_add_u32 s8, s8, 0x1000
	s_addc_u32 s9, s9, 0
	global_load_dwordx4 v[128:131], v1, s[8:9]
	global_load_dwordx4 v[132:135], v1, s[8:9] offset:1024
	global_load_dwordx4 v[136:139], v1, s[8:9] offset:2048
	global_load_dwordx4 v[140:143], v1, s[8:9] offset:3072
	s_add_u32 s8, s8, 0x1000
	s_addc_u32 s9, s9, 0
	global_load_dwordx4 v[144:147], v1, s[8:9]
	global_load_dwordx4 v[148:151], v1, s[8:9] offset:1024
	global_load_dwordx4 v[152:155], v1, s[8:9] offset:2048
	global_load_dwordx4 v[156:159], v1, s[8:9] offset:3072
	s_add_u32 s8, s8, 0x1000
	s_addc_u32 s9, s9, 0
	global_load_dwordx4 v[164:167], v1, s[8:9]
	global_load_dwordx4 v[168:171], v1, s[8:9] offset:1024
	global_load_dwordx4 v[172:175], v1, s[8:9] offset:2048
	global_load_dwordx4 v[176:179], v1, s[8:9] offset:3072
	s_add_u32 s8, s8, 0x1000
	s_addc_u32 s9, s9, 0
	global_load_dwordx4 v[180:183], v1, s[8:9]
	global_load_dwordx4 v[184:187], v1, s[8:9] offset:1024
	global_load_dwordx4 v[188:191], v1, s[8:9] offset:2048
	global_load_dwordx4 v[192:195], v1, s[8:9] offset:3072
	s_add_u32 s8, s8, 0x1000
	s_addc_u32 s9, s9, 0
	global_load_dwordx4 v[196:199], v1, s[8:9]
	global_load_dwordx4 v[200:203], v1, s[8:9] offset:1024
	global_load_dwordx4 v[204:207], v1, s[8:9] offset:2048
	global_load_dwordx4 v[208:211], v1, s[8:9] offset:3072
	s_add_u32 s8, s8, 0x1000
	s_addc_u32 s9, s9, 0
	global_load_dwordx4 v[212:215], v1, s[8:9]
	global_load_dwordx4 v[216:219], v1, s[8:9] offset:1024
	global_load_dwordx4 v[220:223], v1, s[8:9] offset:2048
	global_load_dwordx4 v[224:227], v1, s[8:9] offset:3072
	s_add_u32 s8, s8, 0x1000
	s_addc_u32 s9, s9, 0
	s_waitcnt vmcnt(32)
	v_pk_add_f32 v[40:41], v[40:41], 1.0 op_sel_hi:[1,0]
	v_pk_add_f32 v[42:43], v[42:43], 1.0 op_sel_hi:[1,0]
	v_pk_add_f32 v[64:65], v[64:65], 1.0 op_sel_hi:[1,0]
	v_pk_add_f32 v[66:67], v[66:67], 1.0 op_sel_hi:[1,0]
	v_pk_add_f32 v[68:69], v[68:69], 1.0 op_sel_hi:[1,0]
	v_pk_add_f32 v[70:71], v[70:71], 1.0 op_sel_hi:[1,0]
	v_pk_add_f32 v[72:73], v[72:73], 1.0 op_sel_hi:[1,0]
	v_pk_add_f32 v[74:75], v[74:75], 1.0 op_sel_hi:[1,0]
	s_waitcnt vmcnt(16)
; DI unsigned pk2(float lo, float hi) { return f2bf(lo) | (f2bf(hi) << 16); }
; DI void norm_phase(const Args& A, int wave_s, int l, int which, int rows) {
;     ...
;             float ss = 0.f;
; #pragma unroll
;             for (int j = 0; j < 4; ++j) ss += (xv[rr][j].x * xv[rr][j].x + xv[rr][j].y * xv[rr][j].y) + (xv[rr][j].z * xv[rr][j].z + xv[rr][j].w * xv[rr][j].w);
;             ss = wave_sum(C.lane, ss);
;             const float rs = rsqrtf(ss * (1.f / 1024.f) + EPS);
; #pragma unroll
;             for (int j = 0; j < 4; ++j) { const int col = 4 * (C.lane + 64 * j);
;                 const f32x4 y = xv[rr][j] * rs * g[j] * (sc[j] + 1.f) + sh[j];
;                 v2u o; o.x = pk2(y.x, y.y); o.y = pk2(y.z, y.w);
;                 *(v2u*)(C.H + (size_t)m * 1024 + col) = o; }
	v_mul_f32_e32 v10, v96, v96
	v_fmac_f32_e32 v10, v97, v97
	v_fmac_f32_e32 v10, v98, v98
	v_fmac_f32_e32 v10, v99, v99
	v_fmac_f32_e32 v10, v100, v100
	v_fmac_f32_e32 v10, v101, v101
	v_fmac_f32_e32 v10, v102, v102
	v_fmac_f32_e32 v10, v103, v103
	v_fmac_f32_e32 v10, v104, v104
	v_fmac_f32_e32 v10, v105, v105
	v_fmac_f32_e32 v10, v106, v106
	v_fmac_f32_e32 v10, v107, v107
	v_fmac_f32_e32 v10, v108, v108
	v_fmac_f32_e32 v10, v109, v109
	v_fmac_f32_e32 v10, v110, v110
	v_fmac_f32_e32 v10, v111, v111
	v_mul_f32_e32 v11, v112, v112
	v_fmac_f32_e32 v11, v113, v113
	v_fmac_f32_e32 v11, v114, v114
	v_fmac_f32_e32 v11, v115, v115
	v_fmac_f32_e32 v11, v116, v116
	v_fmac_f32_e32 v11, v117, v117
	v_fmac_f32_e32 v11, v118, v118
	v_fmac_f32_e32 v11, v119, v119
	v_fmac_f32_e32 v11, v120, v120
	v_fmac_f32_e32 v11, v121, v121
	v_fmac_f32_e32 v11, v122, v122
	v_fmac_f32_e32 v11, v123, v123
	v_fmac_f32_e32 v11, v124, v124
	v_fmac_f32_e32 v11, v125, v125
	v_fmac_f32_e32 v11, v126, v126
	v_fmac_f32_e32 v11, v127, v127
	v_mul_f32_e32 v12, v128, v128
	v_fmac_f32_e32 v12, v129, v129
	v_fmac_f32_e32 v12, v130, v130
	v_fmac_f32_e32 v12, v131, v131
	v_fmac_f32_e32 v12, v132, v132
	v_fmac_f32_e32 v12, v133, v133
	v_fmac_f32_e32 v12, v134, v134
	v_fmac_f32_e32 v12, v135, v135
	v_fmac_f32_e32 v12, v136, v136
	v_fmac_f32_e32 v12, v137, v137
	v_fmac_f32_e32 v12, v138, v138
	v_fmac_f32_e32 v12, v139, v139
	v_fmac_f32_e32 v12, v140, v140
	v_fmac_f32_e32 v12, v141, v141
	v_fmac_f32_e32 v12, v142, v142
	v_fmac_f32_e32 v12, v143, v143
	v_mul_f32_e32 v13, v144, v144
	v_fmac_f32_e32 v13, v145, v145
	v_fmac_f32_e32 v13, v146, v146
	v_fmac_f32_e32 v13, v147, v147
	v_fmac_f32_e32 v13, v148, v148
	v_fmac_f32_e32 v13, v149, v149
	v_fmac_f32_e32 v13, v150, v150
	v_fmac_f32_e32 v13, v151, v151
	v_fmac_f32_e32 v13, v152, v152
	v_fmac_f32_e32 v13, v153, v153
	v_fmac_f32_e32 v13, v154, v154
	v_fmac_f32_e32 v13, v155, v155
	v_fmac_f32_e32 v13, v156, v156
	v_fmac_f32_e32 v13, v157, v157
	v_fmac_f32_e32 v13, v158, v158
	v_fmac_f32_e32 v13, v159, v159
	ds_bpermute_b32 v14, v4, v10
	ds_bpermute_b32 v15, v4, v11
	ds_bpermute_b32 v16, v4, v12
	ds_bpermute_b32 v17, v4, v13
	s_waitcnt lgkmcnt(0)
	v_add_f32_e32 v10, v10, v14
	v_add_f32_e32 v11, v11, v15
	v_add_f32_e32 v12, v12, v16
	v_add_f32_e32 v13, v13, v17
	ds_bpermute_b32 v14, v5, v10
	ds_bpermute_b32 v15, v5, v11
	ds_bpermute_b32 v16, v5, v12
	ds_bpermute_b32 v17, v5, v13
	s_waitcnt lgkmcnt(0)
	v_add_f32_e32 v10, v10, v14
	v_add_f32_e32 v11, v11, v15
	v_add_f32_e32 v12, v12, v16
	v_add_f32_e32 v13, v13, v17
	ds_bpermute_b32 v14, v6, v10
	ds_bpermute_b32 v15, v6, v11
	ds_bpermute_b32 v16, v6, v12
	ds_bpermute_b32 v17, v6, v13
	s_waitcnt lgkmcnt(0)
	v_add_f32_e32 v10, v10, v14
	v_add_f32_e32 v11, v11, v15
	v_add_f32_e32 v12, v12, v16
	v_add_f32_e32 v13, v13, v17
	ds_bpermute_b32 v14, v7, v10
	ds_bpermute_b32 v15, v7, v11
	ds_bpermute_b32 v16, v7, v12
	ds_bpermute_b32 v17, v7, v13
	s_waitcnt lgkmcnt(0)
	v_add_f32_e32 v10, v10, v14
	v_add_f32_e32 v11, v11, v15
	v_add_f32_e32 v12, v12, v16
	v_add_f32_e32 v13, v13, v17
	ds_bpermute_b32 v14, v8, v10
	ds_bpermute_b32 v15, v8, v11
	ds_bpermute_b32 v16, v8, v12
	ds_bpermute_b32 v17, v8, v13
	s_waitcnt lgkmcnt(0)
	v_add_f32_e32 v10, v10, v14
	v_add_f32_e32 v11, v11, v15
	v_add_f32_e32 v12, v12, v16
	v_add_f32_e32 v13, v13, v17
	ds_bpermute_b32 v14, v9, v10
	ds_bpermute_b32 v15, v9, v11
	ds_bpermute_b32 v16, v9, v12
	ds_bpermute_b32 v17, v9, v13
	s_waitcnt lgkmcnt(0)
	v_add_f32_e32 v10, v10, v14
	v_add_f32_e32 v11, v11, v15
	v_add_f32_e32 v12, v12, v16
	v_add_f32_e32 v13, v13, v17
	v_fma_f32 v10, v10, s32, v60
	v_fma_f32 v11, v11, s32, v60
	v_fma_f32 v12, v12, s32, v60
	v_fma_f32 v13, v13, s32, v60
	v_rsq_f32_e32 v18, v10
	v_rsq_f32_e32 v20, v11
	v_rsq_f32_e32 v22, v12
	v_rsq_f32_e32 v62, v13
	s_nop 0
	v_pk_mul_f32 v[96:97], v[96:97], v[18:19] op_sel_hi:[1,0]
	v_pk_mul_f32 v[98:99], v[98:99], v[18:19] op_sel_hi:[1,0]
	v_pk_mul_f32 v[100:101], v[100:101], v[18:19] op_sel_hi:[1,0]
	v_pk_mul_f32 v[102:103], v[102:103], v[18:19] op_sel_hi:[1,0]
	v_pk_mul_f32 v[104:105], v[104:105], v[18:19] op_sel_hi:[1,0]
	v_pk_mul_f32 v[106:107], v[106:107], v[18:19] op_sel_hi:[1,0]
	v_pk_mul_f32 v[108:109], v[108:109], v[18:19] op_sel_hi:[1,0]
	v_pk_mul_f32 v[110:111], v[110:111], v[18:19] op_sel_hi:[1,0]
	v_pk_mul_f32 v[96:97], v[24:25], v[96:97]
	v_pk_mul_f32 v[98:99], v[26:27], v[98:99]
	v_pk_mul_f32 v[100:101], v[28:29], v[100:101]
	v_pk_mul_f32 v[102:103], v[30:31], v[102:103]
	v_pk_mul_f32 v[104:105], v[32:33], v[104:105]
	v_pk_mul_f32 v[106:107], v[34:35], v[106:107]
	v_pk_mul_f32 v[108:109], v[36:37], v[108:109]
	v_pk_mul_f32 v[110:111], v[38:39], v[110:111]
	v_pk_fma_f32 v[96:97], v[40:41], v[96:97], v[80:81]
	v_pk_fma_f32 v[98:99], v[42:43], v[98:99], v[82:83]
	v_pk_fma_f32 v[100:101], v[64:65], v[100:101], v[84:85]
	v_pk_fma_f32 v[102:103], v[66:67], v[102:103], v[86:87]
	v_pk_fma_f32 v[104:105], v[68:69], v[104:105], v[88:89]
	v_pk_fma_f32 v[106:107], v[70:71], v[106:107], v[90:91]
	v_pk_fma_f32 v[108:109], v[72:73], v[108:109], v[92:93]
	v_pk_fma_f32 v[110:111], v[74:75], v[110:111], v[94:95]
	v_cvt_pk_bf16_f32 v96, v96, v97
	v_cvt_pk_bf16_f32 v97, v98, v99
	v_cvt_pk_bf16_f32 v100, v100, v101
	v_cvt_pk_bf16_f32 v101, v102, v103
	v_cvt_pk_bf16_f32 v104, v104, v105
	v_cvt_pk_bf16_f32 v105, v106, v107
	v_cvt_pk_bf16_f32 v108, v108, v109
	v_cvt_pk_bf16_f32 v109, v110, v111
	global_store_dwordx2 v2, v[96:97], s[10:11]
	global_store_dwordx2 v2, v[100:101], s[10:11] offset:512
	global_store_dwordx2 v2, v[104:105], s[10:11] offset:1024
	global_store_dwordx2 v2, v[108:109], s[10:11] offset:1536
	s_add_u32 s10, s10, 0x800
; DI unsigned pk2(float lo, float hi) { return f2bf(lo) | (f2bf(hi) << 16); }
; DI void norm_phase(const Args& A, int wave_s, int l, int which, int rows) {
;     ...
;             for (int j = 0; j < 4; ++j) xv[rr][j] = ((const f32x4*)xr)[C.lane + 64 * j];
;     ...
;             for (int j = 0; j < 4; ++j) { const int col = 4 * (C.lane + 64 * j);
;                 const f32x4 y = xv[rr][j] * rs * g[j] * (sc[j] + 1.f) + sh[j];
;                 v2u o; o.x = pk2(y.x, y.y); o.y = pk2(y.z, y.w);
;                 *(v2u*)(C.H + (size_t)m * 1024 + col) = o; }
	s_addc_u32 s11, s11, 0
	v_pk_mul_f32 v[112:113], v[112:113], v[20:21] op_sel_hi:[1,0]
	v_pk_mul_f32 v[114:115], v[114:115], v[20:21] op_sel_hi:[1,0]
	v_pk_mul_f32 v[116:117], v[116:117], v[20:21] op_sel_hi:[1,0]
	v_pk_mul_f32 v[118:119], v[118:119], v[20:21] op_sel_hi:[1,0]
	v_pk_mul_f32 v[120:121], v[120:121], v[20:21] op_sel_hi:[1,0]
	v_pk_mul_f32 v[122:123], v[122:123], v[20:21] op_sel_hi:[1,0]
	v_pk_mul_f32 v[124:125], v[124:125], v[20:21] op_sel_hi:[1,0]
	v_pk_mul_f32 v[126:127], v[126:127], v[20:21] op_sel_hi:[1,0]
	v_pk_mul_f32 v[112:113], v[24:25], v[112:113]
	v_pk_mul_f32 v[114:115], v[26:27], v[114:115]
	v_pk_mul_f32 v[116:117], v[28:29], v[116:117]
	v_pk_mul_f32 v[118:119], v[30:31], v[118:119]
	v_pk_mul_f32 v[120:121], v[32:33], v[120:121]
	v_pk_mul_f32 v[122:123], v[34:35], v[122:123]
	v_pk_mul_f32 v[124:125], v[36:37], v[124:125]
	v_pk_mul_f32 v[126:127], v[38:39], v[126:127]
	v_pk_fma_f32 v[112:113], v[40:41], v[112:113], v[80:81]
	v_pk_fma_f32 v[114:115], v[42:43], v[114:115], v[82:83]
	v_pk_fma_f32 v[116:117], v[64:65], v[116:117], v[84:85]
	v_pk_fma_f32 v[118:119], v[66:67], v[118:119], v[86:87]
	v_pk_fma_f32 v[120:121], v[68:69], v[120:121], v[88:89]
	v_pk_fma_f32 v[122:123], v[70:71], v[122:123], v[90:91]
	v_pk_fma_f32 v[124:125], v[72:73], v[124:125], v[92:93]
	v_pk_fma_f32 v[126:127], v[74:75], v[126:127], v[94:95]
	v_cvt_pk_bf16_f32 v112, v112, v113
	v_cvt_pk_bf16_f32 v113, v114, v115
	v_cvt_pk_bf16_f32 v116, v116, v117
	v_cvt_pk_bf16_f32 v117, v118, v119
	v_cvt_pk_bf16_f32 v120, v120, v121
	v_cvt_pk_bf16_f32 v121, v122, v123
	v_cvt_pk_bf16_f32 v124, v124, v125
	v_cvt_pk_bf16_f32 v125, v126, v127
	global_store_dwordx2 v2, v[112:113], s[10:11]
	global_store_dwordx2 v2, v[116:117], s[10:11] offset:512
	global_store_dwordx2 v2, v[120:121], s[10:11] offset:1024
	global_store_dwordx2 v2, v[124:125], s[10:11] offset:1536
	s_add_u32 s10, s10, 0x800
	s_addc_u32 s11, s11, 0
	v_pk_mul_f32 v[128:129], v[128:129], v[22:23] op_sel_hi:[1,0]
	v_pk_mul_f32 v[130:131], v[130:131], v[22:23] op_sel_hi:[1,0]
	v_pk_mul_f32 v[132:133], v[132:133], v[22:23] op_sel_hi:[1,0]
	v_pk_mul_f32 v[134:135], v[134:135], v[22:23] op_sel_hi:[1,0]
	v_pk_mul_f32 v[136:137], v[136:137], v[22:23] op_sel_hi:[1,0]
	v_pk_mul_f32 v[138:139], v[138:139], v[22:23] op_sel_hi:[1,0]
	v_pk_mul_f32 v[140:141], v[140:141], v[22:23] op_sel_hi:[1,0]
	v_pk_mul_f32 v[142:143], v[142:143], v[22:23] op_sel_hi:[1,0]
	v_pk_mul_f32 v[128:129], v[24:25], v[128:129]
	v_pk_mul_f32 v[130:131], v[26:27], v[130:131]
	v_pk_mul_f32 v[132:133], v[28:29], v[132:133]
	v_pk_mul_f32 v[134:135], v[30:31], v[134:135]
	v_pk_mul_f32 v[136:137], v[32:33], v[136:137]
	v_pk_mul_f32 v[138:139], v[34:35], v[138:139]
	v_pk_mul_f32 v[140:141], v[36:37], v[140:141]
	v_pk_mul_f32 v[142:143], v[38:39], v[142:143]
	v_pk_fma_f32 v[128:129], v[40:41], v[128:129], v[80:81]
	v_pk_fma_f32 v[130:131], v[42:43], v[130:131], v[82:83]
	v_pk_fma_f32 v[132:133], v[64:65], v[132:133], v[84:85]
	v_pk_fma_f32 v[134:135], v[66:67], v[134:135], v[86:87]
	v_pk_fma_f32 v[136:137], v[68:69], v[136:137], v[88:89]
	v_pk_fma_f32 v[138:139], v[70:71], v[138:139], v[90:91]
	v_pk_fma_f32 v[140:141], v[72:73], v[140:141], v[92:93]
	v_pk_fma_f32 v[142:143], v[74:75], v[142:143], v[94:95]
	v_cvt_pk_bf16_f32 v128, v128, v129
	v_cvt_pk_bf16_f32 v129, v130, v131
	v_cvt_pk_bf16_f32 v132, v132, v133
	v_cvt_pk_bf16_f32 v133, v134, v135
	v_cvt_pk_bf16_f32 v136, v136, v137
	v_cvt_pk_bf16_f32 v137, v138, v139
	v_cvt_pk_bf16_f32 v140, v140, v141
	v_cvt_pk_bf16_f32 v141, v142, v143
	global_store_dwordx2 v2, v[128:129], s[10:11]
	global_store_dwordx2 v2, v[132:133], s[10:11] offset:512
	global_store_dwordx2 v2, v[136:137], s[10:11] offset:1024
	global_store_dwordx2 v2, v[140:141], s[10:11] offset:1536
	s_add_u32 s10, s10, 0x800
	s_addc_u32 s11, s11, 0
	v_pk_mul_f32 v[144:145], v[144:145], v[62:63] op_sel_hi:[1,0]
	v_pk_mul_f32 v[146:147], v[146:147], v[62:63] op_sel_hi:[1,0]
	v_pk_mul_f32 v[148:149], v[148:149], v[62:63] op_sel_hi:[1,0]
	v_pk_mul_f32 v[150:151], v[150:151], v[62:63] op_sel_hi:[1,0]
	v_pk_mul_f32 v[152:153], v[152:153], v[62:63] op_sel_hi:[1,0]
	v_pk_mul_f32 v[154:155], v[154:155], v[62:63] op_sel_hi:[1,0]
	v_pk_mul_f32 v[156:157], v[156:157], v[62:63] op_sel_hi:[1,0]
	v_pk_mul_f32 v[158:159], v[158:159], v[62:63] op_sel_hi:[1,0]
	v_pk_mul_f32 v[144:145], v[24:25], v[144:145]
	v_pk_mul_f32 v[146:147], v[26:27], v[146:147]
	v_pk_mul_f32 v[148:149], v[28:29], v[148:149]
	v_pk_mul_f32 v[150:151], v[30:31], v[150:151]
	v_pk_mul_f32 v[152:153], v[32:33], v[152:153]
	v_pk_mul_f32 v[154:155], v[34:35], v[154:155]
	v_pk_mul_f32 v[156:157], v[36:37], v[156:157]
	v_pk_mul_f32 v[158:159], v[38:39], v[158:159]
	v_pk_fma_f32 v[144:145], v[40:41], v[144:145], v[80:81]
	v_pk_fma_f32 v[146:147], v[42:43], v[146:147], v[82:83]
	v_pk_fma_f32 v[148:149], v[64:65], v[148:149], v[84:85]
	v_pk_fma_f32 v[150:151], v[66:67], v[150:151], v[86:87]
	v_pk_fma_f32 v[152:153], v[68:69], v[152:153], v[88:89]
	v_pk_fma_f32 v[154:155], v[70:71], v[154:155], v[90:91]
	v_pk_fma_f32 v[156:157], v[72:73], v[156:157], v[92:93]
	v_pk_fma_f32 v[158:159], v[74:75], v[158:159], v[94:95]
	v_cvt_pk_bf16_f32 v144, v144, v145
	v_cvt_pk_bf16_f32 v145, v146, v147
	v_cvt_pk_bf16_f32 v148, v148, v149
	v_cvt_pk_bf16_f32 v149, v150, v151
	v_cvt_pk_bf16_f32 v152, v152, v153
	v_cvt_pk_bf16_f32 v153, v154, v155
	v_cvt_pk_bf16_f32 v156, v156, v157
	v_cvt_pk_bf16_f32 v157, v158, v159
	global_store_dwordx2 v2, v[144:145], s[10:11]
	global_store_dwordx2 v2, v[148:149], s[10:11] offset:512
	global_store_dwordx2 v2, v[152:153], s[10:11] offset:1024
	global_store_dwordx2 v2, v[156:157], s[10:11] offset:1536
	s_add_u32 s10, s10, 0x800
	s_addc_u32 s11, s11, 0
	global_load_dwordx4 v[96:99], v1, s[8:9]
	global_load_dwordx4 v[100:103], v1, s[8:9] offset:1024
	global_load_dwordx4 v[104:107], v1, s[8:9] offset:2048
	global_load_dwordx4 v[108:111], v1, s[8:9] offset:3072
	s_add_u32 s8, s8, 0x1000
	s_addc_u32 s9, s9, 0
	global_load_dwordx4 v[112:115], v1, s[8:9]
	global_load_dwordx4 v[116:119], v1, s[8:9] offset:1024
	global_load_dwordx4 v[120:123], v1, s[8:9] offset:2048
	global_load_dwordx4 v[124:127], v1, s[8:9] offset:3072
	s_add_u32 s8, s8, 0x1000
	s_addc_u32 s9, s9, 0
	global_load_dwordx4 v[128:131], v1, s[8:9]
	global_load_dwordx4 v[132:135], v1, s[8:9] offset:1024
	global_load_dwordx4 v[136:139], v1, s[8:9] offset:2048
	global_load_dwordx4 v[140:143], v1, s[8:9] offset:3072
	s_add_u32 s8, s8, 0x1000
	s_addc_u32 s9, s9, 0
	global_load_dwordx4 v[144:147], v1, s[8:9]
	global_load_dwordx4 v[148:151], v1, s[8:9] offset:1024
	global_load_dwordx4 v[152:155], v1, s[8:9] offset:2048
	global_load_dwordx4 v[156:159], v1, s[8:9] offset:3072
	s_add_u32 s8, s8, 0x1000
	s_addc_u32 s9, s9, 0
	s_waitcnt vmcnt(32)
; DI unsigned pk2(float lo, float hi) { return f2bf(lo) | (f2bf(hi) << 16); }
; DI void norm_phase(const Args& A, int wave_s, int l, int which, int rows) {
;     ...
;             float ss = 0.f;
; #pragma unroll
;             for (int j = 0; j < 4; ++j) ss += (xv[rr][j].x * xv[rr][j].x + xv[rr][j].y * xv[rr][j].y) + (xv[rr][j].z * xv[rr][j].z + xv[rr][j].w * xv[rr][j].w);
;             ss = wave_sum(C.lane, ss);
;             const float rs = rsqrtf(ss * (1.f / 1024.f) + EPS);
; #pragma unroll
;             for (int j = 0; j < 4; ++j) { const int col = 4 * (C.lane + 64 * j);
;                 const f32x4 y = xv[rr][j] * rs * g[j] * (sc[j] + 1.f) + sh[j];
;                 v2u o; o.x = pk2(y.x, y.y); o.y = pk2(y.z, y.w);
;                 *(v2u*)(C.H + (size_t)m * 1024 + col) = o; }
	v_mul_f32_e32 v10, v164, v164
	v_fmac_f32_e32 v10, v165, v165
	v_fmac_f32_e32 v10, v166, v166
	v_fmac_f32_e32 v10, v167, v167
	v_fmac_f32_e32 v10, v168, v168
	v_fmac_f32_e32 v10, v169, v169
	v_fmac_f32_e32 v10, v170, v170
	v_fmac_f32_e32 v10, v171, v171
	v_fmac_f32_e32 v10, v172, v172
	v_fmac_f32_e32 v10, v173, v173
	v_fmac_f32_e32 v10, v174, v174
	v_fmac_f32_e32 v10, v175, v175
	v_fmac_f32_e32 v10, v176, v176
	v_fmac_f32_e32 v10, v177, v177
	v_fmac_f32_e32 v10, v178, v178
	v_fmac_f32_e32 v10, v179, v179
	v_mul_f32_e32 v11, v180, v180
	v_fmac_f32_e32 v11, v181, v181
	v_fmac_f32_e32 v11, v182, v182
	v_fmac_f32_e32 v11, v183, v183
	v_fmac_f32_e32 v11, v184, v184
	v_fmac_f32_e32 v11, v185, v185
	v_fmac_f32_e32 v11, v186, v186
	v_fmac_f32_e32 v11, v187, v187
	v_fmac_f32_e32 v11, v188, v188
	v_fmac_f32_e32 v11, v189, v189
	v_fmac_f32_e32 v11, v190, v190
	v_fmac_f32_e32 v11, v191, v191
	v_fmac_f32_e32 v11, v192, v192
	v_fmac_f32_e32 v11, v193, v193
	v_fmac_f32_e32 v11, v194, v194
	v_fmac_f32_e32 v11, v195, v195
	v_mul_f32_e32 v12, v196, v196
	v_fmac_f32_e32 v12, v197, v197
	v_fmac_f32_e32 v12, v198, v198
	v_fmac_f32_e32 v12, v199, v199
	v_fmac_f32_e32 v12, v200, v200
	v_fmac_f32_e32 v12, v201, v201
	v_fmac_f32_e32 v12, v202, v202
	v_fmac_f32_e32 v12, v203, v203
	v_fmac_f32_e32 v12, v204, v204
	v_fmac_f32_e32 v12, v205, v205
	v_fmac_f32_e32 v12, v206, v206
	v_fmac_f32_e32 v12, v207, v207
	v_fmac_f32_e32 v12, v208, v208
	v_fmac_f32_e32 v12, v209, v209
	v_fmac_f32_e32 v12, v210, v210
	v_fmac_f32_e32 v12, v211, v211
	v_mul_f32_e32 v13, v212, v212
	v_fmac_f32_e32 v13, v213, v213
	v_fmac_f32_e32 v13, v214, v214
	v_fmac_f32_e32 v13, v215, v215
	v_fmac_f32_e32 v13, v216, v216
	v_fmac_f32_e32 v13, v217, v217
	v_fmac_f32_e32 v13, v218, v218
	v_fmac_f32_e32 v13, v219, v219
	v_fmac_f32_e32 v13, v220, v220
	v_fmac_f32_e32 v13, v221, v221
	v_fmac_f32_e32 v13, v222, v222
	v_fmac_f32_e32 v13, v223, v223
	v_fmac_f32_e32 v13, v224, v224
	v_fmac_f32_e32 v13, v225, v225
	v_fmac_f32_e32 v13, v226, v226
	v_fmac_f32_e32 v13, v227, v227
	ds_bpermute_b32 v14, v4, v10
	ds_bpermute_b32 v15, v4, v11
	ds_bpermute_b32 v16, v4, v12
	ds_bpermute_b32 v17, v4, v13
	s_waitcnt lgkmcnt(0)
	v_add_f32_e32 v10, v10, v14
	v_add_f32_e32 v11, v11, v15
	v_add_f32_e32 v12, v12, v16
	v_add_f32_e32 v13, v13, v17
	ds_bpermute_b32 v14, v5, v10
	ds_bpermute_b32 v15, v5, v11
	ds_bpermute_b32 v16, v5, v12
	ds_bpermute_b32 v17, v5, v13
	s_waitcnt lgkmcnt(0)
	v_add_f32_e32 v10, v10, v14
	v_add_f32_e32 v11, v11, v15
	v_add_f32_e32 v12, v12, v16
	v_add_f32_e32 v13, v13, v17
	ds_bpermute_b32 v14, v6, v10
	ds_bpermute_b32 v15, v6, v11
	ds_bpermute_b32 v16, v6, v12
	ds_bpermute_b32 v17, v6, v13
	s_waitcnt lgkmcnt(0)
	v_add_f32_e32 v10, v10, v14
	v_add_f32_e32 v11, v11, v15
	v_add_f32_e32 v12, v12, v16
	v_add_f32_e32 v13, v13, v17
	ds_bpermute_b32 v14, v7, v10
	ds_bpermute_b32 v15, v7, v11
	ds_bpermute_b32 v16, v7, v12
	ds_bpermute_b32 v17, v7, v13
	s_waitcnt lgkmcnt(0)
	v_add_f32_e32 v10, v10, v14
	v_add_f32_e32 v11, v11, v15
	v_add_f32_e32 v12, v12, v16
	v_add_f32_e32 v13, v13, v17
	ds_bpermute_b32 v14, v8, v10
	ds_bpermute_b32 v15, v8, v11
	ds_bpermute_b32 v16, v8, v12
	ds_bpermute_b32 v17, v8, v13
	s_waitcnt lgkmcnt(0)
	v_add_f32_e32 v10, v10, v14
	v_add_f32_e32 v11, v11, v15
	v_add_f32_e32 v12, v12, v16
	v_add_f32_e32 v13, v13, v17
	ds_bpermute_b32 v14, v9, v10
	ds_bpermute_b32 v15, v9, v11
	ds_bpermute_b32 v16, v9, v12
	ds_bpermute_b32 v17, v9, v13
	s_waitcnt lgkmcnt(0)
	v_add_f32_e32 v10, v10, v14
	v_add_f32_e32 v11, v11, v15
	v_add_f32_e32 v12, v12, v16
	v_add_f32_e32 v13, v13, v17
	v_fma_f32 v10, v10, s32, v60
	v_fma_f32 v11, v11, s32, v60
	v_fma_f32 v12, v12, s32, v60
	v_fma_f32 v13, v13, s32, v60
	v_rsq_f32_e32 v18, v10
	v_rsq_f32_e32 v20, v11
	v_rsq_f32_e32 v22, v12
	v_rsq_f32_e32 v62, v13
	s_nop 0
	v_pk_mul_f32 v[164:165], v[164:165], v[18:19] op_sel_hi:[1,0]
	v_pk_mul_f32 v[166:167], v[166:167], v[18:19] op_sel_hi:[1,0]
	v_pk_mul_f32 v[168:169], v[168:169], v[18:19] op_sel_hi:[1,0]
	v_pk_mul_f32 v[170:171], v[170:171], v[18:19] op_sel_hi:[1,0]
	v_pk_mul_f32 v[172:173], v[172:173], v[18:19] op_sel_hi:[1,0]
	v_pk_mul_f32 v[174:175], v[174:175], v[18:19] op_sel_hi:[1,0]
	v_pk_mul_f32 v[176:177], v[176:177], v[18:19] op_sel_hi:[1,0]
	v_pk_mul_f32 v[178:179], v[178:179], v[18:19] op_sel_hi:[1,0]
	v_pk_mul_f32 v[164:165], v[24:25], v[164:165]
	v_pk_mul_f32 v[166:167], v[26:27], v[166:167]
	v_pk_mul_f32 v[168:169], v[28:29], v[168:169]
	v_pk_mul_f32 v[170:171], v[30:31], v[170:171]
	v_pk_mul_f32 v[172:173], v[32:33], v[172:173]
	v_pk_mul_f32 v[174:175], v[34:35], v[174:175]
	v_pk_mul_f32 v[176:177], v[36:37], v[176:177]
	v_pk_mul_f32 v[178:179], v[38:39], v[178:179]
	v_pk_fma_f32 v[164:165], v[40:41], v[164:165], v[80:81]
	v_pk_fma_f32 v[166:167], v[42:43], v[166:167], v[82:83]
	v_pk_fma_f32 v[168:169], v[64:65], v[168:169], v[84:85]
	v_pk_fma_f32 v[170:171], v[66:67], v[170:171], v[86:87]
	v_pk_fma_f32 v[172:173], v[68:69], v[172:173], v[88:89]
	v_pk_fma_f32 v[174:175], v[70:71], v[174:175], v[90:91]
	v_pk_fma_f32 v[176:177], v[72:73], v[176:177], v[92:93]
	v_pk_fma_f32 v[178:179], v[74:75], v[178:179], v[94:95]
	v_cvt_pk_bf16_f32 v164, v164, v165
	v_cvt_pk_bf16_f32 v165, v166, v167
	v_cvt_pk_bf16_f32 v168, v168, v169
	v_cvt_pk_bf16_f32 v169, v170, v171
	v_cvt_pk_bf16_f32 v172, v172, v173
	v_cvt_pk_bf16_f32 v173, v174, v175
	v_cvt_pk_bf16_f32 v176, v176, v177
	v_cvt_pk_bf16_f32 v177, v178, v179
	global_store_dwordx2 v2, v[164:165], s[10:11]
	global_store_dwordx2 v2, v[168:169], s[10:11] offset:512
	global_store_dwordx2 v2, v[172:173], s[10:11] offset:1024
	global_store_dwordx2 v2, v[176:177], s[10:11] offset:1536
; DI unsigned pk2(float lo, float hi) { return f2bf(lo) | (f2bf(hi) << 16); }
; DI void norm_phase(const Args& A, int wave_s, int l, int which, int rows) {
;     ...
;             for (int j = 0; j < 4; ++j) xv[rr][j] = ((const f32x4*)xr)[C.lane + 64 * j];
;     ...
;             for (int j = 0; j < 4; ++j) { const int col = 4 * (C.lane + 64 * j);
;                 const f32x4 y = xv[rr][j] * rs * g[j] * (sc[j] + 1.f) + sh[j];
;                 v2u o; o.x = pk2(y.x, y.y); o.y = pk2(y.z, y.w);
;                 *(v2u*)(C.H + (size_t)m * 1024 + col) = o; }
	s_add_u32 s10, s10, 0x800
	s_addc_u32 s11, s11, 0
	v_pk_mul_f32 v[180:181], v[180:181], v[20:21] op_sel_hi:[1,0]
	v_pk_mul_f32 v[182:183], v[182:183], v[20:21] op_sel_hi:[1,0]
	v_pk_mul_f32 v[184:185], v[184:185], v[20:21] op_sel_hi:[1,0]
	v_pk_mul_f32 v[186:187], v[186:187], v[20:21] op_sel_hi:[1,0]
	v_pk_mul_f32 v[188:189], v[188:189], v[20:21] op_sel_hi:[1,0]
	v_pk_mul_f32 v[190:191], v[190:191], v[20:21] op_sel_hi:[1,0]
	v_pk_mul_f32 v[192:193], v[192:193], v[20:21] op_sel_hi:[1,0]
	v_pk_mul_f32 v[194:195], v[194:195], v[20:21] op_sel_hi:[1,0]
	v_pk_mul_f32 v[180:181], v[24:25], v[180:181]
	v_pk_mul_f32 v[182:183], v[26:27], v[182:183]
	v_pk_mul_f32 v[184:185], v[28:29], v[184:185]
	v_pk_mul_f32 v[186:187], v[30:31], v[186:187]
	v_pk_mul_f32 v[188:189], v[32:33], v[188:189]
	v_pk_mul_f32 v[190:191], v[34:35], v[190:191]
	v_pk_mul_f32 v[192:193], v[36:37], v[192:193]
	v_pk_mul_f32 v[194:195], v[38:39], v[194:195]
	v_pk_fma_f32 v[180:181], v[40:41], v[180:181], v[80:81]
	v_pk_fma_f32 v[182:183], v[42:43], v[182:183], v[82:83]
	v_pk_fma_f32 v[184:185], v[64:65], v[184:185], v[84:85]
	v_pk_fma_f32 v[186:187], v[66:67], v[186:187], v[86:87]
	v_pk_fma_f32 v[188:189], v[68:69], v[188:189], v[88:89]
	v_pk_fma_f32 v[190:191], v[70:71], v[190:191], v[90:91]
	v_pk_fma_f32 v[192:193], v[72:73], v[192:193], v[92:93]
	v_pk_fma_f32 v[194:195], v[74:75], v[194:195], v[94:95]
	v_cvt_pk_bf16_f32 v180, v180, v181
	v_cvt_pk_bf16_f32 v181, v182, v183
	v_cvt_pk_bf16_f32 v184, v184, v185
	v_cvt_pk_bf16_f32 v185, v186, v187
	v_cvt_pk_bf16_f32 v188, v188, v189
	v_cvt_pk_bf16_f32 v189, v190, v191
	v_cvt_pk_bf16_f32 v192, v192, v193
	v_cvt_pk_bf16_f32 v193, v194, v195
	global_store_dwordx2 v2, v[180:181], s[10:11]
	global_store_dwordx2 v2, v[184:185], s[10:11] offset:512
	global_store_dwordx2 v2, v[188:189], s[10:11] offset:1024
	global_store_dwordx2 v2, v[192:193], s[10:11] offset:1536
	s_add_u32 s10, s10, 0x800
	s_addc_u32 s11, s11, 0
	v_pk_mul_f32 v[196:197], v[196:197], v[22:23] op_sel_hi:[1,0]
	v_pk_mul_f32 v[198:199], v[198:199], v[22:23] op_sel_hi:[1,0]
	v_pk_mul_f32 v[200:201], v[200:201], v[22:23] op_sel_hi:[1,0]
	v_pk_mul_f32 v[202:203], v[202:203], v[22:23] op_sel_hi:[1,0]
	v_pk_mul_f32 v[204:205], v[204:205], v[22:23] op_sel_hi:[1,0]
	v_pk_mul_f32 v[206:207], v[206:207], v[22:23] op_sel_hi:[1,0]
	v_pk_mul_f32 v[208:209], v[208:209], v[22:23] op_sel_hi:[1,0]
	v_pk_mul_f32 v[210:211], v[210:211], v[22:23] op_sel_hi:[1,0]
	v_pk_mul_f32 v[196:197], v[24:25], v[196:197]
	v_pk_mul_f32 v[198:199], v[26:27], v[198:199]
	v_pk_mul_f32 v[200:201], v[28:29], v[200:201]
	v_pk_mul_f32 v[202:203], v[30:31], v[202:203]
	v_pk_mul_f32 v[204:205], v[32:33], v[204:205]
	v_pk_mul_f32 v[206:207], v[34:35], v[206:207]
	v_pk_mul_f32 v[208:209], v[36:37], v[208:209]
	v_pk_mul_f32 v[210:211], v[38:39], v[210:211]
	v_pk_fma_f32 v[196:197], v[40:41], v[196:197], v[80:81]
	v_pk_fma_f32 v[198:199], v[42:43], v[198:199], v[82:83]
	v_pk_fma_f32 v[200:201], v[64:65], v[200:201], v[84:85]
	v_pk_fma_f32 v[202:203], v[66:67], v[202:203], v[86:87]
	v_pk_fma_f32 v[204:205], v[68:69], v[204:205], v[88:89]
	v_pk_fma_f32 v[206:207], v[70:71], v[206:207], v[90:91]
	v_pk_fma_f32 v[208:209], v[72:73], v[208:209], v[92:93]
	v_pk_fma_f32 v[210:211], v[74:75], v[210:211], v[94:95]
	v_cvt_pk_bf16_f32 v196, v196, v197
	v_cvt_pk_bf16_f32 v197, v198, v199
	v_cvt_pk_bf16_f32 v200, v200, v201
	v_cvt_pk_bf16_f32 v201, v202, v203
	v_cvt_pk_bf16_f32 v204, v204, v205
	v_cvt_pk_bf16_f32 v205, v206, v207
	v_cvt_pk_bf16_f32 v208, v208, v209
	v_cvt_pk_bf16_f32 v209, v210, v211
	global_store_dwordx2 v2, v[196:197], s[10:11]
	global_store_dwordx2 v2, v[200:201], s[10:11] offset:512
	global_store_dwordx2 v2, v[204:205], s[10:11] offset:1024
	global_store_dwordx2 v2, v[208:209], s[10:11] offset:1536
	s_add_u32 s10, s10, 0x800
	s_addc_u32 s11, s11, 0
	v_pk_mul_f32 v[212:213], v[212:213], v[62:63] op_sel_hi:[1,0]
	v_pk_mul_f32 v[214:215], v[214:215], v[62:63] op_sel_hi:[1,0]
	v_pk_mul_f32 v[216:217], v[216:217], v[62:63] op_sel_hi:[1,0]
	v_pk_mul_f32 v[218:219], v[218:219], v[62:63] op_sel_hi:[1,0]
	v_pk_mul_f32 v[220:221], v[220:221], v[62:63] op_sel_hi:[1,0]
	v_pk_mul_f32 v[222:223], v[222:223], v[62:63] op_sel_hi:[1,0]
	v_pk_mul_f32 v[224:225], v[224:225], v[62:63] op_sel_hi:[1,0]
	v_pk_mul_f32 v[226:227], v[226:227], v[62:63] op_sel_hi:[1,0]
	v_pk_mul_f32 v[212:213], v[24:25], v[212:213]
	v_pk_mul_f32 v[214:215], v[26:27], v[214:215]
	v_pk_mul_f32 v[216:217], v[28:29], v[216:217]
	v_pk_mul_f32 v[218:219], v[30:31], v[218:219]
	v_pk_mul_f32 v[220:221], v[32:33], v[220:221]
	v_pk_mul_f32 v[222:223], v[34:35], v[222:223]
	v_pk_mul_f32 v[224:225], v[36:37], v[224:225]
	v_pk_mul_f32 v[226:227], v[38:39], v[226:227]
	v_pk_fma_f32 v[212:213], v[40:41], v[212:213], v[80:81]
	v_pk_fma_f32 v[214:215], v[42:43], v[214:215], v[82:83]
	v_pk_fma_f32 v[216:217], v[64:65], v[216:217], v[84:85]
	v_pk_fma_f32 v[218:219], v[66:67], v[218:219], v[86:87]
	v_pk_fma_f32 v[220:221], v[68:69], v[220:221], v[88:89]
	v_pk_fma_f32 v[222:223], v[70:71], v[222:223], v[90:91]
	v_pk_fma_f32 v[224:225], v[72:73], v[224:225], v[92:93]
	v_pk_fma_f32 v[226:227], v[74:75], v[226:227], v[94:95]
	v_cvt_pk_bf16_f32 v212, v212, v213
	v_cvt_pk_bf16_f32 v213, v214, v215
	v_cvt_pk_bf16_f32 v216, v216, v217
	v_cvt_pk_bf16_f32 v217, v218, v219
	v_cvt_pk_bf16_f32 v220, v220, v221
	v_cvt_pk_bf16_f32 v221, v222, v223
	v_cvt_pk_bf16_f32 v224, v224, v225
	v_cvt_pk_bf16_f32 v225, v226, v227
	global_store_dwordx2 v2, v[212:213], s[10:11]
	global_store_dwordx2 v2, v[216:217], s[10:11] offset:512
	global_store_dwordx2 v2, v[220:221], s[10:11] offset:1024
	global_store_dwordx2 v2, v[224:225], s[10:11] offset:1536
	s_add_u32 s10, s10, 0x800
	s_addc_u32 s11, s11, 0
	global_load_dwordx4 v[164:167], v1, s[8:9]
	global_load_dwordx4 v[168:171], v1, s[8:9] offset:1024
	global_load_dwordx4 v[172:175], v1, s[8:9] offset:2048
	global_load_dwordx4 v[176:179], v1, s[8:9] offset:3072
	s_add_u32 s8, s8, 0x1000
	s_addc_u32 s9, s9, 0
	global_load_dwordx4 v[180:183], v1, s[8:9]
	global_load_dwordx4 v[184:187], v1, s[8:9] offset:1024
	global_load_dwordx4 v[188:191], v1, s[8:9] offset:2048
	global_load_dwordx4 v[192:195], v1, s[8:9] offset:3072
	s_add_u32 s8, s8, 0x1000
	s_addc_u32 s9, s9, 0
	global_load_dwordx4 v[196:199], v1, s[8:9]
	global_load_dwordx4 v[200:203], v1, s[8:9] offset:1024
	global_load_dwordx4 v[204:207], v1, s[8:9] offset:2048
	global_load_dwordx4 v[208:211], v1, s[8:9] offset:3072
	s_add_u32 s8, s8, 0x1000
	s_addc_u32 s9, s9, 0
	global_load_dwordx4 v[212:215], v1, s[8:9]
	global_load_dwordx4 v[216:219], v1, s[8:9] offset:1024
	global_load_dwordx4 v[220:223], v1, s[8:9] offset:2048
	global_load_dwordx4 v[224:227], v1, s[8:9] offset:3072
	s_add_u32 s8, s8, 0x1000
	s_addc_u32 s9, s9, 0
	s_waitcnt vmcnt(32)
; DI unsigned pk2(float lo, float hi) { return f2bf(lo) | (f2bf(hi) << 16); }
; DI void norm_phase(const Args& A, int wave_s, int l, int which, int rows) {
;     ...
;             float ss = 0.f;
; #pragma unroll
;             for (int j = 0; j < 4; ++j) ss += (xv[rr][j].x * xv[rr][j].x + xv[rr][j].y * xv[rr][j].y) + (xv[rr][j].z * xv[rr][j].z + xv[rr][j].w * xv[rr][j].w);
;             ss = wave_sum(C.lane, ss);
;             const float rs = rsqrtf(ss * (1.f / 1024.f) + EPS);
; #pragma unroll
;             for (int j = 0; j < 4; ++j) { const int col = 4 * (C.lane + 64 * j);
;                 const f32x4 y = xv[rr][j] * rs * g[j] * (sc[j] + 1.f) + sh[j];
;                 v2u o; o.x = pk2(y.x, y.y); o.y = pk2(y.z, y.w);
;                 *(v2u*)(C.H + (size_t)m * 1024 + col) = o; }
	v_mul_f32_e32 v10, v96, v96
	v_fmac_f32_e32 v10, v97, v97
	v_fmac_f32_e32 v10, v98, v98
	v_fmac_f32_e32 v10, v99, v99
	v_fmac_f32_e32 v10, v100, v100
	v_fmac_f32_e32 v10, v101, v101
	v_fmac_f32_e32 v10, v102, v102
	v_fmac_f32_e32 v10, v103, v103
	v_fmac_f32_e32 v10, v104, v104
	v_fmac_f32_e32 v10, v105, v105
	v_fmac_f32_e32 v10, v106, v106
	v_fmac_f32_e32 v10, v107, v107
	v_fmac_f32_e32 v10, v108, v108
	v_fmac_f32_e32 v10, v109, v109
	v_fmac_f32_e32 v10, v110, v110
	v_fmac_f32_e32 v10, v111, v111
	v_mul_f32_e32 v11, v112, v112
	v_fmac_f32_e32 v11, v113, v113
	v_fmac_f32_e32 v11, v114, v114
	v_fmac_f32_e32 v11, v115, v115
	v_fmac_f32_e32 v11, v116, v116
	v_fmac_f32_e32 v11, v117, v117
	v_fmac_f32_e32 v11, v118, v118
	v_fmac_f32_e32 v11, v119, v119
	v_fmac_f32_e32 v11, v120, v120
	v_fmac_f32_e32 v11, v121, v121
	v_fmac_f32_e32 v11, v122, v122
	v_fmac_f32_e32 v11, v123, v123
	v_fmac_f32_e32 v11, v124, v124
	v_fmac_f32_e32 v11, v125, v125
	v_fmac_f32_e32 v11, v126, v126
	v_fmac_f32_e32 v11, v127, v127
	v_mul_f32_e32 v12, v128, v128
	v_fmac_f32_e32 v12, v129, v129
	v_fmac_f32_e32 v12, v130, v130
	v_fmac_f32_e32 v12, v131, v131
	v_fmac_f32_e32 v12, v132, v132
	v_fmac_f32_e32 v12, v133, v133
	v_fmac_f32_e32 v12, v134, v134
	v_fmac_f32_e32 v12, v135, v135
	v_fmac_f32_e32 v12, v136, v136
	v_fmac_f32_e32 v12, v137, v137
	v_fmac_f32_e32 v12, v138, v138
	v_fmac_f32_e32 v12, v139, v139
	v_fmac_f32_e32 v12, v140, v140
	v_fmac_f32_e32 v12, v141, v141
	v_fmac_f32_e32 v12, v142, v142
	v_fmac_f32_e32 v12, v143, v143
	v_mul_f32_e32 v13, v144, v144
	v_fmac_f32_e32 v13, v145, v145
	v_fmac_f32_e32 v13, v146, v146
	v_fmac_f32_e32 v13, v147, v147
	v_fmac_f32_e32 v13, v148, v148
	v_fmac_f32_e32 v13, v149, v149
	v_fmac_f32_e32 v13, v150, v150
	v_fmac_f32_e32 v13, v151, v151
	v_fmac_f32_e32 v13, v152, v152
	v_fmac_f32_e32 v13, v153, v153
	v_fmac_f32_e32 v13, v154, v154
	v_fmac_f32_e32 v13, v155, v155
	v_fmac_f32_e32 v13, v156, v156
	v_fmac_f32_e32 v13, v157, v157
	v_fmac_f32_e32 v13, v158, v158
	v_fmac_f32_e32 v13, v159, v159
	ds_bpermute_b32 v14, v4, v10
	ds_bpermute_b32 v15, v4, v11
	ds_bpermute_b32 v16, v4, v12
	ds_bpermute_b32 v17, v4, v13
	s_waitcnt lgkmcnt(0)
	v_add_f32_e32 v10, v10, v14
	v_add_f32_e32 v11, v11, v15
	v_add_f32_e32 v12, v12, v16
	v_add_f32_e32 v13, v13, v17
	ds_bpermute_b32 v14, v5, v10
	ds_bpermute_b32 v15, v5, v11
	ds_bpermute_b32 v16, v5, v12
	ds_bpermute_b32 v17, v5, v13
	s_waitcnt lgkmcnt(0)
	v_add_f32_e32 v10, v10, v14
	v_add_f32_e32 v11, v11, v15
	v_add_f32_e32 v12, v12, v16
	v_add_f32_e32 v13, v13, v17
	ds_bpermute_b32 v14, v6, v10
	ds_bpermute_b32 v15, v6, v11
	ds_bpermute_b32 v16, v6, v12
	ds_bpermute_b32 v17, v6, v13
	s_waitcnt lgkmcnt(0)
	v_add_f32_e32 v10, v10, v14
	v_add_f32_e32 v11, v11, v15
	v_add_f32_e32 v12, v12, v16
	v_add_f32_e32 v13, v13, v17
	ds_bpermute_b32 v14, v7, v10
	ds_bpermute_b32 v15, v7, v11
	ds_bpermute_b32 v16, v7, v12
	ds_bpermute_b32 v17, v7, v13
	s_waitcnt lgkmcnt(0)
	v_add_f32_e32 v10, v10, v14
	v_add_f32_e32 v11, v11, v15
	v_add_f32_e32 v12, v12, v16
	v_add_f32_e32 v13, v13, v17
	ds_bpermute_b32 v14, v8, v10
	ds_bpermute_b32 v15, v8, v11
	ds_bpermute_b32 v16, v8, v12
	ds_bpermute_b32 v17, v8, v13
	s_waitcnt lgkmcnt(0)
	v_add_f32_e32 v10, v10, v14
	v_add_f32_e32 v11, v11, v15
	v_add_f32_e32 v12, v12, v16
	v_add_f32_e32 v13, v13, v17
	ds_bpermute_b32 v14, v9, v10
	ds_bpermute_b32 v15, v9, v11
	ds_bpermute_b32 v16, v9, v12
	ds_bpermute_b32 v17, v9, v13
	s_waitcnt lgkmcnt(0)
	v_add_f32_e32 v10, v10, v14
	v_add_f32_e32 v11, v11, v15
	v_add_f32_e32 v12, v12, v16
	v_add_f32_e32 v13, v13, v17
	v_fma_f32 v10, v10, s32, v60
	v_fma_f32 v11, v11, s32, v60
	v_fma_f32 v12, v12, s32, v60
	v_fma_f32 v13, v13, s32, v60
	v_rsq_f32_e32 v18, v10
	v_rsq_f32_e32 v20, v11
	v_rsq_f32_e32 v22, v12
	v_rsq_f32_e32 v62, v13
	s_nop 0
	v_pk_mul_f32 v[96:97], v[96:97], v[18:19] op_sel_hi:[1,0]
	v_pk_mul_f32 v[98:99], v[98:99], v[18:19] op_sel_hi:[1,0]
	v_pk_mul_f32 v[100:101], v[100:101], v[18:19] op_sel_hi:[1,0]
	v_pk_mul_f32 v[102:103], v[102:103], v[18:19] op_sel_hi:[1,0]
	v_pk_mul_f32 v[104:105], v[104:105], v[18:19] op_sel_hi:[1,0]
	v_pk_mul_f32 v[106:107], v[106:107], v[18:19] op_sel_hi:[1,0]
	v_pk_mul_f32 v[108:109], v[108:109], v[18:19] op_sel_hi:[1,0]
	v_pk_mul_f32 v[110:111], v[110:111], v[18:19] op_sel_hi:[1,0]
	v_pk_mul_f32 v[96:97], v[24:25], v[96:97]
	v_pk_mul_f32 v[98:99], v[26:27], v[98:99]
	v_pk_mul_f32 v[100:101], v[28:29], v[100:101]
	v_pk_mul_f32 v[102:103], v[30:31], v[102:103]
	v_pk_mul_f32 v[104:105], v[32:33], v[104:105]
	v_pk_mul_f32 v[106:107], v[34:35], v[106:107]
	v_pk_mul_f32 v[108:109], v[36:37], v[108:109]
	v_pk_mul_f32 v[110:111], v[38:39], v[110:111]
	v_pk_fma_f32 v[96:97], v[40:41], v[96:97], v[80:81]
	v_pk_fma_f32 v[98:99], v[42:43], v[98:99], v[82:83]
	v_pk_fma_f32 v[100:101], v[64:65], v[100:101], v[84:85]
	v_pk_fma_f32 v[102:103], v[66:67], v[102:103], v[86:87]
	v_pk_fma_f32 v[104:105], v[68:69], v[104:105], v[88:89]
	v_pk_fma_f32 v[106:107], v[70:71], v[106:107], v[90:91]
	v_pk_fma_f32 v[108:109], v[72:73], v[108:109], v[92:93]
	v_pk_fma_f32 v[110:111], v[74:75], v[110:111], v[94:95]
	v_cvt_pk_bf16_f32 v96, v96, v97
	v_cvt_pk_bf16_f32 v97, v98, v99
	v_cvt_pk_bf16_f32 v100, v100, v101
	v_cvt_pk_bf16_f32 v101, v102, v103
	v_cvt_pk_bf16_f32 v104, v104, v105
	v_cvt_pk_bf16_f32 v105, v106, v107
	v_cvt_pk_bf16_f32 v108, v108, v109
	v_cvt_pk_bf16_f32 v109, v110, v111
	global_store_dwordx2 v2, v[96:97], s[10:11]
	global_store_dwordx2 v2, v[100:101], s[10:11] offset:512
	global_store_dwordx2 v2, v[104:105], s[10:11] offset:1024
	global_store_dwordx2 v2, v[108:109], s[10:11] offset:1536
	s_add_u32 s10, s10, 0x800
; DI unsigned pk2(float lo, float hi) { return f2bf(lo) | (f2bf(hi) << 16); }
; DI void norm_phase(const Args& A, int wave_s, int l, int which, int rows) {
;     ...
;             const int m = m0 + rr; const float* xr; int v;
;             if (m < NLAT) { xr = (from_in ? C.x : C.out) + (size_t)m * 1024; v = m >> 13; }
;             else { xr = (from_in ? C.ctx : C.XC) + (size_t)(m - NLAT) * 1024; v = 4; }
;             modp[rr] = C.SM + SM_MOD + (l * 5 + v) * 6144 + (which == 1 ? 0 : 3072);
; #pragma unroll
;             for (int j = 0; j < 4; ++j) xv[rr][j] = ((const f32x4*)xr)[C.lane + 64 * j];
;         }
; #pragma unroll
;         for (int rr = 0; rr < 2; ++rr) {
;             const int m = m0 + rr;
;             f32x4 sh[4], sc[4];
; #pragma unroll
;             for (int j = 0; j < 4; ++j) { const int col = 4 * (C.lane + 64 * j); sh[j] = *(const f32x4*)(modp[rr] + col); sc[j] = *(const f32x4*)(modp[rr] + 1024 + col); }
;     ...
;             const float rs = rsqrtf(ss * (1.f / 1024.f) + EPS);
; #pragma unroll
;             for (int j = 0; j < 4; ++j) { const int col = 4 * (C.lane + 64 * j);
;                 const f32x4 y = xv[rr][j] * rs * g[j] * (sc[j] + 1.f) + sh[j];
;                 v2u o; o.x = pk2(y.x, y.y); o.y = pk2(y.z, y.w);
;                 *(v2u*)(C.H + (size_t)m * 1024 + col) = o; }
	s_addc_u32 s11, s11, 0
	v_pk_mul_f32 v[112:113], v[112:113], v[20:21] op_sel_hi:[1,0]
	v_pk_mul_f32 v[114:115], v[114:115], v[20:21] op_sel_hi:[1,0]
	v_pk_mul_f32 v[116:117], v[116:117], v[20:21] op_sel_hi:[1,0]
	v_pk_mul_f32 v[118:119], v[118:119], v[20:21] op_sel_hi:[1,0]
	v_pk_mul_f32 v[120:121], v[120:121], v[20:21] op_sel_hi:[1,0]
	v_pk_mul_f32 v[122:123], v[122:123], v[20:21] op_sel_hi:[1,0]
	v_pk_mul_f32 v[124:125], v[124:125], v[20:21] op_sel_hi:[1,0]
	v_pk_mul_f32 v[126:127], v[126:127], v[20:21] op_sel_hi:[1,0]
	v_pk_mul_f32 v[112:113], v[24:25], v[112:113]
	v_pk_mul_f32 v[114:115], v[26:27], v[114:115]
	v_pk_mul_f32 v[116:117], v[28:29], v[116:117]
	v_pk_mul_f32 v[118:119], v[30:31], v[118:119]
	v_pk_mul_f32 v[120:121], v[32:33], v[120:121]
	v_pk_mul_f32 v[122:123], v[34:35], v[122:123]
	v_pk_mul_f32 v[124:125], v[36:37], v[124:125]
	v_pk_mul_f32 v[126:127], v[38:39], v[126:127]
	v_pk_fma_f32 v[112:113], v[40:41], v[112:113], v[80:81]
	v_pk_fma_f32 v[114:115], v[42:43], v[114:115], v[82:83]
	v_pk_fma_f32 v[116:117], v[64:65], v[116:117], v[84:85]
	v_pk_fma_f32 v[118:119], v[66:67], v[118:119], v[86:87]
	v_pk_fma_f32 v[120:121], v[68:69], v[120:121], v[88:89]
	v_pk_fma_f32 v[122:123], v[70:71], v[122:123], v[90:91]
	v_pk_fma_f32 v[124:125], v[72:73], v[124:125], v[92:93]
	v_pk_fma_f32 v[126:127], v[74:75], v[126:127], v[94:95]
	v_cvt_pk_bf16_f32 v112, v112, v113
	v_cvt_pk_bf16_f32 v113, v114, v115
	v_cvt_pk_bf16_f32 v116, v116, v117
	v_cvt_pk_bf16_f32 v117, v118, v119
	v_cvt_pk_bf16_f32 v120, v120, v121
	v_cvt_pk_bf16_f32 v121, v122, v123
	v_cvt_pk_bf16_f32 v124, v124, v125
	v_cvt_pk_bf16_f32 v125, v126, v127
	global_store_dwordx2 v2, v[112:113], s[10:11]
	global_store_dwordx2 v2, v[116:117], s[10:11] offset:512
	global_store_dwordx2 v2, v[120:121], s[10:11] offset:1024
	global_store_dwordx2 v2, v[124:125], s[10:11] offset:1536
	s_add_u32 s10, s10, 0x800
	s_addc_u32 s11, s11, 0
	v_pk_mul_f32 v[128:129], v[128:129], v[22:23] op_sel_hi:[1,0]
	v_pk_mul_f32 v[130:131], v[130:131], v[22:23] op_sel_hi:[1,0]
	v_pk_mul_f32 v[132:133], v[132:133], v[22:23] op_sel_hi:[1,0]
	v_pk_mul_f32 v[134:135], v[134:135], v[22:23] op_sel_hi:[1,0]
	v_pk_mul_f32 v[136:137], v[136:137], v[22:23] op_sel_hi:[1,0]
	v_pk_mul_f32 v[138:139], v[138:139], v[22:23] op_sel_hi:[1,0]
	v_pk_mul_f32 v[140:141], v[140:141], v[22:23] op_sel_hi:[1,0]
	v_pk_mul_f32 v[142:143], v[142:143], v[22:23] op_sel_hi:[1,0]
	v_pk_mul_f32 v[128:129], v[24:25], v[128:129]
	v_pk_mul_f32 v[130:131], v[26:27], v[130:131]
	v_pk_mul_f32 v[132:133], v[28:29], v[132:133]
	v_pk_mul_f32 v[134:135], v[30:31], v[134:135]
	v_pk_mul_f32 v[136:137], v[32:33], v[136:137]
	v_pk_mul_f32 v[138:139], v[34:35], v[138:139]
	v_pk_mul_f32 v[140:141], v[36:37], v[140:141]
	v_pk_mul_f32 v[142:143], v[38:39], v[142:143]
	v_pk_fma_f32 v[128:129], v[40:41], v[128:129], v[80:81]
	v_pk_fma_f32 v[130:131], v[42:43], v[130:131], v[82:83]
	v_pk_fma_f32 v[132:133], v[64:65], v[132:133], v[84:85]
	v_pk_fma_f32 v[134:135], v[66:67], v[134:135], v[86:87]
	v_pk_fma_f32 v[136:137], v[68:69], v[136:137], v[88:89]
	v_pk_fma_f32 v[138:139], v[70:71], v[138:139], v[90:91]
	v_pk_fma_f32 v[140:141], v[72:73], v[140:141], v[92:93]
	v_pk_fma_f32 v[142:143], v[74:75], v[142:143], v[94:95]
	v_cvt_pk_bf16_f32 v128, v128, v129
	v_cvt_pk_bf16_f32 v129, v130, v131
	v_cvt_pk_bf16_f32 v132, v132, v133
	v_cvt_pk_bf16_f32 v133, v134, v135
	v_cvt_pk_bf16_f32 v136, v136, v137
	v_cvt_pk_bf16_f32 v137, v138, v139
	v_cvt_pk_bf16_f32 v140, v140, v141
	v_cvt_pk_bf16_f32 v141, v142, v143
	global_store_dwordx2 v2, v[128:129], s[10:11]
	global_store_dwordx2 v2, v[132:133], s[10:11] offset:512
	global_store_dwordx2 v2, v[136:137], s[10:11] offset:1024
	global_store_dwordx2 v2, v[140:141], s[10:11] offset:1536
	s_add_u32 s10, s10, 0x800
	s_addc_u32 s11, s11, 0
	v_pk_mul_f32 v[144:145], v[144:145], v[62:63] op_sel_hi:[1,0]
	v_pk_mul_f32 v[146:147], v[146:147], v[62:63] op_sel_hi:[1,0]
	v_pk_mul_f32 v[148:149], v[148:149], v[62:63] op_sel_hi:[1,0]
	v_pk_mul_f32 v[150:151], v[150:151], v[62:63] op_sel_hi:[1,0]
	v_pk_mul_f32 v[152:153], v[152:153], v[62:63] op_sel_hi:[1,0]
	v_pk_mul_f32 v[154:155], v[154:155], v[62:63] op_sel_hi:[1,0]
	v_pk_mul_f32 v[156:157], v[156:157], v[62:63] op_sel_hi:[1,0]
	v_pk_mul_f32 v[158:159], v[158:159], v[62:63] op_sel_hi:[1,0]
	v_pk_mul_f32 v[144:145], v[24:25], v[144:145]
	v_pk_mul_f32 v[146:147], v[26:27], v[146:147]
	v_pk_mul_f32 v[148:149], v[28:29], v[148:149]
	v_pk_mul_f32 v[150:151], v[30:31], v[150:151]
	v_pk_mul_f32 v[152:153], v[32:33], v[152:153]
	v_pk_mul_f32 v[154:155], v[34:35], v[154:155]
	v_pk_mul_f32 v[156:157], v[36:37], v[156:157]
	v_pk_mul_f32 v[158:159], v[38:39], v[158:159]
	v_pk_fma_f32 v[144:145], v[40:41], v[144:145], v[80:81]
	v_pk_fma_f32 v[146:147], v[42:43], v[146:147], v[82:83]
	v_pk_fma_f32 v[148:149], v[64:65], v[148:149], v[84:85]
	v_pk_fma_f32 v[150:151], v[66:67], v[150:151], v[86:87]
	v_pk_fma_f32 v[152:153], v[68:69], v[152:153], v[88:89]
	v_pk_fma_f32 v[154:155], v[70:71], v[154:155], v[90:91]
	v_pk_fma_f32 v[156:157], v[72:73], v[156:157], v[92:93]
	v_pk_fma_f32 v[158:159], v[74:75], v[158:159], v[94:95]
	v_cvt_pk_bf16_f32 v144, v144, v145
	v_cvt_pk_bf16_f32 v145, v146, v147
	v_cvt_pk_bf16_f32 v148, v148, v149
	v_cvt_pk_bf16_f32 v149, v150, v151
	v_cvt_pk_bf16_f32 v152, v152, v153
	v_cvt_pk_bf16_f32 v153, v154, v155
	v_cvt_pk_bf16_f32 v156, v156, v157
	v_cvt_pk_bf16_f32 v157, v158, v159
	global_store_dwordx2 v2, v[144:145], s[10:11]
	global_store_dwordx2 v2, v[148:149], s[10:11] offset:512
	global_store_dwordx2 v2, v[152:153], s[10:11] offset:1024
	global_store_dwordx2 v2, v[156:157], s[10:11] offset:1536
	s_add_u32 s10, s10, 0x800
	s_addc_u32 s11, s11, 0
	s_mul_i32 s5, s6, 5
	s_add_u32 s5, s5, 4
	s_mul_i32 s5, s5, 0x6000
	s_add_u32 s24, s88, 0x103000
	s_addc_u32 s25, s89, 0
	s_add_u32 s24, s24, s5
	s_addc_u32 s25, s25, 0
	s_add_u32 s26, s24, 0x1000
	s_addc_u32 s27, s25, 0
	global_load_dwordx4 v[96:99], v1, s[30:31]
	global_load_dwordx4 v[100:103], v1, s[30:31] offset:1024
	global_load_dwordx4 v[104:107], v1, s[30:31] offset:2048
	global_load_dwordx4 v[108:111], v1, s[30:31] offset:3072
	global_load_dwordx4 v[112:115], v1, s[26:27]
	global_load_dwordx4 v[116:119], v1, s[26:27] offset:1024
	global_load_dwordx4 v[120:123], v1, s[26:27] offset:2048
	global_load_dwordx4 v[124:127], v1, s[26:27] offset:3072
	global_load_dwordx4 v[128:131], v1, s[24:25]
	global_load_dwordx4 v[132:135], v1, s[24:25] offset:1024
	global_load_dwordx4 v[136:139], v1, s[24:25] offset:2048
	global_load_dwordx4 v[140:143], v1, s[24:25] offset:3072
	s_waitcnt vmcnt(28)
; DI unsigned pk2(float lo, float hi) { return f2bf(lo) | (f2bf(hi) << 16); }
; DI void norm_phase(const Args& A, int wave_s, int l, int which, int rows) {
;     ...
;             float ss = 0.f;
; #pragma unroll
;             for (int j = 0; j < 4; ++j) ss += (xv[rr][j].x * xv[rr][j].x + xv[rr][j].y * xv[rr][j].y) + (xv[rr][j].z * xv[rr][j].z + xv[rr][j].w * xv[rr][j].w);
;             ss = wave_sum(C.lane, ss);
;             const float rs = rsqrtf(ss * (1.f / 1024.f) + EPS);
; #pragma unroll
;             for (int j = 0; j < 4; ++j) { const int col = 4 * (C.lane + 64 * j);
;                 const f32x4 y = xv[rr][j] * rs * g[j] * (sc[j] + 1.f) + sh[j];
;                 v2u o; o.x = pk2(y.x, y.y); o.y = pk2(y.z, y.w);
;                 *(v2u*)(C.H + (size_t)m * 1024 + col) = o; }
	v_mul_f32_e32 v10, v164, v164
	v_fmac_f32_e32 v10, v165, v165
	v_fmac_f32_e32 v10, v166, v166
	v_fmac_f32_e32 v10, v167, v167
	v_fmac_f32_e32 v10, v168, v168
	v_fmac_f32_e32 v10, v169, v169
	v_fmac_f32_e32 v10, v170, v170
	v_fmac_f32_e32 v10, v171, v171
	v_fmac_f32_e32 v10, v172, v172
	v_fmac_f32_e32 v10, v173, v173
	v_fmac_f32_e32 v10, v174, v174
	v_fmac_f32_e32 v10, v175, v175
	v_fmac_f32_e32 v10, v176, v176
	v_fmac_f32_e32 v10, v177, v177
	v_fmac_f32_e32 v10, v178, v178
	v_fmac_f32_e32 v10, v179, v179
	v_mul_f32_e32 v11, v180, v180
	v_fmac_f32_e32 v11, v181, v181
	v_fmac_f32_e32 v11, v182, v182
	v_fmac_f32_e32 v11, v183, v183
	v_fmac_f32_e32 v11, v184, v184
	v_fmac_f32_e32 v11, v185, v185
	v_fmac_f32_e32 v11, v186, v186
	v_fmac_f32_e32 v11, v187, v187
	v_fmac_f32_e32 v11, v188, v188
	v_fmac_f32_e32 v11, v189, v189
	v_fmac_f32_e32 v11, v190, v190
	v_fmac_f32_e32 v11, v191, v191
	v_fmac_f32_e32 v11, v192, v192
	v_fmac_f32_e32 v11, v193, v193
	v_fmac_f32_e32 v11, v194, v194
	v_fmac_f32_e32 v11, v195, v195
	v_mul_f32_e32 v12, v196, v196
	v_fmac_f32_e32 v12, v197, v197
	v_fmac_f32_e32 v12, v198, v198
	v_fmac_f32_e32 v12, v199, v199
	v_fmac_f32_e32 v12, v200, v200
	v_fmac_f32_e32 v12, v201, v201
	v_fmac_f32_e32 v12, v202, v202
	v_fmac_f32_e32 v12, v203, v203
	v_fmac_f32_e32 v12, v204, v204
	v_fmac_f32_e32 v12, v205, v205
	v_fmac_f32_e32 v12, v206, v206
	v_fmac_f32_e32 v12, v207, v207
	v_fmac_f32_e32 v12, v208, v208
	v_fmac_f32_e32 v12, v209, v209
	v_fmac_f32_e32 v12, v210, v210
	v_fmac_f32_e32 v12, v211, v211
	v_mul_f32_e32 v13, v212, v212
	v_fmac_f32_e32 v13, v213, v213
	v_fmac_f32_e32 v13, v214, v214
	v_fmac_f32_e32 v13, v215, v215
	v_fmac_f32_e32 v13, v216, v216
	v_fmac_f32_e32 v13, v217, v217
	v_fmac_f32_e32 v13, v218, v218
	v_fmac_f32_e32 v13, v219, v219
	v_fmac_f32_e32 v13, v220, v220
	v_fmac_f32_e32 v13, v221, v221
	v_fmac_f32_e32 v13, v222, v222
	v_fmac_f32_e32 v13, v223, v223
	v_fmac_f32_e32 v13, v224, v224
	v_fmac_f32_e32 v13, v225, v225
	v_fmac_f32_e32 v13, v226, v226
	v_fmac_f32_e32 v13, v227, v227
	ds_bpermute_b32 v14, v4, v10
	ds_bpermute_b32 v15, v4, v11
	ds_bpermute_b32 v16, v4, v12
	ds_bpermute_b32 v17, v4, v13
	s_waitcnt lgkmcnt(0)
	v_add_f32_e32 v10, v10, v14
	v_add_f32_e32 v11, v11, v15
	v_add_f32_e32 v12, v12, v16
	v_add_f32_e32 v13, v13, v17
	ds_bpermute_b32 v14, v5, v10
	ds_bpermute_b32 v15, v5, v11
	ds_bpermute_b32 v16, v5, v12
	ds_bpermute_b32 v17, v5, v13
	s_waitcnt lgkmcnt(0)
	v_add_f32_e32 v10, v10, v14
	v_add_f32_e32 v11, v11, v15
	v_add_f32_e32 v12, v12, v16
	v_add_f32_e32 v13, v13, v17
	ds_bpermute_b32 v14, v6, v10
	ds_bpermute_b32 v15, v6, v11
	ds_bpermute_b32 v16, v6, v12
	ds_bpermute_b32 v17, v6, v13
	s_waitcnt lgkmcnt(0)
	v_add_f32_e32 v10, v10, v14
	v_add_f32_e32 v11, v11, v15
	v_add_f32_e32 v12, v12, v16
	v_add_f32_e32 v13, v13, v17
	ds_bpermute_b32 v14, v7, v10
	ds_bpermute_b32 v15, v7, v11
	ds_bpermute_b32 v16, v7, v12
	ds_bpermute_b32 v17, v7, v13
	s_waitcnt lgkmcnt(0)
	v_add_f32_e32 v10, v10, v14
	v_add_f32_e32 v11, v11, v15
	v_add_f32_e32 v12, v12, v16
	v_add_f32_e32 v13, v13, v17
	ds_bpermute_b32 v14, v8, v10
	ds_bpermute_b32 v15, v8, v11
	ds_bpermute_b32 v16, v8, v12
	ds_bpermute_b32 v17, v8, v13
	s_waitcnt lgkmcnt(0)
	v_add_f32_e32 v10, v10, v14
	v_add_f32_e32 v11, v11, v15
	v_add_f32_e32 v12, v12, v16
	v_add_f32_e32 v13, v13, v17
	ds_bpermute_b32 v14, v9, v10
	ds_bpermute_b32 v15, v9, v11
	ds_bpermute_b32 v16, v9, v12
	ds_bpermute_b32 v17, v9, v13
	s_waitcnt lgkmcnt(0)
	v_add_f32_e32 v10, v10, v14
	v_add_f32_e32 v11, v11, v15
	v_add_f32_e32 v12, v12, v16
	v_add_f32_e32 v13, v13, v17
	v_fma_f32 v10, v10, s32, v60
	v_fma_f32 v11, v11, s32, v60
	v_fma_f32 v12, v12, s32, v60
	v_fma_f32 v13, v13, s32, v60
	v_rsq_f32_e32 v18, v10
	v_rsq_f32_e32 v20, v11
	v_rsq_f32_e32 v22, v12
	v_rsq_f32_e32 v62, v13
	s_nop 0
	v_pk_mul_f32 v[164:165], v[164:165], v[18:19] op_sel_hi:[1,0]
	v_pk_mul_f32 v[166:167], v[166:167], v[18:19] op_sel_hi:[1,0]
	v_pk_mul_f32 v[168:169], v[168:169], v[18:19] op_sel_hi:[1,0]
	v_pk_mul_f32 v[170:171], v[170:171], v[18:19] op_sel_hi:[1,0]
	v_pk_mul_f32 v[172:173], v[172:173], v[18:19] op_sel_hi:[1,0]
	v_pk_mul_f32 v[174:175], v[174:175], v[18:19] op_sel_hi:[1,0]
	v_pk_mul_f32 v[176:177], v[176:177], v[18:19] op_sel_hi:[1,0]
	v_pk_mul_f32 v[178:179], v[178:179], v[18:19] op_sel_hi:[1,0]
	v_pk_mul_f32 v[164:165], v[24:25], v[164:165]
	v_pk_mul_f32 v[166:167], v[26:27], v[166:167]
	v_pk_mul_f32 v[168:169], v[28:29], v[168:169]
	v_pk_mul_f32 v[170:171], v[30:31], v[170:171]
	v_pk_mul_f32 v[172:173], v[32:33], v[172:173]
	v_pk_mul_f32 v[174:175], v[34:35], v[174:175]
	v_pk_mul_f32 v[176:177], v[36:37], v[176:177]
	v_pk_mul_f32 v[178:179], v[38:39], v[178:179]
	v_pk_fma_f32 v[164:165], v[40:41], v[164:165], v[80:81]
	v_pk_fma_f32 v[166:167], v[42:43], v[166:167], v[82:83]
	v_pk_fma_f32 v[168:169], v[64:65], v[168:169], v[84:85]
	v_pk_fma_f32 v[170:171], v[66:67], v[170:171], v[86:87]
	v_pk_fma_f32 v[172:173], v[68:69], v[172:173], v[88:89]
	v_pk_fma_f32 v[174:175], v[70:71], v[174:175], v[90:91]
	v_pk_fma_f32 v[176:177], v[72:73], v[176:177], v[92:93]
	v_pk_fma_f32 v[178:179], v[74:75], v[178:179], v[94:95]
	v_cvt_pk_bf16_f32 v164, v164, v165
	v_cvt_pk_bf16_f32 v165, v166, v167
	v_cvt_pk_bf16_f32 v168, v168, v169
	v_cvt_pk_bf16_f32 v169, v170, v171
	v_cvt_pk_bf16_f32 v172, v172, v173
	v_cvt_pk_bf16_f32 v173, v174, v175
	v_cvt_pk_bf16_f32 v176, v176, v177
	v_cvt_pk_bf16_f32 v177, v178, v179
	global_store_dwordx2 v2, v[164:165], s[10:11]
	global_store_dwordx2 v2, v[168:169], s[10:11] offset:512
	global_store_dwordx2 v2, v[172:173], s[10:11] offset:1024
	global_store_dwordx2 v2, v[176:177], s[10:11] offset:1536
; DI unsigned pk2(float lo, float hi) { return f2bf(lo) | (f2bf(hi) << 16); }
; DI void norm_phase(const Args& A, int wave_s, int l, int which, int rows) {
;     ...
;             if (m < NLAT) { xr = (from_in ? C.x : C.out) + (size_t)m * 1024; v = m >> 13; }
;             else { xr = (from_in ? C.ctx : C.XC) + (size_t)(m - NLAT) * 1024; v = 4; }
;             modp[rr] = C.SM + SM_MOD + (l * 5 + v) * 6144 + (which == 1 ? 0 : 3072);
;     ...
;             for (int j = 0; j < 4; ++j) { const int col = 4 * (C.lane + 64 * j); sh[j] = *(const f32x4*)(modp[rr] + col); sc[j] = *(const f32x4*)(modp[rr] + 1024 + col); }
;     ...
;             for (int j = 0; j < 4; ++j) { const int col = 4 * (C.lane + 64 * j);
;                 const f32x4 y = xv[rr][j] * rs * g[j] * (sc[j] + 1.f) + sh[j];
;                 v2u o; o.x = pk2(y.x, y.y); o.y = pk2(y.z, y.w);
;                 *(v2u*)(C.H + (size_t)m * 1024 + col) = o; }
	s_add_u32 s10, s10, 0x800
	s_addc_u32 s11, s11, 0
	v_pk_mul_f32 v[180:181], v[180:181], v[20:21] op_sel_hi:[1,0]
	v_pk_mul_f32 v[182:183], v[182:183], v[20:21] op_sel_hi:[1,0]
	v_pk_mul_f32 v[184:185], v[184:185], v[20:21] op_sel_hi:[1,0]
	v_pk_mul_f32 v[186:187], v[186:187], v[20:21] op_sel_hi:[1,0]
	v_pk_mul_f32 v[188:189], v[188:189], v[20:21] op_sel_hi:[1,0]
	v_pk_mul_f32 v[190:191], v[190:191], v[20:21] op_sel_hi:[1,0]
	v_pk_mul_f32 v[192:193], v[192:193], v[20:21] op_sel_hi:[1,0]
	v_pk_mul_f32 v[194:195], v[194:195], v[20:21] op_sel_hi:[1,0]
	v_pk_mul_f32 v[180:181], v[24:25], v[180:181]
	v_pk_mul_f32 v[182:183], v[26:27], v[182:183]
	v_pk_mul_f32 v[184:185], v[28:29], v[184:185]
	v_pk_mul_f32 v[186:187], v[30:31], v[186:187]
	v_pk_mul_f32 v[188:189], v[32:33], v[188:189]
	v_pk_mul_f32 v[190:191], v[34:35], v[190:191]
	v_pk_mul_f32 v[192:193], v[36:37], v[192:193]
	v_pk_mul_f32 v[194:195], v[38:39], v[194:195]
	v_pk_fma_f32 v[180:181], v[40:41], v[180:181], v[80:81]
	v_pk_fma_f32 v[182:183], v[42:43], v[182:183], v[82:83]
	v_pk_fma_f32 v[184:185], v[64:65], v[184:185], v[84:85]
	v_pk_fma_f32 v[186:187], v[66:67], v[186:187], v[86:87]
	v_pk_fma_f32 v[188:189], v[68:69], v[188:189], v[88:89]
	v_pk_fma_f32 v[190:191], v[70:71], v[190:191], v[90:91]
	v_pk_fma_f32 v[192:193], v[72:73], v[192:193], v[92:93]
	v_pk_fma_f32 v[194:195], v[74:75], v[194:195], v[94:95]
	v_cvt_pk_bf16_f32 v180, v180, v181
	v_cvt_pk_bf16_f32 v181, v182, v183
	v_cvt_pk_bf16_f32 v184, v184, v185
	v_cvt_pk_bf16_f32 v185, v186, v187
	v_cvt_pk_bf16_f32 v188, v188, v189
	v_cvt_pk_bf16_f32 v189, v190, v191
	v_cvt_pk_bf16_f32 v192, v192, v193
	v_cvt_pk_bf16_f32 v193, v194, v195
	global_store_dwordx2 v2, v[180:181], s[10:11]
	global_store_dwordx2 v2, v[184:185], s[10:11] offset:512
	global_store_dwordx2 v2, v[188:189], s[10:11] offset:1024
	global_store_dwordx2 v2, v[192:193], s[10:11] offset:1536
	s_add_u32 s10, s10, 0x800
	s_addc_u32 s11, s11, 0
	v_pk_mul_f32 v[196:197], v[196:197], v[22:23] op_sel_hi:[1,0]
	v_pk_mul_f32 v[198:199], v[198:199], v[22:23] op_sel_hi:[1,0]
	v_pk_mul_f32 v[200:201], v[200:201], v[22:23] op_sel_hi:[1,0]
	v_pk_mul_f32 v[202:203], v[202:203], v[22:23] op_sel_hi:[1,0]
	v_pk_mul_f32 v[204:205], v[204:205], v[22:23] op_sel_hi:[1,0]
	v_pk_mul_f32 v[206:207], v[206:207], v[22:23] op_sel_hi:[1,0]
	v_pk_mul_f32 v[208:209], v[208:209], v[22:23] op_sel_hi:[1,0]
	v_pk_mul_f32 v[210:211], v[210:211], v[22:23] op_sel_hi:[1,0]
	v_pk_mul_f32 v[196:197], v[24:25], v[196:197]
	v_pk_mul_f32 v[198:199], v[26:27], v[198:199]
	v_pk_mul_f32 v[200:201], v[28:29], v[200:201]
	v_pk_mul_f32 v[202:203], v[30:31], v[202:203]
	v_pk_mul_f32 v[204:205], v[32:33], v[204:205]
	v_pk_mul_f32 v[206:207], v[34:35], v[206:207]
	v_pk_mul_f32 v[208:209], v[36:37], v[208:209]
	v_pk_mul_f32 v[210:211], v[38:39], v[210:211]
	v_pk_fma_f32 v[196:197], v[40:41], v[196:197], v[80:81]
	v_pk_fma_f32 v[198:199], v[42:43], v[198:199], v[82:83]
	v_pk_fma_f32 v[200:201], v[64:65], v[200:201], v[84:85]
	v_pk_fma_f32 v[202:203], v[66:67], v[202:203], v[86:87]
	v_pk_fma_f32 v[204:205], v[68:69], v[204:205], v[88:89]
	v_pk_fma_f32 v[206:207], v[70:71], v[206:207], v[90:91]
	v_pk_fma_f32 v[208:209], v[72:73], v[208:209], v[92:93]
	v_pk_fma_f32 v[210:211], v[74:75], v[210:211], v[94:95]
	v_cvt_pk_bf16_f32 v196, v196, v197
	v_cvt_pk_bf16_f32 v197, v198, v199
	v_cvt_pk_bf16_f32 v200, v200, v201
	v_cvt_pk_bf16_f32 v201, v202, v203
	v_cvt_pk_bf16_f32 v204, v204, v205
	v_cvt_pk_bf16_f32 v205, v206, v207
	v_cvt_pk_bf16_f32 v208, v208, v209
	v_cvt_pk_bf16_f32 v209, v210, v211
	global_store_dwordx2 v2, v[196:197], s[10:11]
	global_store_dwordx2 v2, v[200:201], s[10:11] offset:512
	global_store_dwordx2 v2, v[204:205], s[10:11] offset:1024
	global_store_dwordx2 v2, v[208:209], s[10:11] offset:1536
	s_add_u32 s10, s10, 0x800
	s_addc_u32 s11, s11, 0
	v_pk_mul_f32 v[212:213], v[212:213], v[62:63] op_sel_hi:[1,0]
	v_pk_mul_f32 v[214:215], v[214:215], v[62:63] op_sel_hi:[1,0]
	v_pk_mul_f32 v[216:217], v[216:217], v[62:63] op_sel_hi:[1,0]
	v_pk_mul_f32 v[218:219], v[218:219], v[62:63] op_sel_hi:[1,0]
	v_pk_mul_f32 v[220:221], v[220:221], v[62:63] op_sel_hi:[1,0]
	v_pk_mul_f32 v[222:223], v[222:223], v[62:63] op_sel_hi:[1,0]
	v_pk_mul_f32 v[224:225], v[224:225], v[62:63] op_sel_hi:[1,0]
	v_pk_mul_f32 v[226:227], v[226:227], v[62:63] op_sel_hi:[1,0]
	v_pk_mul_f32 v[212:213], v[24:25], v[212:213]
	v_pk_mul_f32 v[214:215], v[26:27], v[214:215]
	v_pk_mul_f32 v[216:217], v[28:29], v[216:217]
	v_pk_mul_f32 v[218:219], v[30:31], v[218:219]
	v_pk_mul_f32 v[220:221], v[32:33], v[220:221]
	v_pk_mul_f32 v[222:223], v[34:35], v[222:223]
	v_pk_mul_f32 v[224:225], v[36:37], v[224:225]
	v_pk_mul_f32 v[226:227], v[38:39], v[226:227]
	v_pk_fma_f32 v[212:213], v[40:41], v[212:213], v[80:81]
	v_pk_fma_f32 v[214:215], v[42:43], v[214:215], v[82:83]
	v_pk_fma_f32 v[216:217], v[64:65], v[216:217], v[84:85]
	v_pk_fma_f32 v[218:219], v[66:67], v[218:219], v[86:87]
	v_pk_fma_f32 v[220:221], v[68:69], v[220:221], v[88:89]
	v_pk_fma_f32 v[222:223], v[70:71], v[222:223], v[90:91]
	v_pk_fma_f32 v[224:225], v[72:73], v[224:225], v[92:93]
	v_pk_fma_f32 v[226:227], v[74:75], v[226:227], v[94:95]
	v_cvt_pk_bf16_f32 v212, v212, v213
	v_cvt_pk_bf16_f32 v213, v214, v215
	v_cvt_pk_bf16_f32 v216, v216, v217
	v_cvt_pk_bf16_f32 v217, v218, v219
	v_cvt_pk_bf16_f32 v220, v220, v221
	v_cvt_pk_bf16_f32 v221, v222, v223
	v_cvt_pk_bf16_f32 v224, v224, v225
	v_cvt_pk_bf16_f32 v225, v226, v227
	global_store_dwordx2 v2, v[212:213], s[10:11]
	global_store_dwordx2 v2, v[216:217], s[10:11] offset:512
	global_store_dwordx2 v2, v[220:221], s[10:11] offset:1024
	global_store_dwordx2 v2, v[224:225], s[10:11] offset:1536
	s_add_u32 s10, s10, 0x800
	s_addc_u32 s11, s11, 0
	s_add_u32 s10, s88, 0x3800000
	s_addc_u32 s11, s89, 0
	s_add_u32 s10, s10, 0x4000000
	s_addc_u32 s11, s11, 0
	s_lshl_b32 s5, s7, 11
	s_add_u32 s10, s10, s5
	s_addc_u32 s11, s11, 0
	s_waitcnt vmcnt(16)
	v_pk_add_f32 v[112:113], v[112:113], 1.0 op_sel_hi:[1,0]
	v_pk_add_f32 v[114:115], v[114:115], 1.0 op_sel_hi:[1,0]
	v_pk_add_f32 v[116:117], v[116:117], 1.0 op_sel_hi:[1,0]
	v_pk_add_f32 v[118:119], v[118:119], 1.0 op_sel_hi:[1,0]
	v_pk_add_f32 v[120:121], v[120:121], 1.0 op_sel_hi:[1,0]
	v_pk_add_f32 v[122:123], v[122:123], 1.0 op_sel_hi:[1,0]
	v_pk_add_f32 v[124:125], v[124:125], 1.0 op_sel_hi:[1,0]
	v_pk_add_f32 v[126:127], v[126:127], 1.0 op_sel_hi:[1,0]
	s_cmp_eq_u32 s2, 0
	s_cbranch_scc1 .Lnorm_n2_done
; DI unsigned pk2(float lo, float hi) { return f2bf(lo) | (f2bf(hi) << 16); }
; __device__ __forceinline__ unsigned xb_add(unsigned* p, unsigned v) { return __hip_atomic_fetch_add(p, v, __ATOMIC_RELAXED, __HIP_MEMORY_SCOPE_AGENT); }
; DI void norm_phase(const Args& A, int wave_s, int l, int which, int rows) {
;     ...
;             float ss = 0.f;
; #pragma unroll
;             for (int j = 0; j < 4; ++j) ss += (xv[rr][j].x * xv[rr][j].x + xv[rr][j].y * xv[rr][j].y) + (xv[rr][j].z * xv[rr][j].z + xv[rr][j].w * xv[rr][j].w);
;             ss = wave_sum(C.lane, ss);
;             const float rs = rsqrtf(ss * (1.f / 1024.f) + EPS);
; #pragma unroll
;             for (int j = 0; j < 4; ++j) { const int col = 4 * (C.lane + 64 * j);
;                 const f32x4 y = xv[rr][j] * rs * g[j] * (sc[j] + 1.f) + sh[j];
;                 v2u o; o.x = pk2(y.x, y.y); o.y = pk2(y.z, y.w);
;                 *(v2u*)(C.H + (size_t)m * 1024 + col) = o; }
; __device__ __forceinline__ void xcd_barrier(const XcdBarrier& b, int xtid) {
;     asm volatile("s_waitcnt vmcnt(0)" ::: "memory");
;     __syncthreads();
;     if (xtid == 0) {
;         unsigned* bar = b.bar; unsigned bx_ = b.x; asm volatile("" : "+s"(bx_));
;         __builtin_amdgcn_s_waitcnt(0);
;         unsigned nloc = b.st[0], nx = b.st[1];
;         if (nloc == 0u) { xcd_barrier_complete(bar, bx_, nloc, nx); b.st[0] = nloc; b.st[1] = nx; }
;         const unsigned old = xb_add(&bar[XB_XSUB(bx_)], 1u);
	v_mul_f32_e32 v10, v96, v96
	v_fmac_f32_e32 v10, v97, v97
	v_fmac_f32_e32 v10, v98, v98
	v_fmac_f32_e32 v10, v99, v99
	v_fmac_f32_e32 v10, v100, v100
	v_fmac_f32_e32 v10, v101, v101
	v_fmac_f32_e32 v10, v102, v102
	v_fmac_f32_e32 v10, v103, v103
	v_fmac_f32_e32 v10, v104, v104
	v_fmac_f32_e32 v10, v105, v105
	v_fmac_f32_e32 v10, v106, v106
	v_fmac_f32_e32 v10, v107, v107
	v_fmac_f32_e32 v10, v108, v108
	v_fmac_f32_e32 v10, v109, v109
	v_fmac_f32_e32 v10, v110, v110
	v_fmac_f32_e32 v10, v111, v111
	ds_bpermute_b32 v14, v4, v10
	s_waitcnt lgkmcnt(0)
	v_add_f32_e32 v10, v10, v14
	ds_bpermute_b32 v14, v5, v10
	s_waitcnt lgkmcnt(0)
	v_add_f32_e32 v10, v10, v14
	ds_bpermute_b32 v14, v6, v10
	s_waitcnt lgkmcnt(0)
	v_add_f32_e32 v10, v10, v14
	ds_bpermute_b32 v14, v7, v10
	s_waitcnt lgkmcnt(0)
	v_add_f32_e32 v10, v10, v14
	ds_bpermute_b32 v14, v8, v10
	s_waitcnt lgkmcnt(0)
	v_add_f32_e32 v10, v10, v14
	ds_bpermute_b32 v14, v9, v10
	s_waitcnt lgkmcnt(0)
	v_add_f32_e32 v10, v10, v14
	v_fma_f32 v10, v10, s32, v60
	v_rsq_f32_e32 v18, v10
	s_nop 0
	v_pk_mul_f32 v[96:97], v[96:97], v[18:19] op_sel_hi:[1,0]
	v_pk_mul_f32 v[98:99], v[98:99], v[18:19] op_sel_hi:[1,0]
	v_pk_mul_f32 v[100:101], v[100:101], v[18:19] op_sel_hi:[1,0]
	v_pk_mul_f32 v[102:103], v[102:103], v[18:19] op_sel_hi:[1,0]
	v_pk_mul_f32 v[104:105], v[104:105], v[18:19] op_sel_hi:[1,0]
	v_pk_mul_f32 v[106:107], v[106:107], v[18:19] op_sel_hi:[1,0]
	v_pk_mul_f32 v[108:109], v[108:109], v[18:19] op_sel_hi:[1,0]
	v_pk_mul_f32 v[110:111], v[110:111], v[18:19] op_sel_hi:[1,0]
	v_pk_mul_f32 v[96:97], v[24:25], v[96:97]
	v_pk_mul_f32 v[98:99], v[26:27], v[98:99]
	v_pk_mul_f32 v[100:101], v[28:29], v[100:101]
	v_pk_mul_f32 v[102:103], v[30:31], v[102:103]
	v_pk_mul_f32 v[104:105], v[32:33], v[104:105]
	v_pk_mul_f32 v[106:107], v[34:35], v[106:107]
	v_pk_mul_f32 v[108:109], v[36:37], v[108:109]
	v_pk_mul_f32 v[110:111], v[38:39], v[110:111]
	v_pk_fma_f32 v[96:97], v[112:113], v[96:97], v[128:129]
	v_pk_fma_f32 v[98:99], v[114:115], v[98:99], v[130:131]
	v_pk_fma_f32 v[100:101], v[116:117], v[100:101], v[132:133]
	v_pk_fma_f32 v[102:103], v[118:119], v[102:103], v[134:135]
	v_pk_fma_f32 v[104:105], v[120:121], v[104:105], v[136:137]
	v_pk_fma_f32 v[106:107], v[122:123], v[106:107], v[138:139]
	v_pk_fma_f32 v[108:109], v[124:125], v[108:109], v[140:141]
	v_pk_fma_f32 v[110:111], v[126:127], v[110:111], v[142:143]
	v_cvt_pk_bf16_f32 v96, v96, v97
	v_cvt_pk_bf16_f32 v97, v98, v99
	v_cvt_pk_bf16_f32 v100, v100, v101
	v_cvt_pk_bf16_f32 v101, v102, v103
	v_cvt_pk_bf16_f32 v104, v104, v105
	v_cvt_pk_bf16_f32 v105, v106, v107
	v_cvt_pk_bf16_f32 v108, v108, v109
	v_cvt_pk_bf16_f32 v109, v110, v111
	global_store_dwordx2 v2, v[96:97], s[10:11]
	global_store_dwordx2 v2, v[100:101], s[10:11] offset:512
	global_store_dwordx2 v2, v[104:105], s[10:11] offset:1024
	global_store_dwordx2 v2, v[108:109], s[10:11] offset:1536
.Lnorm_n2_done:
.LBB0_534:
	v_mbcnt_lo_u32_b32 v0, -1, 0
	v_mbcnt_hi_u32_b32 v0, -1, v0
	s_waitcnt vmcnt(0)
	s_nop 0
	v_sub_u32_e32 v0, 0, v0
	v_cmp_eq_u32_e32 vcc, s94, v0
	s_barrier
	s_and_saveexec_b64 s[4:5], vcc
	s_cbranch_execz .LBB0_586
	v_readlane_b32 s6, v254, 62
	s_mov_b32 s2, s64
	s_waitcnt vmcnt(0) expcnt(0) lgkmcnt(0)
	v_mov_b32_e32 v0, s6
	ds_read_b32 v2, v0
	v_readlane_b32 s6, v254, 63
	s_waitcnt lgkmcnt(0)
	v_cmp_ne_u32_e32 vcc, 0, v2
	v_mov_b32_e32 v0, s6
	ds_read_b32 v0, v0
	s_cbranch_vccnz .LBB0_550
	s_mov_b32 s13, 1
	s_branch .LBB0_538
